# GEMM loops: removed the s_setprio 0/1 flip between the two MFMA clusters of each phase (priority stays 1 across both)
# speedup vs baseline: 1.0158x; 1.0158x over previous
; #define PG8_STAGE(bufoff, gbase, voff) do { _Pragma("unroll") for (int _i = 0; _i < 2; ++_i) \
;         __builtin_amdgcn_global_load_lds((const unsigned*)((const char*)(gbase) + (voff)[_i]), (LAS unsigned*)(lds + (bufoff) + ldsw + _i * 8192), 16, 0, 0); } while (0)
; #define PG8_LDA(dst, b, h) do { _Pragma("unroll") for (int m = 0; m < 4; ++m) _Pragma("unroll") for (int k = 0; k < 2; ++k) dst[m][k] = *(const LAS bf16x8*)(lds + PG8_SA(b, h) + aoff + m * 2048 + k * 1024); } while (0)
; #define PG8_LDB(dst, b, h) do { _Pragma("unroll") for (int n = 0; n < 2; ++n) _Pragma("unroll") for (int k = 0; k < 2; ++k) dst[n][k] = *(const LAS bf16x8*)(lds + PG8_SB(b, h) + boff + n * 2048 + k * 1024); } while (0)
; #define PG8_WAIT_V(n) asm volatile("s_waitcnt vmcnt(" #n ")" ::: "memory")
; #define PG8_WAIT_L(n) asm volatile("s_waitcnt lgkmcnt(" #n ")" ::: "memory")
; #define PG8_BAR __builtin_amdgcn_s_barrier()
; #define PG8_SCHED __builtin_amdgcn_sched_barrier(0)
; template <class Epi, class Sched, bool SWAPD = false>
; __device__ __forceinline__ void gemm_phase(LAS unsigned char* lds, const Gemm g, const Sched& S, const Epi& E) {
;     ...
;             PG8_LDB(B0, 0, 0); PG8_LDB(B1, 0, 1); PG8_SCHED; PG8_LDA(At, 0, 0); PG8_STAGE(PG8_SA(1, 1), a1 + hstepA, voffA);
;             PG8_WAIT_V(8); PG8_WAIT_L(0); PG8_BAR; PG8_MMA(0, 0, At, B0); PG8_MMA(0, 1, At, B1); PG8_BAR; PG8_SCHED;
;             PG8_LDA(At, 0, 1); PG8_STAGE(PG8_SB(0, 0), b2, voffB); PG8_STAGE(PG8_SB(0, 1), b2 + hstepB, voffB); PG8_STAGE(PG8_SA(0, 0), a2, voffA);
;             PG8_WAIT_V(8); PG8_WAIT_L(0); PG8_BAR; PG8_MMA(1, 0, At, B0); PG8_MMA(1, 1, At, B1); PG8_BAR; PG8_SCHED;
.LBB0_256:
	ds_read_b128 v[148:151], v145
	ds_read_b128 v[152:155], v145 offset:1024
	ds_read_b128 v[156:159], v145 offset:2048
	ds_read_b128 v[160:163], v145 offset:3072
	ds_read_b128 v[164:167], v146
	ds_read_b128 v[168:171], v146 offset:1024
	ds_read_b128 v[172:175], v146 offset:2048
	ds_read_b128 v[176:179], v146 offset:3072
	s_add_u32 s46, s44, 0xfffc0080
	s_addc_u32 s47, s45, -1
	s_cmp_eq_u32 s68, 12
	s_cselect_b32 s51, s13, s47
	s_cselect_b32 s50, s23, s46
	s_cselect_b32 s47, s64, s67
	s_cselect_b32 s46, s65, s66
	v_lshl_add_u64 v[140:141], s[44:45], 0, v[132:133]
	s_add_i32 m0, s31, 0xc000
	ds_read_b128 v[180:183], v147
	ds_read_b128 v[184:187], v147 offset:1024
	ds_read_b128 v[188:191], v147 offset:2048
	ds_read_b128 v[192:195], v147 offset:3072
	ds_read_b128 v[196:199], v147 offset:4096
	ds_read_b128 v[200:203], v147 offset:5120
	ds_read_b128 v[208:211], v147 offset:6144
	ds_read_b128 v[212:215], v147 offset:7168
	global_load_lds_dwordx4 v[140:141], off
	v_lshl_add_u64 v[140:141], s[44:45], 0, v[134:135]
	s_add_i32 m0, s31, 0xe000
	s_nop 0
	global_load_lds_dwordx4 v[140:141], off
	s_waitcnt vmcnt(8)
	s_waitcnt lgkmcnt(0)
	s_barrier
	s_setprio 1
	s_waitcnt lgkmcnt(0)
	v_mfma_f32_16x16x32_bf16 v[124:127], v[148:151], v[180:183], v[124:127]
	v_mfma_f32_16x16x32_bf16 v[116:119], v[156:159], v[180:183], v[116:119]
	v_mfma_f32_16x16x32_bf16 v[108:111], v[148:151], v[188:191], v[108:111]
	v_mfma_f32_16x16x32_bf16 v[100:103], v[156:159], v[188:191], v[100:103]
	v_mfma_f32_16x16x32_bf16 v[92:95], v[148:151], v[196:199], v[92:95]
	v_mfma_f32_16x16x32_bf16 v[84:87], v[156:159], v[196:199], v[84:87]
	v_mfma_f32_16x16x32_bf16 v[76:79], v[148:151], v[208:211], v[76:79]
	v_mfma_f32_16x16x32_bf16 v[68:71], v[156:159], v[208:211], v[68:71]
	v_mfma_f32_16x16x32_bf16 v[124:127], v[152:155], v[184:187], v[124:127]
	v_mfma_f32_16x16x32_bf16 v[116:119], v[160:163], v[184:187], v[116:119]
	v_mfma_f32_16x16x32_bf16 v[108:111], v[152:155], v[192:195], v[108:111]
	v_mfma_f32_16x16x32_bf16 v[100:103], v[160:163], v[192:195], v[100:103]
	v_mfma_f32_16x16x32_bf16 v[92:95], v[152:155], v[200:203], v[92:95]
	v_mfma_f32_16x16x32_bf16 v[84:87], v[160:163], v[200:203], v[84:87]
	v_mfma_f32_16x16x32_bf16 v[76:79], v[152:155], v[212:215], v[76:79]
	v_mfma_f32_16x16x32_bf16 v[68:71], v[160:163], v[212:215], v[68:71]
	v_mfma_f32_16x16x32_bf16 v[120:123], v[164:167], v[180:183], v[120:123]
	v_mfma_f32_16x16x32_bf16 v[112:115], v[172:175], v[180:183], v[112:115]
	v_mfma_f32_16x16x32_bf16 v[104:107], v[164:167], v[188:191], v[104:107]
	v_mfma_f32_16x16x32_bf16 v[96:99], v[172:175], v[188:191], v[96:99]
	v_mfma_f32_16x16x32_bf16 v[88:91], v[164:167], v[196:199], v[88:91]
	v_mfma_f32_16x16x32_bf16 v[80:83], v[172:175], v[196:199], v[80:83]
	v_mfma_f32_16x16x32_bf16 v[72:75], v[164:167], v[208:211], v[72:75]
	v_mfma_f32_16x16x32_bf16 v[64:67], v[172:175], v[208:211], v[64:67]
	v_mfma_f32_16x16x32_bf16 v[120:123], v[168:171], v[184:187], v[120:123]
	v_mfma_f32_16x16x32_bf16 v[112:115], v[176:179], v[184:187], v[112:115]
	v_mfma_f32_16x16x32_bf16 v[104:107], v[168:171], v[192:195], v[104:107]
	v_mfma_f32_16x16x32_bf16 v[96:99], v[176:179], v[192:195], v[96:99]
	v_mfma_f32_16x16x32_bf16 v[88:91], v[168:171], v[200:203], v[88:91]
	v_mfma_f32_16x16x32_bf16 v[80:83], v[176:179], v[200:203], v[80:83]
	v_mfma_f32_16x16x32_bf16 v[72:75], v[168:171], v[212:215], v[72:75]
	v_mfma_f32_16x16x32_bf16 v[64:67], v[176:179], v[212:215], v[64:67]
	s_setprio 0
	s_barrier
	s_add_i32 s69, s54, s11
	v_lshl_add_u64 v[140:141], s[46:47], 0, v[130:131]
	s_mov_b32 m0, s69
	ds_read_b128 v[180:183], v147 offset:16384
	ds_read_b128 v[184:187], v147 offset:17408
	ds_read_b128 v[188:191], v147 offset:18432
	ds_read_b128 v[192:195], v147 offset:19456
	ds_read_b128 v[196:199], v147 offset:20480
	ds_read_b128 v[200:203], v147 offset:21504
	ds_read_b128 v[208:211], v147 offset:22528
	ds_read_b128 v[212:215], v147 offset:23552
	global_load_lds_dwordx4 v[140:141], off
	s_add_i32 m0, s69, 0x2000
	s_add_u32 s72, s46, 0x40000
	v_lshl_add_u64 v[204:205], s[46:47], 0, v[128:129]
	s_addc_u32 s73, s47, 0
	s_add_i32 s69, s55, s11
	global_load_lds_dwordx4 v[204:205], off
	v_lshl_add_u64 v[216:217], s[72:73], 0, v[130:131]
	s_mov_b32 m0, s69
	v_lshl_add_u64 v[218:219], s[50:51], 0, v[128:129]
	global_load_lds_dwordx4 v[216:217], off
	v_lshl_add_u64 v[216:217], s[72:73], 0, v[128:129]
	s_add_i32 m0, s69, 0x2000
	s_nop 0
	global_load_lds_dwordx4 v[216:217], off
	v_lshl_add_u64 v[216:217], s[50:51], 0, v[130:131]
	s_mov_b32 m0, s31
	s_nop 0
	global_load_lds_dwordx4 v[216:217], off
	s_mov_b32 m0, s33
	s_nop 0
	global_load_lds_dwordx4 v[218:219], off
	s_waitcnt vmcnt(8)
	s_waitcnt lgkmcnt(0)
	s_barrier
; #define PG8_STAGE(bufoff, gbase, voff) do { _Pragma("unroll") for (int _i = 0; _i < 2; ++_i) \
;         __builtin_amdgcn_global_load_lds((const unsigned*)((const char*)(gbase) + (voff)[_i]), (LAS unsigned*)(lds + (bufoff) + ldsw + _i * 8192), 16, 0, 0); } while (0)
; #define PG8_LDA(dst, b, h) do { _Pragma("unroll") for (int m = 0; m < 4; ++m) _Pragma("unroll") for (int k = 0; k < 2; ++k) dst[m][k] = *(const LAS bf16x8*)(lds + PG8_SA(b, h) + aoff + m * 2048 + k * 1024); } while (0)
; #define PG8_LDB(dst, b, h) do { _Pragma("unroll") for (int n = 0; n < 2; ++n) _Pragma("unroll") for (int k = 0; k < 2; ++k) dst[n][k] = *(const LAS bf16x8*)(lds + PG8_SB(b, h) + boff + n * 2048 + k * 1024); } while (0)
; #define PG8_WAIT_V(n) asm volatile("s_waitcnt vmcnt(" #n ")" ::: "memory")
; #define PG8_WAIT_L(n) asm volatile("s_waitcnt lgkmcnt(" #n ")" ::: "memory")
; #define PG8_BAR __builtin_amdgcn_s_barrier()
; #define PG8_SCHED __builtin_amdgcn_sched_barrier(0)
; template <class Epi, class Sched, bool SWAPD = false>
; __device__ __forceinline__ void gemm_phase(LAS unsigned char* lds, const Gemm g, const Sched& S, const Epi& E) {
;     ...
;             PG8_WAIT_V(8); PG8_WAIT_L(0); PG8_BAR; PG8_MMA(1, 0, At, B0); PG8_MMA(1, 1, At, B1); PG8_BAR; PG8_SCHED;
;             PG8_LDB(B0, 1, 0); PG8_LDB(B1, 1, 1); PG8_SCHED; PG8_LDA(At, 1, 0); PG8_STAGE(PG8_SA(0, 1), a2 + hstepA, voffA);
;             PG8_WAIT_V(8); PG8_WAIT_L(0); PG8_BAR; PG8_MMA(0, 0, At, B0); PG8_MMA(0, 1, At, B1); PG8_BAR; PG8_SCHED;
	s_setprio 1
	s_waitcnt lgkmcnt(0)
	v_mfma_f32_16x16x32_bf16 v[60:63], v[148:151], v[180:183], v[60:63]
	v_mfma_f32_16x16x32_bf16 v[52:55], v[156:159], v[180:183], v[52:55]
	v_mfma_f32_16x16x32_bf16 v[44:47], v[148:151], v[188:191], v[44:47]
	v_mfma_f32_16x16x32_bf16 v[36:39], v[156:159], v[188:191], v[36:39]
	v_mfma_f32_16x16x32_bf16 v[28:31], v[148:151], v[196:199], v[28:31]
	v_mfma_f32_16x16x32_bf16 v[20:23], v[156:159], v[196:199], v[20:23]
	v_mfma_f32_16x16x32_bf16 v[12:15], v[148:151], v[208:211], v[12:15]
	v_mfma_f32_16x16x32_bf16 v[4:7], v[156:159], v[208:211], v[4:7]
	v_mfma_f32_16x16x32_bf16 v[60:63], v[152:155], v[184:187], v[60:63]
	v_mfma_f32_16x16x32_bf16 v[52:55], v[160:163], v[184:187], v[52:55]
	v_mfma_f32_16x16x32_bf16 v[44:47], v[152:155], v[192:195], v[44:47]
	v_mfma_f32_16x16x32_bf16 v[36:39], v[160:163], v[192:195], v[36:39]
	v_mfma_f32_16x16x32_bf16 v[28:31], v[152:155], v[200:203], v[28:31]
	v_mfma_f32_16x16x32_bf16 v[20:23], v[160:163], v[200:203], v[20:23]
	v_mfma_f32_16x16x32_bf16 v[12:15], v[152:155], v[212:215], v[12:15]
	v_mfma_f32_16x16x32_bf16 v[4:7], v[160:163], v[212:215], v[4:7]
	v_mfma_f32_16x16x32_bf16 v[56:59], v[164:167], v[180:183], v[56:59]
	v_mfma_f32_16x16x32_bf16 v[48:51], v[172:175], v[180:183], v[48:51]
	v_mfma_f32_16x16x32_bf16 v[40:43], v[164:167], v[188:191], v[40:43]
	v_mfma_f32_16x16x32_bf16 v[32:35], v[172:175], v[188:191], v[32:35]
	v_mfma_f32_16x16x32_bf16 v[24:27], v[164:167], v[196:199], v[24:27]
	v_mfma_f32_16x16x32_bf16 v[16:19], v[172:175], v[196:199], v[16:19]
	v_mfma_f32_16x16x32_bf16 v[8:11], v[164:167], v[208:211], v[8:11]
	v_mfma_f32_16x16x32_bf16 v[0:3], v[172:175], v[208:211], v[0:3]
	v_mfma_f32_16x16x32_bf16 v[56:59], v[168:171], v[184:187], v[56:59]
	v_mfma_f32_16x16x32_bf16 v[48:51], v[176:179], v[184:187], v[48:51]
	v_mfma_f32_16x16x32_bf16 v[40:43], v[168:171], v[192:195], v[40:43]
	v_mfma_f32_16x16x32_bf16 v[32:35], v[176:179], v[192:195], v[32:35]
	v_mfma_f32_16x16x32_bf16 v[24:27], v[168:171], v[200:203], v[24:27]
	v_mfma_f32_16x16x32_bf16 v[16:19], v[176:179], v[200:203], v[16:19]
	v_mfma_f32_16x16x32_bf16 v[8:11], v[168:171], v[212:215], v[8:11]
	v_mfma_f32_16x16x32_bf16 v[0:3], v[176:179], v[212:215], v[0:3]
	s_setprio 0
	s_barrier
	s_add_i32 s69, 0, 0x18000
	s_add_i32 s72, 0, 0x1c000
	v_add_u32_e32 v160, s69, v143
	v_add_u32_e32 v176, s72, v143
	ds_read_b128 v[148:151], v160
	ds_read_b128 v[152:155], v160 offset:1024
	ds_read_b128 v[156:159], v160 offset:2048
	ds_read_b128 v[160:163], v160 offset:3072
	ds_read_b128 v[164:167], v176
	ds_read_b128 v[168:171], v176 offset:1024
	ds_read_b128 v[172:175], v176 offset:2048
	ds_read_b128 v[176:179], v176 offset:3072
	s_add_u32 s50, s50, 0x40000
	s_addc_u32 s51, s51, 0
	s_mov_b32 m0, s34
	v_lshl_add_u64 v[220:221], s[50:51], 0, v[130:131]
	ds_read_b128 v[180:183], v147 offset:32768
	ds_read_b128 v[184:187], v147 offset:33792
	ds_read_b128 v[188:191], v147 offset:34816
	ds_read_b128 v[192:195], v147 offset:35840
	ds_read_b128 v[196:199], v147 offset:36864
	ds_read_b128 v[200:203], v147 offset:37888
	ds_read_b128 v[208:211], v147 offset:38912
	ds_read_b128 v[212:215], v147 offset:39936
	global_load_lds_dwordx4 v[220:221], off
	v_lshl_add_u64 v[220:221], s[50:51], 0, v[128:129]
	s_mov_b32 m0, s35
	s_nop 0
	global_load_lds_dwordx4 v[220:221], off
	s_waitcnt vmcnt(8)
	s_waitcnt lgkmcnt(0)
	s_barrier
	s_setprio 1
	s_waitcnt lgkmcnt(0)
	v_mfma_f32_16x16x32_bf16 v[124:127], v[148:151], v[180:183], v[124:127]
	v_mfma_f32_16x16x32_bf16 v[116:119], v[156:159], v[180:183], v[116:119]
	v_mfma_f32_16x16x32_bf16 v[108:111], v[148:151], v[188:191], v[108:111]
	v_mfma_f32_16x16x32_bf16 v[100:103], v[156:159], v[188:191], v[100:103]
	v_mfma_f32_16x16x32_bf16 v[92:95], v[148:151], v[196:199], v[92:95]
	v_mfma_f32_16x16x32_bf16 v[84:87], v[156:159], v[196:199], v[84:87]
	v_mfma_f32_16x16x32_bf16 v[76:79], v[148:151], v[208:211], v[76:79]
	v_mfma_f32_16x16x32_bf16 v[68:71], v[156:159], v[208:211], v[68:71]
	v_mfma_f32_16x16x32_bf16 v[124:127], v[152:155], v[184:187], v[124:127]
	v_mfma_f32_16x16x32_bf16 v[116:119], v[160:163], v[184:187], v[116:119]
	v_mfma_f32_16x16x32_bf16 v[108:111], v[152:155], v[192:195], v[108:111]
	v_mfma_f32_16x16x32_bf16 v[100:103], v[160:163], v[192:195], v[100:103]
	v_mfma_f32_16x16x32_bf16 v[92:95], v[152:155], v[200:203], v[92:95]
	v_mfma_f32_16x16x32_bf16 v[84:87], v[160:163], v[200:203], v[84:87]
	v_mfma_f32_16x16x32_bf16 v[76:79], v[152:155], v[212:215], v[76:79]
	v_mfma_f32_16x16x32_bf16 v[68:71], v[160:163], v[212:215], v[68:71]
	v_mfma_f32_16x16x32_bf16 v[120:123], v[164:167], v[180:183], v[120:123]
	v_mfma_f32_16x16x32_bf16 v[112:115], v[172:175], v[180:183], v[112:115]
	v_mfma_f32_16x16x32_bf16 v[104:107], v[164:167], v[188:191], v[104:107]
	v_mfma_f32_16x16x32_bf16 v[96:99], v[172:175], v[188:191], v[96:99]
	v_mfma_f32_16x16x32_bf16 v[88:91], v[164:167], v[196:199], v[88:91]
	v_mfma_f32_16x16x32_bf16 v[80:83], v[172:175], v[196:199], v[80:83]
	v_mfma_f32_16x16x32_bf16 v[72:75], v[164:167], v[208:211], v[72:75]
	v_mfma_f32_16x16x32_bf16 v[64:67], v[172:175], v[208:211], v[64:67]
	v_mfma_f32_16x16x32_bf16 v[120:123], v[168:171], v[184:187], v[120:123]
	v_mfma_f32_16x16x32_bf16 v[112:115], v[176:179], v[184:187], v[112:115]
	v_mfma_f32_16x16x32_bf16 v[104:107], v[168:171], v[192:195], v[104:107]
	v_mfma_f32_16x16x32_bf16 v[96:99], v[176:179], v[192:195], v[96:99]
	v_mfma_f32_16x16x32_bf16 v[88:91], v[168:171], v[200:203], v[88:91]
	v_mfma_f32_16x16x32_bf16 v[80:83], v[176:179], v[200:203], v[80:83]
	v_mfma_f32_16x16x32_bf16 v[72:75], v[168:171], v[212:215], v[72:75]
	v_mfma_f32_16x16x32_bf16 v[64:67], v[176:179], v[212:215], v[64:67]
	s_setprio 0
	s_barrier
; #define PG8_STAGE(bufoff, gbase, voff) do { _Pragma("unroll") for (int _i = 0; _i < 2; ++_i) \
;         __builtin_amdgcn_global_load_lds((const unsigned*)((const char*)(gbase) + (voff)[_i]), (LAS unsigned*)(lds + (bufoff) + ldsw + _i * 8192), 16, 0, 0); } while (0)
; #define PG8_LDA(dst, b, h) do { _Pragma("unroll") for (int m = 0; m < 4; ++m) _Pragma("unroll") for (int k = 0; k < 2; ++k) dst[m][k] = *(const LAS bf16x8*)(lds + PG8_SA(b, h) + aoff + m * 2048 + k * 1024); } while (0)
; #define PG8_WAIT_V(n) asm volatile("s_waitcnt vmcnt(" #n ")" ::: "memory")
; #define PG8_WAIT_L(n) asm volatile("s_waitcnt lgkmcnt(" #n ")" ::: "memory")
; #define PG8_BAR __builtin_amdgcn_s_barrier()
; #define PG8_SCHED __builtin_amdgcn_sched_barrier(0)
; template <class Epi, class Sched, bool SWAPD = false>
; __device__ __forceinline__ void gemm_phase(LAS unsigned char* lds, const Gemm g, const Sched& S, const Epi& E) {
;     ...
;             PG8_WAIT_V(8); PG8_WAIT_L(0); PG8_BAR; PG8_MMA(0, 0, At, B0); PG8_MMA(0, 1, At, B1); PG8_BAR; PG8_SCHED;
;             PG8_LDA(At, 1, 1); PG8_STAGE(PG8_SB(1, 0), b3, voffB); PG8_STAGE(PG8_SB(1, 1), b3 + hstepB, voffB); PG8_STAGE(PG8_SA(1, 0), a3, voffA);
;             PG8_WAIT_V(8); PG8_WAIT_L(0); PG8_BAR; PG8_MMA(1, 0, At, B0); PG8_MMA(1, 1, At, B1); PG8_BAR; PG8_SCHED;
;         }
	s_add_i32 s50, s69, s11
	v_lshl_add_u64 v[140:141], v[140:141], 0, s[6:7]
	s_mov_b32 m0, s50
	ds_read_b128 v[180:183], v147 offset:49152
	ds_read_b128 v[184:187], v147 offset:50176
	ds_read_b128 v[188:191], v147 offset:51200
	ds_read_b128 v[192:195], v147 offset:52224
	ds_read_b128 v[196:199], v147 offset:53248
	ds_read_b128 v[200:203], v147 offset:54272
	ds_read_b128 v[208:211], v147 offset:55296
	ds_read_b128 v[212:215], v147 offset:56320
	global_load_lds_dwordx4 v[140:141], off
	s_add_i32 m0, s50, 0x2000
	s_add_u32 s46, s46, 0x40080
	v_lshl_add_u64 v[140:141], v[204:205], 0, s[6:7]
	s_addc_u32 s47, s47, 0
	s_add_i32 s50, s72, s11
	global_load_lds_dwordx4 v[140:141], off
	v_lshl_add_u64 v[140:141], s[46:47], 0, v[130:131]
	s_mov_b32 m0, s50
	s_nop 0
	global_load_lds_dwordx4 v[140:141], off
	v_lshl_add_u64 v[140:141], s[46:47], 0, v[128:129]
	s_add_i32 m0, s50, 0x2000
	s_nop 0
	global_load_lds_dwordx4 v[140:141], off
	v_lshl_add_u64 v[140:141], v[216:217], 0, s[6:7]
	s_mov_b32 m0, s52
	s_nop 0
	global_load_lds_dwordx4 v[140:141], off
	v_lshl_add_u64 v[140:141], v[218:219], 0, s[6:7]
	s_mov_b32 m0, s53
	s_nop 0
	global_load_lds_dwordx4 v[140:141], off
	s_waitcnt vmcnt(8)
	s_waitcnt lgkmcnt(0)
	s_barrier
	s_setprio 1
	s_waitcnt lgkmcnt(0)
	v_mfma_f32_16x16x32_bf16 v[60:63], v[148:151], v[180:183], v[60:63]
	v_mfma_f32_16x16x32_bf16 v[52:55], v[156:159], v[180:183], v[52:55]
	v_mfma_f32_16x16x32_bf16 v[44:47], v[148:151], v[188:191], v[44:47]
	v_mfma_f32_16x16x32_bf16 v[36:39], v[156:159], v[188:191], v[36:39]
	v_mfma_f32_16x16x32_bf16 v[28:31], v[148:151], v[196:199], v[28:31]
	v_mfma_f32_16x16x32_bf16 v[20:23], v[156:159], v[196:199], v[20:23]
	v_mfma_f32_16x16x32_bf16 v[12:15], v[148:151], v[208:211], v[12:15]
	v_mfma_f32_16x16x32_bf16 v[4:7], v[156:159], v[208:211], v[4:7]
	v_mfma_f32_16x16x32_bf16 v[60:63], v[152:155], v[184:187], v[60:63]
	v_mfma_f32_16x16x32_bf16 v[52:55], v[160:163], v[184:187], v[52:55]
	v_mfma_f32_16x16x32_bf16 v[44:47], v[152:155], v[192:195], v[44:47]
	v_mfma_f32_16x16x32_bf16 v[36:39], v[160:163], v[192:195], v[36:39]
	v_mfma_f32_16x16x32_bf16 v[28:31], v[152:155], v[200:203], v[28:31]
	v_mfma_f32_16x16x32_bf16 v[20:23], v[160:163], v[200:203], v[20:23]
	v_mfma_f32_16x16x32_bf16 v[12:15], v[152:155], v[212:215], v[12:15]
	v_mfma_f32_16x16x32_bf16 v[4:7], v[160:163], v[212:215], v[4:7]
	v_mfma_f32_16x16x32_bf16 v[56:59], v[164:167], v[180:183], v[56:59]
	v_mfma_f32_16x16x32_bf16 v[48:51], v[172:175], v[180:183], v[48:51]
	v_mfma_f32_16x16x32_bf16 v[40:43], v[164:167], v[188:191], v[40:43]
	v_mfma_f32_16x16x32_bf16 v[32:35], v[172:175], v[188:191], v[32:35]
	v_mfma_f32_16x16x32_bf16 v[24:27], v[164:167], v[196:199], v[24:27]
	v_mfma_f32_16x16x32_bf16 v[16:19], v[172:175], v[196:199], v[16:19]
	v_mfma_f32_16x16x32_bf16 v[8:11], v[164:167], v[208:211], v[8:11]
	v_mfma_f32_16x16x32_bf16 v[0:3], v[172:175], v[208:211], v[0:3]
	v_mfma_f32_16x16x32_bf16 v[56:59], v[168:171], v[184:187], v[56:59]
	v_mfma_f32_16x16x32_bf16 v[48:51], v[176:179], v[184:187], v[48:51]
	v_mfma_f32_16x16x32_bf16 v[40:43], v[168:171], v[192:195], v[40:43]
	v_mfma_f32_16x16x32_bf16 v[32:35], v[176:179], v[192:195], v[32:35]
	v_mfma_f32_16x16x32_bf16 v[24:27], v[168:171], v[200:203], v[24:27]
	v_mfma_f32_16x16x32_bf16 v[16:19], v[176:179], v[200:203], v[16:19]
	v_mfma_f32_16x16x32_bf16 v[8:11], v[168:171], v[212:215], v[8:11]
	v_mfma_f32_16x16x32_bf16 v[0:3], v[176:179], v[212:215], v[0:3]
	s_setprio 0
	s_barrier
	s_add_i32 s68, s68, 2
	s_add_u32 s44, s44, 0x100
	s_addc_u32 s45, s45, 0
	s_add_u32 s66, s66, 0x100
	s_addc_u32 s67, s67, 0
	s_cmp_gt_u32 s68, 13
	s_cbranch_scc0 .LBB0_256
	s_and_b64 vcc, exec, s[8:9]
	s_cbranch_vccz .LBB0_259
	s_barrier

; #define PG8_STAGE(bufoff, gbase, voff) do { _Pragma("unroll") for (int _i = 0; _i < 2; ++_i) \
;         __builtin_amdgcn_global_load_lds((const unsigned*)((const char*)(gbase) + (voff)[_i]), (LAS unsigned*)(lds + (bufoff) + ldsw + _i * 8192), 16, 0, 0); } while (0)
; #define PG8_LDA(dst, b, h) do { _Pragma("unroll") for (int m = 0; m < 4; ++m) _Pragma("unroll") for (int k = 0; k < 2; ++k) dst[m][k] = *(const LAS bf16x8*)(lds + PG8_SA(b, h) + aoff + m * 2048 + k * 1024); } while (0)
; #define PG8_LDB(dst, b, h) do { _Pragma("unroll") for (int n = 0; n < 2; ++n) _Pragma("unroll") for (int k = 0; k < 2; ++k) dst[n][k] = *(const LAS bf16x8*)(lds + PG8_SB(b, h) + boff + n * 2048 + k * 1024); } while (0)
; #define PG8_WAIT_V(n) asm volatile("s_waitcnt vmcnt(" #n ")" ::: "memory")
; #define PG8_WAIT_L(n) asm volatile("s_waitcnt lgkmcnt(" #n ")" ::: "memory")
; #define PG8_BAR __builtin_amdgcn_s_barrier()
; #define PG8_SCHED __builtin_amdgcn_sched_barrier(0)
; template <class Epi, class Sched, bool SWAPD = false>
; __device__ __forceinline__ void gemm_phase(LAS unsigned char* lds, const Gemm g, const Sched& S, const Epi& E) {
;     ...
;             PG8_LDB(B0, 0, 0); PG8_LDB(B1, 0, 1); PG8_SCHED; PG8_LDA(At, 0, 0); PG8_STAGE(PG8_SA(1, 1), a1 + hstepA, voffA);
;             PG8_WAIT_V(8); PG8_WAIT_L(0); PG8_BAR; PG8_MMA(0, 0, At, B0); PG8_MMA(0, 1, At, B1); PG8_BAR; PG8_SCHED;
;             PG8_LDA(At, 0, 1); PG8_STAGE(PG8_SB(0, 0), b2, voffB); PG8_STAGE(PG8_SB(0, 1), b2 + hstepB, voffB); PG8_STAGE(PG8_SA(0, 0), a2, voffA);
;             PG8_WAIT_V(8); PG8_WAIT_L(0); PG8_BAR; PG8_MMA(1, 0, At, B0); PG8_MMA(1, 1, At, B1); PG8_BAR; PG8_SCHED;
.LBB0_353:
	v_add_u32_e32 v132, s57, v184
	ds_read_b128 v[174:177], v132
	ds_read_b128 v[178:181], v132 offset:1024
	ds_read_b128 v[188:191], v132 offset:2048
	ds_read_b128 v[192:195], v132 offset:3072
	v_add_u32_e32 v132, s64, v184
	ds_read_b128 v[196:199], v132
	ds_read_b128 v[200:203], v132 offset:1024
	ds_read_b128 v[208:211], v132 offset:2048
	ds_read_b128 v[212:215], v132 offset:3072
	s_add_i32 s77, s44, 2
	s_add_u32 s42, s38, 0x100
	s_addc_u32 s43, s39, 0
	s_cmp_eq_u32 s74, s44
	s_cselect_b32 s44, s35, s75
	s_cselect_b32 s47, s29, s43
	s_cselect_b32 s46, s33, s42
	s_cselect_b32 s45, s34, s76
	v_lshl_add_u64 v[182:183], s[38:39], 0, v[166:167]
	s_add_i32 m0, s30, 0xc000
	ds_read_b128 v[216:219], v186
	ds_read_b128 v[220:223], v186 offset:1024
	ds_read_b128 v[224:227], v186 offset:2048
	ds_read_b128 v[228:231], v186 offset:3072
	ds_read_b128 v[232:235], v186 offset:4096
	ds_read_b128 v[236:239], v186 offset:5120
	ds_read_b128 v[240:243], v186 offset:6144
	ds_read_b128 v[244:247], v186 offset:7168
	global_load_lds_dwordx4 v[182:183], off
	v_lshl_add_u64 v[182:183], s[38:39], 0, v[168:169]
	s_add_i32 m0, s30, 0xe000
	s_nop 0
	global_load_lds_dwordx4 v[182:183], off
	s_waitcnt vmcnt(8)
	s_waitcnt lgkmcnt(0)
	s_barrier
	s_setprio 1
	s_waitcnt lgkmcnt(0)
	v_mfma_f32_16x16x32_bf16 v[124:127], v[174:177], v[216:219], v[124:127]
	v_mfma_f32_16x16x32_bf16 v[120:123], v[188:191], v[216:219], v[120:123]
	v_mfma_f32_16x16x32_bf16 v[108:111], v[174:177], v[224:227], v[108:111]
	v_mfma_f32_16x16x32_bf16 v[104:107], v[188:191], v[224:227], v[104:107]
	v_mfma_f32_16x16x32_bf16 v[92:95], v[174:177], v[232:235], v[92:95]
	v_mfma_f32_16x16x32_bf16 v[88:91], v[188:191], v[232:235], v[88:91]
	v_mfma_f32_16x16x32_bf16 v[76:79], v[174:177], v[240:243], v[76:79]
	v_mfma_f32_16x16x32_bf16 v[72:75], v[188:191], v[240:243], v[72:75]
	v_mfma_f32_16x16x32_bf16 v[124:127], v[178:181], v[220:223], v[124:127]
	v_mfma_f32_16x16x32_bf16 v[120:123], v[192:195], v[220:223], v[120:123]
	v_mfma_f32_16x16x32_bf16 v[108:111], v[178:181], v[228:231], v[108:111]
	v_mfma_f32_16x16x32_bf16 v[104:107], v[192:195], v[228:231], v[104:107]
	v_mfma_f32_16x16x32_bf16 v[92:95], v[178:181], v[236:239], v[92:95]
	v_mfma_f32_16x16x32_bf16 v[88:91], v[192:195], v[236:239], v[88:91]
	v_mfma_f32_16x16x32_bf16 v[76:79], v[178:181], v[244:247], v[76:79]
	v_mfma_f32_16x16x32_bf16 v[72:75], v[192:195], v[244:247], v[72:75]
	v_mfma_f32_16x16x32_bf16 v[116:119], v[196:199], v[216:219], v[116:119]
	v_mfma_f32_16x16x32_bf16 v[112:115], v[208:211], v[216:219], v[112:115]
	v_mfma_f32_16x16x32_bf16 v[100:103], v[196:199], v[224:227], v[100:103]
	v_mfma_f32_16x16x32_bf16 v[96:99], v[208:211], v[224:227], v[96:99]
	v_mfma_f32_16x16x32_bf16 v[84:87], v[196:199], v[232:235], v[84:87]
	v_mfma_f32_16x16x32_bf16 v[80:83], v[208:211], v[232:235], v[80:83]
	v_mfma_f32_16x16x32_bf16 v[68:71], v[196:199], v[240:243], v[68:71]
	v_mfma_f32_16x16x32_bf16 v[64:67], v[208:211], v[240:243], v[64:67]
	v_mfma_f32_16x16x32_bf16 v[116:119], v[200:203], v[220:223], v[116:119]
	v_mfma_f32_16x16x32_bf16 v[112:115], v[212:215], v[220:223], v[112:115]
	v_mfma_f32_16x16x32_bf16 v[100:103], v[200:203], v[228:231], v[100:103]
	v_mfma_f32_16x16x32_bf16 v[96:99], v[212:215], v[228:231], v[96:99]
	v_mfma_f32_16x16x32_bf16 v[84:87], v[200:203], v[236:239], v[84:87]
	v_mfma_f32_16x16x32_bf16 v[80:83], v[212:215], v[236:239], v[80:83]
	v_mfma_f32_16x16x32_bf16 v[68:71], v[200:203], v[244:247], v[68:71]
	v_mfma_f32_16x16x32_bf16 v[64:67], v[212:215], v[244:247], v[64:67]
	s_setprio 0
	s_barrier
	s_add_i32 s38, s57, s21
	v_lshl_add_u64 v[182:183], s[44:45], 0, v[128:129]
	s_mov_b32 m0, s38
	ds_read_b128 v[216:219], v186 offset:16384
	ds_read_b128 v[220:223], v186 offset:17408
	ds_read_b128 v[224:227], v186 offset:18432
	ds_read_b128 v[228:231], v186 offset:19456
	ds_read_b128 v[232:235], v186 offset:20480
	ds_read_b128 v[236:239], v186 offset:21504
	ds_read_b128 v[240:243], v186 offset:22528
	ds_read_b128 v[244:247], v186 offset:23552
	global_load_lds_dwordx4 v[182:183], off
	s_add_i32 m0, s38, 0x2000
	s_add_u32 s38, s44, 0xb0000
	v_lshl_add_u64 v[204:205], s[44:45], 0, v[130:131]
	s_addc_u32 s39, s45, 0
	s_add_i32 s78, s64, s21
	global_load_lds_dwordx4 v[204:205], off
	v_lshl_add_u64 v[248:249], s[38:39], 0, v[128:129]
	s_mov_b32 m0, s78
	v_lshl_add_u64 v[250:251], s[46:47], 0, v[130:131]
	global_load_lds_dwordx4 v[248:249], off
	v_lshl_add_u64 v[248:249], s[38:39], 0, v[130:131]
	s_add_i32 m0, s78, 0x2000
	s_nop 0
	global_load_lds_dwordx4 v[248:249], off
	v_lshl_add_u64 v[248:249], s[46:47], 0, v[128:129]
	s_mov_b32 m0, s30
	s_nop 0
	global_load_lds_dwordx4 v[248:249], off
	s_mov_b32 m0, s31
	s_nop 0
	global_load_lds_dwordx4 v[250:251], off
	s_waitcnt vmcnt(8)
	s_waitcnt lgkmcnt(0)
	s_barrier
; #define PG8_STAGE(bufoff, gbase, voff) do { _Pragma("unroll") for (int _i = 0; _i < 2; ++_i) \
;         __builtin_amdgcn_global_load_lds((const unsigned*)((const char*)(gbase) + (voff)[_i]), (LAS unsigned*)(lds + (bufoff) + ldsw + _i * 8192), 16, 0, 0); } while (0)
; #define PG8_LDA(dst, b, h) do { _Pragma("unroll") for (int m = 0; m < 4; ++m) _Pragma("unroll") for (int k = 0; k < 2; ++k) dst[m][k] = *(const LAS bf16x8*)(lds + PG8_SA(b, h) + aoff + m * 2048 + k * 1024); } while (0)
; #define PG8_LDB(dst, b, h) do { _Pragma("unroll") for (int n = 0; n < 2; ++n) _Pragma("unroll") for (int k = 0; k < 2; ++k) dst[n][k] = *(const LAS bf16x8*)(lds + PG8_SB(b, h) + boff + n * 2048 + k * 1024); } while (0)
; #define PG8_WAIT_V(n) asm volatile("s_waitcnt vmcnt(" #n ")" ::: "memory")
; #define PG8_WAIT_L(n) asm volatile("s_waitcnt lgkmcnt(" #n ")" ::: "memory")
; #define PG8_BAR __builtin_amdgcn_s_barrier()
; #define PG8_SCHED __builtin_amdgcn_sched_barrier(0)
; template <class Epi, class Sched, bool SWAPD = false>
; __device__ __forceinline__ void gemm_phase(LAS unsigned char* lds, const Gemm g, const Sched& S, const Epi& E) {
;     ...
;             PG8_WAIT_V(8); PG8_WAIT_L(0); PG8_BAR; PG8_MMA(1, 0, At, B0); PG8_MMA(1, 1, At, B1); PG8_BAR; PG8_SCHED;
;             PG8_LDB(B0, 1, 0); PG8_LDB(B1, 1, 1); PG8_SCHED; PG8_LDA(At, 1, 0); PG8_STAGE(PG8_SA(0, 1), a2 + hstepA, voffA);
;             PG8_WAIT_V(8); PG8_WAIT_L(0); PG8_BAR; PG8_MMA(0, 0, At, B0); PG8_MMA(0, 1, At, B1); PG8_BAR; PG8_SCHED;
	s_setprio 1
	s_waitcnt lgkmcnt(0)
	v_mfma_f32_16x16x32_bf16 v[60:63], v[174:177], v[216:219], v[60:63]
	v_mfma_f32_16x16x32_bf16 v[56:59], v[188:191], v[216:219], v[56:59]
	v_mfma_f32_16x16x32_bf16 v[44:47], v[174:177], v[224:227], v[44:47]
	v_mfma_f32_16x16x32_bf16 v[40:43], v[188:191], v[224:227], v[40:43]
	v_mfma_f32_16x16x32_bf16 v[28:31], v[174:177], v[232:235], v[28:31]
	v_mfma_f32_16x16x32_bf16 v[24:27], v[188:191], v[232:235], v[24:27]
	v_mfma_f32_16x16x32_bf16 v[12:15], v[174:177], v[240:243], v[12:15]
	v_mfma_f32_16x16x32_bf16 v[8:11], v[188:191], v[240:243], v[8:11]
	v_mfma_f32_16x16x32_bf16 v[60:63], v[178:181], v[220:223], v[60:63]
	v_mfma_f32_16x16x32_bf16 v[56:59], v[192:195], v[220:223], v[56:59]
	v_mfma_f32_16x16x32_bf16 v[44:47], v[178:181], v[228:231], v[44:47]
	v_mfma_f32_16x16x32_bf16 v[40:43], v[192:195], v[228:231], v[40:43]
	v_mfma_f32_16x16x32_bf16 v[28:31], v[178:181], v[236:239], v[28:31]
	v_mfma_f32_16x16x32_bf16 v[24:27], v[192:195], v[236:239], v[24:27]
	v_mfma_f32_16x16x32_bf16 v[12:15], v[178:181], v[244:247], v[12:15]
	v_mfma_f32_16x16x32_bf16 v[8:11], v[192:195], v[244:247], v[8:11]
	v_mfma_f32_16x16x32_bf16 v[52:55], v[196:199], v[216:219], v[52:55]
	v_mfma_f32_16x16x32_bf16 v[48:51], v[208:211], v[216:219], v[48:51]
	v_mfma_f32_16x16x32_bf16 v[36:39], v[196:199], v[224:227], v[36:39]
	v_mfma_f32_16x16x32_bf16 v[32:35], v[208:211], v[224:227], v[32:35]
	v_mfma_f32_16x16x32_bf16 v[20:23], v[196:199], v[232:235], v[20:23]
	v_mfma_f32_16x16x32_bf16 v[16:19], v[208:211], v[232:235], v[16:19]
	v_mfma_f32_16x16x32_bf16 v[4:7], v[196:199], v[240:243], v[4:7]
	v_mfma_f32_16x16x32_bf16 v[0:3], v[208:211], v[240:243], v[0:3]
	v_mfma_f32_16x16x32_bf16 v[52:55], v[200:203], v[220:223], v[52:55]
	v_mfma_f32_16x16x32_bf16 v[48:51], v[212:215], v[220:223], v[48:51]
	v_mfma_f32_16x16x32_bf16 v[36:39], v[200:203], v[228:231], v[36:39]
	v_mfma_f32_16x16x32_bf16 v[32:35], v[212:215], v[228:231], v[32:35]
	v_mfma_f32_16x16x32_bf16 v[20:23], v[200:203], v[236:239], v[20:23]
	v_mfma_f32_16x16x32_bf16 v[16:19], v[212:215], v[236:239], v[16:19]
	v_mfma_f32_16x16x32_bf16 v[4:7], v[200:203], v[244:247], v[4:7]
	v_mfma_f32_16x16x32_bf16 v[0:3], v[212:215], v[244:247], v[0:3]
	s_setprio 0
	s_barrier
	s_add_i32 s78, 0, 0x18000
	v_add_u32_e32 v132, s78, v184
	s_add_i32 s79, 0, 0x1c000
	ds_read_b128 v[174:177], v132
	ds_read_b128 v[178:181], v132 offset:1024
	ds_read_b128 v[188:191], v132 offset:2048
	ds_read_b128 v[192:195], v132 offset:3072
	v_add_u32_e32 v132, s79, v184
	ds_read_b128 v[196:199], v132
	ds_read_b128 v[200:203], v132 offset:1024
	ds_read_b128 v[208:211], v132 offset:2048
	ds_read_b128 v[212:215], v132 offset:3072
	s_add_u32 s38, s46, 0xb0000
	s_addc_u32 s39, s47, 0
	s_mov_b32 m0, s50
	v_lshl_add_u64 v[252:253], s[38:39], 0, v[128:129]
	ds_read_b128 v[216:219], v186 offset:32768
	ds_read_b128 v[220:223], v186 offset:33792
	ds_read_b128 v[224:227], v186 offset:34816
	ds_read_b128 v[228:231], v186 offset:35840
	ds_read_b128 v[232:235], v186 offset:36864
	ds_read_b128 v[236:239], v186 offset:37888
	ds_read_b128 v[240:243], v186 offset:38912
	ds_read_b128 v[244:247], v186 offset:39936
	global_load_lds_dwordx4 v[252:253], off
	v_lshl_add_u64 v[252:253], s[38:39], 0, v[130:131]
	s_mov_b32 m0, s51
	s_nop 0
	global_load_lds_dwordx4 v[252:253], off
	s_waitcnt vmcnt(8)
	s_waitcnt lgkmcnt(0)
	s_barrier
	s_setprio 1
	s_waitcnt lgkmcnt(0)
	v_mfma_f32_16x16x32_bf16 v[124:127], v[174:177], v[216:219], v[124:127]
	v_mfma_f32_16x16x32_bf16 v[120:123], v[188:191], v[216:219], v[120:123]
	v_mfma_f32_16x16x32_bf16 v[108:111], v[174:177], v[224:227], v[108:111]
	v_mfma_f32_16x16x32_bf16 v[104:107], v[188:191], v[224:227], v[104:107]
	v_mfma_f32_16x16x32_bf16 v[92:95], v[174:177], v[232:235], v[92:95]
	v_mfma_f32_16x16x32_bf16 v[88:91], v[188:191], v[232:235], v[88:91]
	v_mfma_f32_16x16x32_bf16 v[76:79], v[174:177], v[240:243], v[76:79]
	v_mfma_f32_16x16x32_bf16 v[72:75], v[188:191], v[240:243], v[72:75]
	v_mfma_f32_16x16x32_bf16 v[124:127], v[178:181], v[220:223], v[124:127]
	v_mfma_f32_16x16x32_bf16 v[120:123], v[192:195], v[220:223], v[120:123]
	v_mfma_f32_16x16x32_bf16 v[108:111], v[178:181], v[228:231], v[108:111]
	v_mfma_f32_16x16x32_bf16 v[104:107], v[192:195], v[228:231], v[104:107]
	v_mfma_f32_16x16x32_bf16 v[92:95], v[178:181], v[236:239], v[92:95]
	v_mfma_f32_16x16x32_bf16 v[88:91], v[192:195], v[236:239], v[88:91]
	v_mfma_f32_16x16x32_bf16 v[76:79], v[178:181], v[244:247], v[76:79]
	v_mfma_f32_16x16x32_bf16 v[72:75], v[192:195], v[244:247], v[72:75]
	v_mfma_f32_16x16x32_bf16 v[116:119], v[196:199], v[216:219], v[116:119]
	v_mfma_f32_16x16x32_bf16 v[112:115], v[208:211], v[216:219], v[112:115]
	v_mfma_f32_16x16x32_bf16 v[100:103], v[196:199], v[224:227], v[100:103]
	v_mfma_f32_16x16x32_bf16 v[96:99], v[208:211], v[224:227], v[96:99]
	v_mfma_f32_16x16x32_bf16 v[84:87], v[196:199], v[232:235], v[84:87]
	v_mfma_f32_16x16x32_bf16 v[80:83], v[208:211], v[232:235], v[80:83]
	v_mfma_f32_16x16x32_bf16 v[68:71], v[196:199], v[240:243], v[68:71]
	v_mfma_f32_16x16x32_bf16 v[64:67], v[208:211], v[240:243], v[64:67]
	v_mfma_f32_16x16x32_bf16 v[116:119], v[200:203], v[220:223], v[116:119]
	v_mfma_f32_16x16x32_bf16 v[112:115], v[212:215], v[220:223], v[112:115]
	v_mfma_f32_16x16x32_bf16 v[100:103], v[200:203], v[228:231], v[100:103]
	v_mfma_f32_16x16x32_bf16 v[96:99], v[212:215], v[228:231], v[96:99]
	v_mfma_f32_16x16x32_bf16 v[84:87], v[200:203], v[236:239], v[84:87]
	v_mfma_f32_16x16x32_bf16 v[80:83], v[212:215], v[236:239], v[80:83]
	v_mfma_f32_16x16x32_bf16 v[68:71], v[200:203], v[244:247], v[68:71]
	v_mfma_f32_16x16x32_bf16 v[64:67], v[212:215], v[244:247], v[64:67]
	s_setprio 0
	s_barrier
; #define PG8_STAGE(bufoff, gbase, voff) do { _Pragma("unroll") for (int _i = 0; _i < 2; ++_i) \
;         __builtin_amdgcn_global_load_lds((const unsigned*)((const char*)(gbase) + (voff)[_i]), (LAS unsigned*)(lds + (bufoff) + ldsw + _i * 8192), 16, 0, 0); } while (0)
; #define PG8_LDA(dst, b, h) do { _Pragma("unroll") for (int m = 0; m < 4; ++m) _Pragma("unroll") for (int k = 0; k < 2; ++k) dst[m][k] = *(const LAS bf16x8*)(lds + PG8_SA(b, h) + aoff + m * 2048 + k * 1024); } while (0)
; #define PG8_WAIT_V(n) asm volatile("s_waitcnt vmcnt(" #n ")" ::: "memory")
; #define PG8_WAIT_L(n) asm volatile("s_waitcnt lgkmcnt(" #n ")" ::: "memory")
; #define PG8_BAR __builtin_amdgcn_s_barrier()
; #define PG8_SCHED __builtin_amdgcn_sched_barrier(0)
; template <class Epi, class Sched, bool SWAPD = false>
; __device__ __forceinline__ void gemm_phase(LAS unsigned char* lds, const Gemm g, const Sched& S, const Epi& E) {
;     ...
;             PG8_WAIT_V(8); PG8_WAIT_L(0); PG8_BAR; PG8_MMA(0, 0, At, B0); PG8_MMA(0, 1, At, B1); PG8_BAR; PG8_SCHED;
;             PG8_LDA(At, 1, 1); PG8_STAGE(PG8_SB(1, 0), b3, voffB); PG8_STAGE(PG8_SB(1, 1), b3 + hstepB, voffB); PG8_STAGE(PG8_SA(1, 0), a3, voffA);
;             PG8_WAIT_V(8); PG8_WAIT_L(0); PG8_BAR; PG8_MMA(1, 0, At, B0); PG8_MMA(1, 1, At, B1); PG8_BAR; PG8_SCHED;
;         }
	s_add_i32 s38, s78, s21
	v_lshl_add_u64 v[182:183], v[182:183], 0, s[8:9]
	s_mov_b32 m0, s38
	ds_read_b128 v[216:219], v186 offset:49152
	ds_read_b128 v[220:223], v186 offset:50176
	ds_read_b128 v[224:227], v186 offset:51200
	ds_read_b128 v[228:231], v186 offset:52224
	ds_read_b128 v[232:235], v186 offset:53248
	ds_read_b128 v[236:239], v186 offset:54272
	ds_read_b128 v[240:243], v186 offset:55296
	ds_read_b128 v[244:247], v186 offset:56320
	global_load_lds_dwordx4 v[182:183], off
	s_add_i32 m0, s38, 0x2000
	s_add_u32 s38, s44, 0xb0080
	v_lshl_add_u64 v[182:183], v[204:205], 0, s[8:9]
	s_addc_u32 s39, s45, 0
	s_add_i32 s44, s79, s21
	global_load_lds_dwordx4 v[182:183], off
	v_lshl_add_u64 v[182:183], s[38:39], 0, v[128:129]
	s_mov_b32 m0, s44
	s_nop 0
	global_load_lds_dwordx4 v[182:183], off
	v_lshl_add_u64 v[182:183], s[38:39], 0, v[130:131]
	s_add_i32 m0, s44, 0x2000
	s_nop 0
	global_load_lds_dwordx4 v[182:183], off
	v_lshl_add_u64 v[182:183], v[248:249], 0, s[8:9]
	s_mov_b32 m0, s54
	s_nop 0
	global_load_lds_dwordx4 v[182:183], off
	v_lshl_add_u64 v[182:183], v[250:251], 0, s[8:9]
	s_mov_b32 m0, s55
	s_nop 0
	global_load_lds_dwordx4 v[182:183], off
	s_waitcnt vmcnt(8)
	s_waitcnt lgkmcnt(0)
	s_barrier
	s_setprio 1
	s_waitcnt lgkmcnt(0)
	v_mfma_f32_16x16x32_bf16 v[60:63], v[174:177], v[216:219], v[60:63]
	v_mfma_f32_16x16x32_bf16 v[56:59], v[188:191], v[216:219], v[56:59]
	v_mfma_f32_16x16x32_bf16 v[44:47], v[174:177], v[224:227], v[44:47]
	v_mfma_f32_16x16x32_bf16 v[40:43], v[188:191], v[224:227], v[40:43]
	v_mfma_f32_16x16x32_bf16 v[28:31], v[174:177], v[232:235], v[28:31]
	v_mfma_f32_16x16x32_bf16 v[24:27], v[188:191], v[232:235], v[24:27]
	v_mfma_f32_16x16x32_bf16 v[12:15], v[174:177], v[240:243], v[12:15]
	v_mfma_f32_16x16x32_bf16 v[8:11], v[188:191], v[240:243], v[8:11]
	v_mfma_f32_16x16x32_bf16 v[60:63], v[178:181], v[220:223], v[60:63]
	v_mfma_f32_16x16x32_bf16 v[56:59], v[192:195], v[220:223], v[56:59]
	v_mfma_f32_16x16x32_bf16 v[44:47], v[178:181], v[228:231], v[44:47]
	v_mfma_f32_16x16x32_bf16 v[40:43], v[192:195], v[228:231], v[40:43]
	v_mfma_f32_16x16x32_bf16 v[28:31], v[178:181], v[236:239], v[28:31]
	v_mfma_f32_16x16x32_bf16 v[24:27], v[192:195], v[236:239], v[24:27]
	v_mfma_f32_16x16x32_bf16 v[12:15], v[178:181], v[244:247], v[12:15]
	v_mfma_f32_16x16x32_bf16 v[8:11], v[192:195], v[244:247], v[8:11]
	v_mfma_f32_16x16x32_bf16 v[52:55], v[196:199], v[216:219], v[52:55]
	v_mfma_f32_16x16x32_bf16 v[48:51], v[208:211], v[216:219], v[48:51]
	v_mfma_f32_16x16x32_bf16 v[36:39], v[196:199], v[224:227], v[36:39]
	v_mfma_f32_16x16x32_bf16 v[32:35], v[208:211], v[224:227], v[32:35]
	v_mfma_f32_16x16x32_bf16 v[20:23], v[196:199], v[232:235], v[20:23]
	v_mfma_f32_16x16x32_bf16 v[16:19], v[208:211], v[232:235], v[16:19]
	v_mfma_f32_16x16x32_bf16 v[4:7], v[196:199], v[240:243], v[4:7]
	v_mfma_f32_16x16x32_bf16 v[0:3], v[208:211], v[240:243], v[0:3]
	v_mfma_f32_16x16x32_bf16 v[52:55], v[200:203], v[220:223], v[52:55]
	v_mfma_f32_16x16x32_bf16 v[48:51], v[212:215], v[220:223], v[48:51]
	v_mfma_f32_16x16x32_bf16 v[36:39], v[200:203], v[228:231], v[36:39]
	v_mfma_f32_16x16x32_bf16 v[32:35], v[212:215], v[228:231], v[32:35]
	v_mfma_f32_16x16x32_bf16 v[20:23], v[200:203], v[236:239], v[20:23]
	v_mfma_f32_16x16x32_bf16 v[16:19], v[212:215], v[236:239], v[16:19]
	v_mfma_f32_16x16x32_bf16 v[4:7], v[200:203], v[244:247], v[4:7]
	v_mfma_f32_16x16x32_bf16 v[0:3], v[212:215], v[244:247], v[0:3]
	s_setprio 0
	s_barrier
	s_add_u32 s75, s75, 0x100
	s_addc_u32 s76, s76, 0
	s_cmp_ge_i32 s77, s0
	s_mov_b64 s[38:39], s[42:43]
	s_mov_b32 s44, s77
	s_cbranch_scc0 .LBB0_353
	s_and_b64 vcc, exec, s[10:11]
	s_cbranch_vccz .LBB0_359

; #define PG8_STAGE(bufoff, gbase, voff) do { _Pragma("unroll") for (int _i = 0; _i < 2; ++_i) \
;         __builtin_amdgcn_global_load_lds((const unsigned*)((const char*)(gbase) + (voff)[_i]), (LAS unsigned*)(lds + (bufoff) + ldsw + _i * 8192), 16, 0, 0); } while (0)
; #define PG8_LDA(dst, b, h) do { _Pragma("unroll") for (int m = 0; m < 4; ++m) _Pragma("unroll") for (int k = 0; k < 2; ++k) dst[m][k] = *(const LAS bf16x8*)(lds + PG8_SA(b, h) + aoff + m * 2048 + k * 1024); } while (0)
; #define PG8_LDB(dst, b, h) do { _Pragma("unroll") for (int n = 0; n < 2; ++n) _Pragma("unroll") for (int k = 0; k < 2; ++k) dst[n][k] = *(const LAS bf16x8*)(lds + PG8_SB(b, h) + boff + n * 2048 + k * 1024); } while (0)
; #define PG8_WAIT_V(n) asm volatile("s_waitcnt vmcnt(" #n ")" ::: "memory")
; #define PG8_WAIT_L(n) asm volatile("s_waitcnt lgkmcnt(" #n ")" ::: "memory")
; #define PG8_BAR __builtin_amdgcn_s_barrier()
; #define PG8_SCHED __builtin_amdgcn_sched_barrier(0)
; template <class Epi, class Sched, bool SWAPD = false>
; __device__ __forceinline__ void gemm_phase(LAS unsigned char* lds, const Gemm g, const Sched& S, const Epi& E) {
;     ...
;             PG8_LDB(B0, 0, 0); PG8_LDB(B1, 0, 1); PG8_SCHED; PG8_LDA(At, 0, 0); PG8_STAGE(PG8_SA(1, 1), a1 + hstepA, voffA);
;             PG8_WAIT_V(8); PG8_WAIT_L(0); PG8_BAR; PG8_MMA(0, 0, At, B0); PG8_MMA(0, 1, At, B1); PG8_BAR; PG8_SCHED;
;             PG8_LDA(At, 0, 1); PG8_STAGE(PG8_SB(0, 0), b2, voffB); PG8_STAGE(PG8_SB(0, 1), b2 + hstepB, voffB); PG8_STAGE(PG8_SA(0, 0), a2, voffA);
;             PG8_WAIT_V(8); PG8_WAIT_L(0); PG8_BAR; PG8_MMA(1, 0, At, B0); PG8_MMA(1, 1, At, B1); PG8_BAR; PG8_SCHED;
.LBB0_486:
	ds_read_b128 v[152:155], v149
	ds_read_b128 v[156:159], v149 offset:1024
	ds_read_b128 v[160:163], v149 offset:2048
	ds_read_b128 v[164:167], v149 offset:3072
	ds_read_b128 v[168:171], v150
	ds_read_b128 v[172:175], v150 offset:1024
	ds_read_b128 v[176:179], v150 offset:2048
	ds_read_b128 v[180:183], v150 offset:3072
	s_add_u32 s42, s40, 0xfffc0080
	s_addc_u32 s43, s41, -1
	s_cmp_eq_u32 s66, 12
	s_cselect_b32 s45, s7, s43
	s_cselect_b32 s44, s13, s42
	s_cselect_b32 s43, s25, s65
	s_cselect_b32 s42, s57, s64
	v_lshl_add_u64 v[204:205], s[40:41], 0, v[138:139]
	s_add_i32 m0, s30, 0xc000
	ds_read_b128 v[184:187], v151
	ds_read_b128 v[188:191], v151 offset:1024
	ds_read_b128 v[192:195], v151 offset:2048
	ds_read_b128 v[196:199], v151 offset:3072
	ds_read_b128 v[200:203], v151 offset:4096
	ds_read_b128 v[208:211], v151 offset:5120
	ds_read_b128 v[212:215], v151 offset:6144
	ds_read_b128 v[216:219], v151 offset:7168
	global_load_lds_dwordx4 v[204:205], off
	v_lshl_add_u64 v[204:205], s[40:41], 0, v[140:141]
	s_add_i32 m0, s30, 0xe000
	s_nop 0
	global_load_lds_dwordx4 v[204:205], off
	s_waitcnt vmcnt(8)
	s_waitcnt lgkmcnt(0)
	s_barrier
	s_setprio 1
	s_waitcnt lgkmcnt(0)
	v_mfma_f32_16x16x32_bf16 v[124:127], v[152:155], v[184:187], v[124:127]
	v_mfma_f32_16x16x32_bf16 v[120:123], v[160:163], v[184:187], v[120:123]
	v_mfma_f32_16x16x32_bf16 v[108:111], v[152:155], v[192:195], v[108:111]
	v_mfma_f32_16x16x32_bf16 v[104:107], v[160:163], v[192:195], v[104:107]
	v_mfma_f32_16x16x32_bf16 v[92:95], v[152:155], v[200:203], v[92:95]
	v_mfma_f32_16x16x32_bf16 v[88:91], v[160:163], v[200:203], v[88:91]
	v_mfma_f32_16x16x32_bf16 v[76:79], v[152:155], v[212:215], v[76:79]
	v_mfma_f32_16x16x32_bf16 v[72:75], v[160:163], v[212:215], v[72:75]
	v_mfma_f32_16x16x32_bf16 v[124:127], v[156:159], v[188:191], v[124:127]
	v_mfma_f32_16x16x32_bf16 v[120:123], v[164:167], v[188:191], v[120:123]
	v_mfma_f32_16x16x32_bf16 v[108:111], v[156:159], v[196:199], v[108:111]
	v_mfma_f32_16x16x32_bf16 v[104:107], v[164:167], v[196:199], v[104:107]
	v_mfma_f32_16x16x32_bf16 v[92:95], v[156:159], v[208:211], v[92:95]
	v_mfma_f32_16x16x32_bf16 v[88:91], v[164:167], v[208:211], v[88:91]
	v_mfma_f32_16x16x32_bf16 v[76:79], v[156:159], v[216:219], v[76:79]
	v_mfma_f32_16x16x32_bf16 v[72:75], v[164:167], v[216:219], v[72:75]
	v_mfma_f32_16x16x32_bf16 v[116:119], v[168:171], v[184:187], v[116:119]
	v_mfma_f32_16x16x32_bf16 v[112:115], v[176:179], v[184:187], v[112:115]
	v_mfma_f32_16x16x32_bf16 v[100:103], v[168:171], v[192:195], v[100:103]
	v_mfma_f32_16x16x32_bf16 v[96:99], v[176:179], v[192:195], v[96:99]
	v_mfma_f32_16x16x32_bf16 v[84:87], v[168:171], v[200:203], v[84:87]
	v_mfma_f32_16x16x32_bf16 v[80:83], v[176:179], v[200:203], v[80:83]
	v_mfma_f32_16x16x32_bf16 v[68:71], v[168:171], v[212:215], v[68:71]
	v_mfma_f32_16x16x32_bf16 v[64:67], v[176:179], v[212:215], v[64:67]
	v_mfma_f32_16x16x32_bf16 v[116:119], v[172:175], v[188:191], v[116:119]
	v_mfma_f32_16x16x32_bf16 v[112:115], v[180:183], v[188:191], v[112:115]
	v_mfma_f32_16x16x32_bf16 v[100:103], v[172:175], v[196:199], v[100:103]
	v_mfma_f32_16x16x32_bf16 v[96:99], v[180:183], v[196:199], v[96:99]
	v_mfma_f32_16x16x32_bf16 v[84:87], v[172:175], v[208:211], v[84:87]
	v_mfma_f32_16x16x32_bf16 v[80:83], v[180:183], v[208:211], v[80:83]
	v_mfma_f32_16x16x32_bf16 v[68:71], v[172:175], v[216:219], v[68:71]
	v_mfma_f32_16x16x32_bf16 v[64:67], v[180:183], v[216:219], v[64:67]
	s_setprio 0
	s_barrier
	s_add_i32 s67, s35, s21
	v_lshl_add_u64 v[204:205], s[42:43], 0, v[128:129]
	s_mov_b32 m0, s67
	ds_read_b128 v[184:187], v151 offset:16384
	ds_read_b128 v[188:191], v151 offset:17408
	ds_read_b128 v[192:195], v151 offset:18432
	ds_read_b128 v[196:199], v151 offset:19456
	ds_read_b128 v[200:203], v151 offset:20480
	ds_read_b128 v[208:211], v151 offset:21504
	ds_read_b128 v[212:215], v151 offset:22528
	ds_read_b128 v[216:219], v151 offset:23552
	global_load_lds_dwordx4 v[204:205], off
	s_add_i32 m0, s67, 0x2000
	s_add_u32 s68, s42, 0x40000
	v_lshl_add_u64 v[220:221], s[42:43], 0, v[130:131]
	s_addc_u32 s69, s43, 0
	s_add_i32 s67, s53, s21
	global_load_lds_dwordx4 v[220:221], off
	v_lshl_add_u64 v[222:223], s[68:69], 0, v[128:129]
	s_mov_b32 m0, s67
	v_lshl_add_u64 v[224:225], s[44:45], 0, v[130:131]
	global_load_lds_dwordx4 v[222:223], off
	v_lshl_add_u64 v[222:223], s[68:69], 0, v[130:131]
	s_add_i32 m0, s67, 0x2000
	s_nop 0
	global_load_lds_dwordx4 v[222:223], off
	v_lshl_add_u64 v[222:223], s[44:45], 0, v[128:129]
	s_mov_b32 m0, s30
	s_nop 0
	global_load_lds_dwordx4 v[222:223], off
	s_mov_b32 m0, s31
	s_nop 0
	global_load_lds_dwordx4 v[224:225], off
	s_waitcnt vmcnt(8)
	s_waitcnt lgkmcnt(0)
	s_barrier
; #define PG8_STAGE(bufoff, gbase, voff) do { _Pragma("unroll") for (int _i = 0; _i < 2; ++_i) \
;         __builtin_amdgcn_global_load_lds((const unsigned*)((const char*)(gbase) + (voff)[_i]), (LAS unsigned*)(lds + (bufoff) + ldsw + _i * 8192), 16, 0, 0); } while (0)
; #define PG8_LDA(dst, b, h) do { _Pragma("unroll") for (int m = 0; m < 4; ++m) _Pragma("unroll") for (int k = 0; k < 2; ++k) dst[m][k] = *(const LAS bf16x8*)(lds + PG8_SA(b, h) + aoff + m * 2048 + k * 1024); } while (0)
; #define PG8_LDB(dst, b, h) do { _Pragma("unroll") for (int n = 0; n < 2; ++n) _Pragma("unroll") for (int k = 0; k < 2; ++k) dst[n][k] = *(const LAS bf16x8*)(lds + PG8_SB(b, h) + boff + n * 2048 + k * 1024); } while (0)
; #define PG8_WAIT_V(n) asm volatile("s_waitcnt vmcnt(" #n ")" ::: "memory")
; #define PG8_WAIT_L(n) asm volatile("s_waitcnt lgkmcnt(" #n ")" ::: "memory")
; #define PG8_BAR __builtin_amdgcn_s_barrier()
; #define PG8_SCHED __builtin_amdgcn_sched_barrier(0)
; template <class Epi, class Sched, bool SWAPD = false>
; __device__ __forceinline__ void gemm_phase(LAS unsigned char* lds, const Gemm g, const Sched& S, const Epi& E) {
;     ...
;             PG8_WAIT_V(8); PG8_WAIT_L(0); PG8_BAR; PG8_MMA(1, 0, At, B0); PG8_MMA(1, 1, At, B1); PG8_BAR; PG8_SCHED;
;             PG8_LDB(B0, 1, 0); PG8_LDB(B1, 1, 1); PG8_SCHED; PG8_LDA(At, 1, 0); PG8_STAGE(PG8_SA(0, 1), a2 + hstepA, voffA);
;             PG8_WAIT_V(8); PG8_WAIT_L(0); PG8_BAR; PG8_MMA(0, 0, At, B0); PG8_MMA(0, 1, At, B1); PG8_BAR; PG8_SCHED;
	s_setprio 1
	s_waitcnt lgkmcnt(0)
	v_mfma_f32_16x16x32_bf16 v[60:63], v[152:155], v[184:187], v[60:63]
	v_mfma_f32_16x16x32_bf16 v[56:59], v[160:163], v[184:187], v[56:59]
	v_mfma_f32_16x16x32_bf16 v[44:47], v[152:155], v[192:195], v[44:47]
	v_mfma_f32_16x16x32_bf16 v[40:43], v[160:163], v[192:195], v[40:43]
	v_mfma_f32_16x16x32_bf16 v[28:31], v[152:155], v[200:203], v[28:31]
	v_mfma_f32_16x16x32_bf16 v[24:27], v[160:163], v[200:203], v[24:27]
	v_mfma_f32_16x16x32_bf16 v[12:15], v[152:155], v[212:215], v[12:15]
	v_mfma_f32_16x16x32_bf16 v[8:11], v[160:163], v[212:215], v[8:11]
	v_mfma_f32_16x16x32_bf16 v[60:63], v[156:159], v[188:191], v[60:63]
	v_mfma_f32_16x16x32_bf16 v[56:59], v[164:167], v[188:191], v[56:59]
	v_mfma_f32_16x16x32_bf16 v[44:47], v[156:159], v[196:199], v[44:47]
	v_mfma_f32_16x16x32_bf16 v[40:43], v[164:167], v[196:199], v[40:43]
	v_mfma_f32_16x16x32_bf16 v[28:31], v[156:159], v[208:211], v[28:31]
	v_mfma_f32_16x16x32_bf16 v[24:27], v[164:167], v[208:211], v[24:27]
	v_mfma_f32_16x16x32_bf16 v[12:15], v[156:159], v[216:219], v[12:15]
	v_mfma_f32_16x16x32_bf16 v[8:11], v[164:167], v[216:219], v[8:11]
	v_mfma_f32_16x16x32_bf16 v[52:55], v[168:171], v[184:187], v[52:55]
	v_mfma_f32_16x16x32_bf16 v[48:51], v[176:179], v[184:187], v[48:51]
	v_mfma_f32_16x16x32_bf16 v[36:39], v[168:171], v[192:195], v[36:39]
	v_mfma_f32_16x16x32_bf16 v[32:35], v[176:179], v[192:195], v[32:35]
	v_mfma_f32_16x16x32_bf16 v[20:23], v[168:171], v[200:203], v[20:23]
	v_mfma_f32_16x16x32_bf16 v[16:19], v[176:179], v[200:203], v[16:19]
	v_mfma_f32_16x16x32_bf16 v[4:7], v[168:171], v[212:215], v[4:7]
	v_mfma_f32_16x16x32_bf16 v[0:3], v[176:179], v[212:215], v[0:3]
	v_mfma_f32_16x16x32_bf16 v[52:55], v[172:175], v[188:191], v[52:55]
	v_mfma_f32_16x16x32_bf16 v[48:51], v[180:183], v[188:191], v[48:51]
	v_mfma_f32_16x16x32_bf16 v[36:39], v[172:175], v[196:199], v[36:39]
	v_mfma_f32_16x16x32_bf16 v[32:35], v[180:183], v[196:199], v[32:35]
	v_mfma_f32_16x16x32_bf16 v[20:23], v[172:175], v[208:211], v[20:23]
	v_mfma_f32_16x16x32_bf16 v[16:19], v[180:183], v[208:211], v[16:19]
	v_mfma_f32_16x16x32_bf16 v[4:7], v[172:175], v[216:219], v[4:7]
	v_mfma_f32_16x16x32_bf16 v[0:3], v[180:183], v[216:219], v[0:3]
	s_setprio 0
	s_barrier
	s_add_i32 s67, 0, 0x18000
	v_add_u32_e32 v132, s67, v146
	s_add_i32 s68, 0, 0x1c000
	ds_read_b128 v[152:155], v132
	ds_read_b128 v[156:159], v132 offset:1024
	ds_read_b128 v[160:163], v132 offset:2048
	ds_read_b128 v[164:167], v132 offset:3072
	v_add_u32_e32 v132, s68, v146
	ds_read_b128 v[168:171], v132
	ds_read_b128 v[172:175], v132 offset:1024
	ds_read_b128 v[176:179], v132 offset:2048
	ds_read_b128 v[180:183], v132 offset:3072
	s_add_u32 s44, s44, 0x40000
	s_addc_u32 s45, s45, 0
	s_mov_b32 m0, s33
	v_lshl_add_u64 v[226:227], s[44:45], 0, v[128:129]
	ds_read_b128 v[184:187], v151 offset:32768
	ds_read_b128 v[188:191], v151 offset:33792
	ds_read_b128 v[192:195], v151 offset:34816
	ds_read_b128 v[196:199], v151 offset:35840
	ds_read_b128 v[200:203], v151 offset:36864
	ds_read_b128 v[208:211], v151 offset:37888
	ds_read_b128 v[212:215], v151 offset:38912
	ds_read_b128 v[216:219], v151 offset:39936
	global_load_lds_dwordx4 v[226:227], off
	v_lshl_add_u64 v[226:227], s[44:45], 0, v[130:131]
	s_mov_b32 m0, s46
	s_nop 0
	global_load_lds_dwordx4 v[226:227], off
	s_waitcnt vmcnt(8)
	s_waitcnt lgkmcnt(0)
	s_barrier
	s_setprio 1
	s_waitcnt lgkmcnt(0)
	v_mfma_f32_16x16x32_bf16 v[124:127], v[152:155], v[184:187], v[124:127]
	v_mfma_f32_16x16x32_bf16 v[120:123], v[160:163], v[184:187], v[120:123]
	v_mfma_f32_16x16x32_bf16 v[108:111], v[152:155], v[192:195], v[108:111]
	v_mfma_f32_16x16x32_bf16 v[104:107], v[160:163], v[192:195], v[104:107]
	v_mfma_f32_16x16x32_bf16 v[92:95], v[152:155], v[200:203], v[92:95]
	v_mfma_f32_16x16x32_bf16 v[88:91], v[160:163], v[200:203], v[88:91]
	v_mfma_f32_16x16x32_bf16 v[76:79], v[152:155], v[212:215], v[76:79]
	v_mfma_f32_16x16x32_bf16 v[72:75], v[160:163], v[212:215], v[72:75]
	v_mfma_f32_16x16x32_bf16 v[124:127], v[156:159], v[188:191], v[124:127]
	v_mfma_f32_16x16x32_bf16 v[120:123], v[164:167], v[188:191], v[120:123]
	v_mfma_f32_16x16x32_bf16 v[108:111], v[156:159], v[196:199], v[108:111]
	v_mfma_f32_16x16x32_bf16 v[104:107], v[164:167], v[196:199], v[104:107]
	v_mfma_f32_16x16x32_bf16 v[92:95], v[156:159], v[208:211], v[92:95]
	v_mfma_f32_16x16x32_bf16 v[88:91], v[164:167], v[208:211], v[88:91]
	v_mfma_f32_16x16x32_bf16 v[76:79], v[156:159], v[216:219], v[76:79]
	v_mfma_f32_16x16x32_bf16 v[72:75], v[164:167], v[216:219], v[72:75]
	v_mfma_f32_16x16x32_bf16 v[116:119], v[168:171], v[184:187], v[116:119]
	v_mfma_f32_16x16x32_bf16 v[112:115], v[176:179], v[184:187], v[112:115]
	v_mfma_f32_16x16x32_bf16 v[100:103], v[168:171], v[192:195], v[100:103]
	v_mfma_f32_16x16x32_bf16 v[96:99], v[176:179], v[192:195], v[96:99]
	v_mfma_f32_16x16x32_bf16 v[84:87], v[168:171], v[200:203], v[84:87]
	v_mfma_f32_16x16x32_bf16 v[80:83], v[176:179], v[200:203], v[80:83]
	v_mfma_f32_16x16x32_bf16 v[68:71], v[168:171], v[212:215], v[68:71]
	v_mfma_f32_16x16x32_bf16 v[64:67], v[176:179], v[212:215], v[64:67]
	v_mfma_f32_16x16x32_bf16 v[116:119], v[172:175], v[188:191], v[116:119]
	v_mfma_f32_16x16x32_bf16 v[112:115], v[180:183], v[188:191], v[112:115]
	v_mfma_f32_16x16x32_bf16 v[100:103], v[172:175], v[196:199], v[100:103]
	v_mfma_f32_16x16x32_bf16 v[96:99], v[180:183], v[196:199], v[96:99]
	v_mfma_f32_16x16x32_bf16 v[84:87], v[172:175], v[208:211], v[84:87]
	v_mfma_f32_16x16x32_bf16 v[80:83], v[180:183], v[208:211], v[80:83]
	v_mfma_f32_16x16x32_bf16 v[68:71], v[172:175], v[216:219], v[68:71]
	v_mfma_f32_16x16x32_bf16 v[64:67], v[180:183], v[216:219], v[64:67]
	s_setprio 0
	s_barrier
; #define PG8_STAGE(bufoff, gbase, voff) do { _Pragma("unroll") for (int _i = 0; _i < 2; ++_i) \
;         __builtin_amdgcn_global_load_lds((const unsigned*)((const char*)(gbase) + (voff)[_i]), (LAS unsigned*)(lds + (bufoff) + ldsw + _i * 8192), 16, 0, 0); } while (0)
; #define PG8_LDA(dst, b, h) do { _Pragma("unroll") for (int m = 0; m < 4; ++m) _Pragma("unroll") for (int k = 0; k < 2; ++k) dst[m][k] = *(const LAS bf16x8*)(lds + PG8_SA(b, h) + aoff + m * 2048 + k * 1024); } while (0)
; #define PG8_WAIT_V(n) asm volatile("s_waitcnt vmcnt(" #n ")" ::: "memory")
; #define PG8_WAIT_L(n) asm volatile("s_waitcnt lgkmcnt(" #n ")" ::: "memory")
; #define PG8_BAR __builtin_amdgcn_s_barrier()
; #define PG8_SCHED __builtin_amdgcn_sched_barrier(0)
; template <class Epi, class Sched, bool SWAPD = false>
; __device__ __forceinline__ void gemm_phase(LAS unsigned char* lds, const Gemm g, const Sched& S, const Epi& E) {
;     ...
;             PG8_WAIT_V(8); PG8_WAIT_L(0); PG8_BAR; PG8_MMA(0, 0, At, B0); PG8_MMA(0, 1, At, B1); PG8_BAR; PG8_SCHED;
;             PG8_LDA(At, 1, 1); PG8_STAGE(PG8_SB(1, 0), b3, voffB); PG8_STAGE(PG8_SB(1, 1), b3 + hstepB, voffB); PG8_STAGE(PG8_SA(1, 0), a3, voffA);
;             PG8_WAIT_V(8); PG8_WAIT_L(0); PG8_BAR; PG8_MMA(1, 0, At, B0); PG8_MMA(1, 1, At, B1); PG8_BAR; PG8_SCHED;
;         }
	s_add_i32 s44, s67, s21
	v_lshl_add_u64 v[204:205], v[204:205], 0, s[8:9]
	s_mov_b32 m0, s44
	ds_read_b128 v[184:187], v151 offset:49152
	ds_read_b128 v[188:191], v151 offset:50176
	ds_read_b128 v[192:195], v151 offset:51200
	ds_read_b128 v[196:199], v151 offset:52224
	ds_read_b128 v[200:203], v151 offset:53248
	ds_read_b128 v[208:211], v151 offset:54272
	ds_read_b128 v[212:215], v151 offset:55296
	ds_read_b128 v[216:219], v151 offset:56320
	global_load_lds_dwordx4 v[204:205], off
	s_add_i32 m0, s44, 0x2000
	s_add_u32 s42, s42, 0x40080
	v_lshl_add_u64 v[204:205], v[220:221], 0, s[8:9]
	s_addc_u32 s43, s43, 0
	s_add_i32 s44, s68, s21
	global_load_lds_dwordx4 v[204:205], off
	v_lshl_add_u64 v[204:205], s[42:43], 0, v[128:129]
	s_mov_b32 m0, s44
	s_nop 0
	global_load_lds_dwordx4 v[204:205], off
	v_lshl_add_u64 v[204:205], s[42:43], 0, v[130:131]
	s_add_i32 m0, s44, 0x2000
	s_nop 0
	global_load_lds_dwordx4 v[204:205], off
	v_lshl_add_u64 v[204:205], v[222:223], 0, s[8:9]
	s_mov_b32 m0, s51
	s_nop 0
	global_load_lds_dwordx4 v[204:205], off
	v_lshl_add_u64 v[204:205], v[224:225], 0, s[8:9]
	s_mov_b32 m0, s52
	s_nop 0
	global_load_lds_dwordx4 v[204:205], off
	s_waitcnt vmcnt(8)
	s_waitcnt lgkmcnt(0)
	s_barrier
	s_setprio 1
	s_waitcnt lgkmcnt(0)
	v_mfma_f32_16x16x32_bf16 v[60:63], v[152:155], v[184:187], v[60:63]
	v_mfma_f32_16x16x32_bf16 v[56:59], v[160:163], v[184:187], v[56:59]
	v_mfma_f32_16x16x32_bf16 v[44:47], v[152:155], v[192:195], v[44:47]
	v_mfma_f32_16x16x32_bf16 v[40:43], v[160:163], v[192:195], v[40:43]
	v_mfma_f32_16x16x32_bf16 v[28:31], v[152:155], v[200:203], v[28:31]
	v_mfma_f32_16x16x32_bf16 v[24:27], v[160:163], v[200:203], v[24:27]
	v_mfma_f32_16x16x32_bf16 v[12:15], v[152:155], v[212:215], v[12:15]
	v_mfma_f32_16x16x32_bf16 v[8:11], v[160:163], v[212:215], v[8:11]
	v_mfma_f32_16x16x32_bf16 v[60:63], v[156:159], v[188:191], v[60:63]
	v_mfma_f32_16x16x32_bf16 v[56:59], v[164:167], v[188:191], v[56:59]
	v_mfma_f32_16x16x32_bf16 v[44:47], v[156:159], v[196:199], v[44:47]
	v_mfma_f32_16x16x32_bf16 v[40:43], v[164:167], v[196:199], v[40:43]
	v_mfma_f32_16x16x32_bf16 v[28:31], v[156:159], v[208:211], v[28:31]
	v_mfma_f32_16x16x32_bf16 v[24:27], v[164:167], v[208:211], v[24:27]
	v_mfma_f32_16x16x32_bf16 v[12:15], v[156:159], v[216:219], v[12:15]
	v_mfma_f32_16x16x32_bf16 v[8:11], v[164:167], v[216:219], v[8:11]
	v_mfma_f32_16x16x32_bf16 v[52:55], v[168:171], v[184:187], v[52:55]
	v_mfma_f32_16x16x32_bf16 v[48:51], v[176:179], v[184:187], v[48:51]
	v_mfma_f32_16x16x32_bf16 v[36:39], v[168:171], v[192:195], v[36:39]
	v_mfma_f32_16x16x32_bf16 v[32:35], v[176:179], v[192:195], v[32:35]
	v_mfma_f32_16x16x32_bf16 v[20:23], v[168:171], v[200:203], v[20:23]
	v_mfma_f32_16x16x32_bf16 v[16:19], v[176:179], v[200:203], v[16:19]
	v_mfma_f32_16x16x32_bf16 v[4:7], v[168:171], v[212:215], v[4:7]
	v_mfma_f32_16x16x32_bf16 v[0:3], v[176:179], v[212:215], v[0:3]
	v_mfma_f32_16x16x32_bf16 v[52:55], v[172:175], v[188:191], v[52:55]
	v_mfma_f32_16x16x32_bf16 v[48:51], v[180:183], v[188:191], v[48:51]
	v_mfma_f32_16x16x32_bf16 v[36:39], v[172:175], v[196:199], v[36:39]
	v_mfma_f32_16x16x32_bf16 v[32:35], v[180:183], v[196:199], v[32:35]
	v_mfma_f32_16x16x32_bf16 v[20:23], v[172:175], v[208:211], v[20:23]
	v_mfma_f32_16x16x32_bf16 v[16:19], v[180:183], v[208:211], v[16:19]
	v_mfma_f32_16x16x32_bf16 v[4:7], v[172:175], v[216:219], v[4:7]
	v_mfma_f32_16x16x32_bf16 v[0:3], v[180:183], v[216:219], v[0:3]
	s_setprio 0
	s_barrier
	s_add_i32 s66, s66, 2
	s_add_u32 s40, s40, 0x100
	s_addc_u32 s41, s41, 0
	s_add_u32 s64, s64, 0x100
	s_addc_u32 s65, s65, 0
	s_cmp_gt_u32 s66, 13
	s_cbranch_scc0 .LBB0_486
	s_and_b64 vcc, exec, s[10:11]
	s_cbranch_vccz .LBB0_489
	s_barrier

; #define PG8_STAGE(bufoff, gbase, voff) do { _Pragma("unroll") for (int _i = 0; _i < 2; ++_i) \
;         __builtin_amdgcn_global_load_lds((const unsigned*)((const char*)(gbase) + (voff)[_i]), (LAS unsigned*)(lds + (bufoff) + ldsw + _i * 8192), 16, 0, 0); } while (0)
; #define PG8_LDA(dst, b, h) do { _Pragma("unroll") for (int m = 0; m < 4; ++m) _Pragma("unroll") for (int k = 0; k < 2; ++k) dst[m][k] = *(const LAS bf16x8*)(lds + PG8_SA(b, h) + aoff + m * 2048 + k * 1024); } while (0)
; #define PG8_LDB(dst, b, h) do { _Pragma("unroll") for (int n = 0; n < 2; ++n) _Pragma("unroll") for (int k = 0; k < 2; ++k) dst[n][k] = *(const LAS bf16x8*)(lds + PG8_SB(b, h) + boff + n * 2048 + k * 1024); } while (0)
; #define PG8_WAIT_V(n) asm volatile("s_waitcnt vmcnt(" #n ")" ::: "memory")
; #define PG8_WAIT_L(n) asm volatile("s_waitcnt lgkmcnt(" #n ")" ::: "memory")
; #define PG8_BAR __builtin_amdgcn_s_barrier()
; #define PG8_SCHED __builtin_amdgcn_sched_barrier(0)
; template <class Epi, class Sched, bool SWAPD = false>
; __device__ __forceinline__ void gemm_phase(LAS unsigned char* lds, const Gemm g, const Sched& S, const Epi& E) {
;     ...
;             PG8_LDB(B0, 0, 0); PG8_LDB(B1, 0, 1); PG8_SCHED; PG8_LDA(At, 0, 0); PG8_STAGE(PG8_SA(1, 1), a1 + hstepA, voffA);
;             PG8_WAIT_V(8); PG8_WAIT_L(0); PG8_BAR; PG8_MMA(0, 0, At, B0); PG8_MMA(0, 1, At, B1); PG8_BAR; PG8_SCHED;
;             PG8_LDA(At, 0, 1); PG8_STAGE(PG8_SB(0, 0), b2, voffB); PG8_STAGE(PG8_SB(0, 1), b2 + hstepB, voffB); PG8_STAGE(PG8_SA(0, 0), a2, voffA);
;             PG8_WAIT_V(8); PG8_WAIT_L(0); PG8_BAR; PG8_MMA(1, 0, At, B0); PG8_MMA(1, 1, At, B1); PG8_BAR; PG8_SCHED;
.LBB0_633:
	ds_read_b128 v[152:155], v148
	ds_read_b128 v[156:159], v148 offset:1024
	ds_read_b128 v[160:163], v148 offset:2048
	ds_read_b128 v[164:167], v148 offset:3072
	ds_read_b128 v[168:171], v149
	ds_read_b128 v[172:175], v149 offset:1024
	ds_read_b128 v[176:179], v149 offset:2048
	ds_read_b128 v[180:183], v149 offset:3072
	s_add_u32 s52, s50, 0x100
	s_addc_u32 s53, s51, 0
	s_cmp_eq_u32 s81, 4
	s_cselect_b32 s57, s75, s53
	s_cselect_b32 s56, s76, s52
	s_cselect_b32 s55, s77, s80
	s_cselect_b32 s54, s78, s79
	v_lshl_add_u64 v[204:205], s[50:51], 0, v[138:139]
	s_add_i32 m0, s33, 0xc000
	ds_read_b128 v[184:187], v150
	ds_read_b128 v[188:191], v150 offset:1024
	ds_read_b128 v[192:195], v150 offset:2048
	ds_read_b128 v[196:199], v150 offset:3072
	ds_read_b128 v[200:203], v150 offset:4096
	ds_read_b128 v[208:211], v150 offset:5120
	ds_read_b128 v[212:215], v150 offset:6144
	ds_read_b128 v[216:219], v150 offset:7168
	global_load_lds_dwordx4 v[204:205], off
	v_lshl_add_u64 v[204:205], s[50:51], 0, v[140:141]
	s_add_i32 m0, s33, 0xe000
	s_nop 0
	global_load_lds_dwordx4 v[204:205], off
	s_waitcnt vmcnt(8)
	s_waitcnt lgkmcnt(0)
	s_barrier
	s_setprio 1
	s_waitcnt lgkmcnt(0)
	v_mfma_f32_16x16x32_bf16 v[124:127], v[152:155], v[184:187], v[124:127]
	v_mfma_f32_16x16x32_bf16 v[120:123], v[160:163], v[184:187], v[120:123]
	v_mfma_f32_16x16x32_bf16 v[116:119], v[152:155], v[192:195], v[116:119]
	v_mfma_f32_16x16x32_bf16 v[112:115], v[160:163], v[192:195], v[112:115]
	v_mfma_f32_16x16x32_bf16 v[104:107], v[152:155], v[200:203], v[104:107]
	v_mfma_f32_16x16x32_bf16 v[96:99], v[160:163], v[200:203], v[96:99]
	v_mfma_f32_16x16x32_bf16 v[88:91], v[152:155], v[212:215], v[88:91]
	v_mfma_f32_16x16x32_bf16 v[80:83], v[160:163], v[212:215], v[80:83]
	v_mfma_f32_16x16x32_bf16 v[124:127], v[156:159], v[188:191], v[124:127]
	v_mfma_f32_16x16x32_bf16 v[120:123], v[164:167], v[188:191], v[120:123]
	v_mfma_f32_16x16x32_bf16 v[116:119], v[156:159], v[196:199], v[116:119]
	v_mfma_f32_16x16x32_bf16 v[112:115], v[164:167], v[196:199], v[112:115]
	v_mfma_f32_16x16x32_bf16 v[104:107], v[156:159], v[208:211], v[104:107]
	v_mfma_f32_16x16x32_bf16 v[96:99], v[164:167], v[208:211], v[96:99]
	v_mfma_f32_16x16x32_bf16 v[88:91], v[156:159], v[216:219], v[88:91]
	v_mfma_f32_16x16x32_bf16 v[80:83], v[164:167], v[216:219], v[80:83]
	v_mfma_f32_16x16x32_bf16 v[108:111], v[168:171], v[184:187], v[108:111]
	v_mfma_f32_16x16x32_bf16 v[100:103], v[176:179], v[184:187], v[100:103]
	v_mfma_f32_16x16x32_bf16 v[92:95], v[168:171], v[192:195], v[92:95]
	v_mfma_f32_16x16x32_bf16 v[84:87], v[176:179], v[192:195], v[84:87]
	v_mfma_f32_16x16x32_bf16 v[76:79], v[168:171], v[200:203], v[76:79]
	v_mfma_f32_16x16x32_bf16 v[72:75], v[176:179], v[200:203], v[72:75]
	v_mfma_f32_16x16x32_bf16 v[68:71], v[168:171], v[212:215], v[68:71]
	v_mfma_f32_16x16x32_bf16 v[64:67], v[176:179], v[212:215], v[64:67]
	v_mfma_f32_16x16x32_bf16 v[108:111], v[172:175], v[188:191], v[108:111]
	v_mfma_f32_16x16x32_bf16 v[100:103], v[180:183], v[188:191], v[100:103]
	v_mfma_f32_16x16x32_bf16 v[92:95], v[172:175], v[196:199], v[92:95]
	v_mfma_f32_16x16x32_bf16 v[84:87], v[180:183], v[196:199], v[84:87]
	v_mfma_f32_16x16x32_bf16 v[76:79], v[172:175], v[208:211], v[76:79]
	v_mfma_f32_16x16x32_bf16 v[72:75], v[180:183], v[208:211], v[72:75]
	v_mfma_f32_16x16x32_bf16 v[68:71], v[172:175], v[216:219], v[68:71]
	v_mfma_f32_16x16x32_bf16 v[64:67], v[180:183], v[216:219], v[64:67]
	s_setprio 0
	s_barrier
	s_add_i32 s50, s64, s21
	v_lshl_add_u64 v[204:205], s[54:55], 0, v[132:133]
	s_mov_b32 m0, s50
	ds_read_b128 v[184:187], v150 offset:16384
	ds_read_b128 v[188:191], v150 offset:17408
	ds_read_b128 v[192:195], v150 offset:18432
	ds_read_b128 v[196:199], v150 offset:19456
	ds_read_b128 v[200:203], v150 offset:20480
	ds_read_b128 v[208:211], v150 offset:21504
	ds_read_b128 v[212:215], v150 offset:22528
	ds_read_b128 v[216:219], v150 offset:23552
	global_load_lds_dwordx4 v[204:205], off
	s_add_i32 m0, s50, 0x2000
	s_add_u32 s50, s54, 0x20000
	v_lshl_add_u64 v[220:221], s[54:55], 0, v[128:129]
	s_addc_u32 s51, s55, 0
	s_add_i32 s82, s65, s21
	global_load_lds_dwordx4 v[220:221], off
	v_lshl_add_u64 v[222:223], s[50:51], 0, v[132:133]
	s_mov_b32 m0, s82
	v_lshl_add_u64 v[224:225], s[56:57], 0, v[130:131]
	global_load_lds_dwordx4 v[222:223], off
	v_lshl_add_u64 v[222:223], s[50:51], 0, v[128:129]
	s_add_i32 m0, s82, 0x2000
	s_nop 0
	global_load_lds_dwordx4 v[222:223], off
	v_lshl_add_u64 v[222:223], s[56:57], 0, v[134:135]
	s_mov_b32 m0, s33
	s_nop 0
	global_load_lds_dwordx4 v[222:223], off
	s_mov_b32 m0, s34
	s_nop 0
	global_load_lds_dwordx4 v[224:225], off
	s_waitcnt vmcnt(8)
	s_waitcnt lgkmcnt(0)
	s_barrier
; #define PG8_STAGE(bufoff, gbase, voff) do { _Pragma("unroll") for (int _i = 0; _i < 2; ++_i) \
;         __builtin_amdgcn_global_load_lds((const unsigned*)((const char*)(gbase) + (voff)[_i]), (LAS unsigned*)(lds + (bufoff) + ldsw + _i * 8192), 16, 0, 0); } while (0)
; #define PG8_LDA(dst, b, h) do { _Pragma("unroll") for (int m = 0; m < 4; ++m) _Pragma("unroll") for (int k = 0; k < 2; ++k) dst[m][k] = *(const LAS bf16x8*)(lds + PG8_SA(b, h) + aoff + m * 2048 + k * 1024); } while (0)
; #define PG8_LDB(dst, b, h) do { _Pragma("unroll") for (int n = 0; n < 2; ++n) _Pragma("unroll") for (int k = 0; k < 2; ++k) dst[n][k] = *(const LAS bf16x8*)(lds + PG8_SB(b, h) + boff + n * 2048 + k * 1024); } while (0)
; #define PG8_WAIT_V(n) asm volatile("s_waitcnt vmcnt(" #n ")" ::: "memory")
; #define PG8_WAIT_L(n) asm volatile("s_waitcnt lgkmcnt(" #n ")" ::: "memory")
; #define PG8_BAR __builtin_amdgcn_s_barrier()
; #define PG8_SCHED __builtin_amdgcn_sched_barrier(0)
; template <class Epi, class Sched, bool SWAPD = false>
; __device__ __forceinline__ void gemm_phase(LAS unsigned char* lds, const Gemm g, const Sched& S, const Epi& E) {
;     ...
;             PG8_WAIT_V(8); PG8_WAIT_L(0); PG8_BAR; PG8_MMA(1, 0, At, B0); PG8_MMA(1, 1, At, B1); PG8_BAR; PG8_SCHED;
;             PG8_LDB(B0, 1, 0); PG8_LDB(B1, 1, 1); PG8_SCHED; PG8_LDA(At, 1, 0); PG8_STAGE(PG8_SA(0, 1), a2 + hstepA, voffA);
;             PG8_WAIT_V(8); PG8_WAIT_L(0); PG8_BAR; PG8_MMA(0, 0, At, B0); PG8_MMA(0, 1, At, B1); PG8_BAR; PG8_SCHED;
	s_setprio 1
	s_waitcnt lgkmcnt(0)
	v_mfma_f32_16x16x32_bf16 v[60:63], v[152:155], v[184:187], v[60:63]
	v_mfma_f32_16x16x32_bf16 v[56:59], v[160:163], v[184:187], v[56:59]
	v_mfma_f32_16x16x32_bf16 v[52:55], v[152:155], v[192:195], v[52:55]
	v_mfma_f32_16x16x32_bf16 v[48:51], v[160:163], v[192:195], v[48:51]
	v_mfma_f32_16x16x32_bf16 v[40:43], v[152:155], v[200:203], v[40:43]
	v_mfma_f32_16x16x32_bf16 v[32:35], v[160:163], v[200:203], v[32:35]
	v_mfma_f32_16x16x32_bf16 v[24:27], v[152:155], v[212:215], v[24:27]
	v_mfma_f32_16x16x32_bf16 v[16:19], v[160:163], v[212:215], v[16:19]
	v_mfma_f32_16x16x32_bf16 v[60:63], v[156:159], v[188:191], v[60:63]
	v_mfma_f32_16x16x32_bf16 v[56:59], v[164:167], v[188:191], v[56:59]
	v_mfma_f32_16x16x32_bf16 v[52:55], v[156:159], v[196:199], v[52:55]
	v_mfma_f32_16x16x32_bf16 v[48:51], v[164:167], v[196:199], v[48:51]
	v_mfma_f32_16x16x32_bf16 v[40:43], v[156:159], v[208:211], v[40:43]
	v_mfma_f32_16x16x32_bf16 v[32:35], v[164:167], v[208:211], v[32:35]
	v_mfma_f32_16x16x32_bf16 v[24:27], v[156:159], v[216:219], v[24:27]
	v_mfma_f32_16x16x32_bf16 v[16:19], v[164:167], v[216:219], v[16:19]
	v_mfma_f32_16x16x32_bf16 v[44:47], v[168:171], v[184:187], v[44:47]
	v_mfma_f32_16x16x32_bf16 v[36:39], v[176:179], v[184:187], v[36:39]
	v_mfma_f32_16x16x32_bf16 v[28:31], v[168:171], v[192:195], v[28:31]
	v_mfma_f32_16x16x32_bf16 v[20:23], v[176:179], v[192:195], v[20:23]
	v_mfma_f32_16x16x32_bf16 v[12:15], v[168:171], v[200:203], v[12:15]
	v_mfma_f32_16x16x32_bf16 v[8:11], v[176:179], v[200:203], v[8:11]
	v_mfma_f32_16x16x32_bf16 v[4:7], v[168:171], v[212:215], v[4:7]
	v_mfma_f32_16x16x32_bf16 v[0:3], v[176:179], v[212:215], v[0:3]
	v_mfma_f32_16x16x32_bf16 v[44:47], v[172:175], v[188:191], v[44:47]
	v_mfma_f32_16x16x32_bf16 v[36:39], v[180:183], v[188:191], v[36:39]
	v_mfma_f32_16x16x32_bf16 v[28:31], v[172:175], v[196:199], v[28:31]
	v_mfma_f32_16x16x32_bf16 v[20:23], v[180:183], v[196:199], v[20:23]
	v_mfma_f32_16x16x32_bf16 v[12:15], v[172:175], v[208:211], v[12:15]
	v_mfma_f32_16x16x32_bf16 v[8:11], v[180:183], v[208:211], v[8:11]
	v_mfma_f32_16x16x32_bf16 v[4:7], v[172:175], v[216:219], v[4:7]
	v_mfma_f32_16x16x32_bf16 v[0:3], v[180:183], v[216:219], v[0:3]
	s_setprio 0
	s_barrier
	s_add_i32 s82, 0, 0x18000
	v_add_u32_e32 v151, s82, v147
	s_add_i32 s83, 0, 0x1c000
	ds_read_b128 v[152:155], v151
	ds_read_b128 v[156:159], v151 offset:1024
	ds_read_b128 v[160:163], v151 offset:2048
	ds_read_b128 v[164:167], v151 offset:3072
	v_add_u32_e32 v151, s83, v147
	ds_read_b128 v[168:171], v151
	ds_read_b128 v[172:175], v151 offset:1024
	ds_read_b128 v[176:179], v151 offset:2048
	ds_read_b128 v[180:183], v151 offset:3072
	s_add_u32 s50, s56, 0x30000
	s_addc_u32 s51, s57, 0
	s_mov_b32 m0, s35
	v_lshl_add_u64 v[226:227], s[50:51], 0, v[134:135]
	ds_read_b128 v[184:187], v150 offset:32768
	ds_read_b128 v[188:191], v150 offset:33792
	ds_read_b128 v[192:195], v150 offset:34816
	ds_read_b128 v[196:199], v150 offset:35840
	ds_read_b128 v[200:203], v150 offset:36864
	ds_read_b128 v[208:211], v150 offset:37888
	ds_read_b128 v[212:215], v150 offset:38912
	ds_read_b128 v[216:219], v150 offset:39936
	global_load_lds_dwordx4 v[226:227], off
	v_lshl_add_u64 v[226:227], s[50:51], 0, v[130:131]
	s_mov_b32 m0, s58
	s_nop 0
	global_load_lds_dwordx4 v[226:227], off
	s_waitcnt vmcnt(8)
	s_waitcnt lgkmcnt(0)
	s_barrier
	s_setprio 1
	s_waitcnt lgkmcnt(0)
	v_mfma_f32_16x16x32_bf16 v[124:127], v[152:155], v[184:187], v[124:127]
	v_mfma_f32_16x16x32_bf16 v[120:123], v[160:163], v[184:187], v[120:123]
	v_mfma_f32_16x16x32_bf16 v[116:119], v[152:155], v[192:195], v[116:119]
	v_mfma_f32_16x16x32_bf16 v[112:115], v[160:163], v[192:195], v[112:115]
	v_mfma_f32_16x16x32_bf16 v[104:107], v[152:155], v[200:203], v[104:107]
	v_mfma_f32_16x16x32_bf16 v[96:99], v[160:163], v[200:203], v[96:99]
	v_mfma_f32_16x16x32_bf16 v[88:91], v[152:155], v[212:215], v[88:91]
	v_mfma_f32_16x16x32_bf16 v[80:83], v[160:163], v[212:215], v[80:83]
	v_mfma_f32_16x16x32_bf16 v[124:127], v[156:159], v[188:191], v[124:127]
	v_mfma_f32_16x16x32_bf16 v[120:123], v[164:167], v[188:191], v[120:123]
	v_mfma_f32_16x16x32_bf16 v[116:119], v[156:159], v[196:199], v[116:119]
	v_mfma_f32_16x16x32_bf16 v[112:115], v[164:167], v[196:199], v[112:115]
	v_mfma_f32_16x16x32_bf16 v[104:107], v[156:159], v[208:211], v[104:107]
	v_mfma_f32_16x16x32_bf16 v[96:99], v[164:167], v[208:211], v[96:99]
	v_mfma_f32_16x16x32_bf16 v[88:91], v[156:159], v[216:219], v[88:91]
	v_mfma_f32_16x16x32_bf16 v[80:83], v[164:167], v[216:219], v[80:83]
	v_mfma_f32_16x16x32_bf16 v[108:111], v[168:171], v[184:187], v[108:111]
	v_mfma_f32_16x16x32_bf16 v[100:103], v[176:179], v[184:187], v[100:103]
	v_mfma_f32_16x16x32_bf16 v[92:95], v[168:171], v[192:195], v[92:95]
	v_mfma_f32_16x16x32_bf16 v[84:87], v[176:179], v[192:195], v[84:87]
	v_mfma_f32_16x16x32_bf16 v[76:79], v[168:171], v[200:203], v[76:79]
	v_mfma_f32_16x16x32_bf16 v[72:75], v[176:179], v[200:203], v[72:75]
	v_mfma_f32_16x16x32_bf16 v[68:71], v[168:171], v[212:215], v[68:71]
	v_mfma_f32_16x16x32_bf16 v[64:67], v[176:179], v[212:215], v[64:67]
	v_mfma_f32_16x16x32_bf16 v[108:111], v[172:175], v[188:191], v[108:111]
	v_mfma_f32_16x16x32_bf16 v[100:103], v[180:183], v[188:191], v[100:103]
	v_mfma_f32_16x16x32_bf16 v[92:95], v[172:175], v[196:199], v[92:95]
	v_mfma_f32_16x16x32_bf16 v[84:87], v[180:183], v[196:199], v[84:87]
	v_mfma_f32_16x16x32_bf16 v[76:79], v[172:175], v[208:211], v[76:79]
	v_mfma_f32_16x16x32_bf16 v[72:75], v[180:183], v[208:211], v[72:75]
	v_mfma_f32_16x16x32_bf16 v[68:71], v[172:175], v[216:219], v[68:71]
	v_mfma_f32_16x16x32_bf16 v[64:67], v[180:183], v[216:219], v[64:67]
	s_setprio 0
	s_barrier
; #define PG8_STAGE(bufoff, gbase, voff) do { _Pragma("unroll") for (int _i = 0; _i < 2; ++_i) \
;         __builtin_amdgcn_global_load_lds((const unsigned*)((const char*)(gbase) + (voff)[_i]), (LAS unsigned*)(lds + (bufoff) + ldsw + _i * 8192), 16, 0, 0); } while (0)
; #define PG8_LDA(dst, b, h) do { _Pragma("unroll") for (int m = 0; m < 4; ++m) _Pragma("unroll") for (int k = 0; k < 2; ++k) dst[m][k] = *(const LAS bf16x8*)(lds + PG8_SA(b, h) + aoff + m * 2048 + k * 1024); } while (0)
; #define PG8_WAIT_V(n) asm volatile("s_waitcnt vmcnt(" #n ")" ::: "memory")
; #define PG8_WAIT_L(n) asm volatile("s_waitcnt lgkmcnt(" #n ")" ::: "memory")
; #define PG8_BAR __builtin_amdgcn_s_barrier()
; #define PG8_SCHED __builtin_amdgcn_sched_barrier(0)
; template <class Epi, class Sched, bool SWAPD = false>
; __device__ __forceinline__ void gemm_phase(LAS unsigned char* lds, const Gemm g, const Sched& S, const Epi& E) {
;     ...
;             PG8_WAIT_V(8); PG8_WAIT_L(0); PG8_BAR; PG8_MMA(0, 0, At, B0); PG8_MMA(0, 1, At, B1); PG8_BAR; PG8_SCHED;
;             PG8_LDA(At, 1, 1); PG8_STAGE(PG8_SB(1, 0), b3, voffB); PG8_STAGE(PG8_SB(1, 1), b3 + hstepB, voffB); PG8_STAGE(PG8_SA(1, 0), a3, voffA);
;             PG8_WAIT_V(8); PG8_WAIT_L(0); PG8_BAR; PG8_MMA(1, 0, At, B0); PG8_MMA(1, 1, At, B1); PG8_BAR; PG8_SCHED;
;         }
	s_add_i32 s50, s82, s21
	v_lshl_add_u64 v[204:205], v[204:205], 0, s[10:11]
	s_mov_b32 m0, s50
	ds_read_b128 v[184:187], v150 offset:49152
	ds_read_b128 v[188:191], v150 offset:50176
	ds_read_b128 v[192:195], v150 offset:51200
	ds_read_b128 v[196:199], v150 offset:52224
	ds_read_b128 v[200:203], v150 offset:53248
	ds_read_b128 v[208:211], v150 offset:54272
	ds_read_b128 v[212:215], v150 offset:55296
	ds_read_b128 v[216:219], v150 offset:56320
	global_load_lds_dwordx4 v[204:205], off
	s_add_i32 m0, s50, 0x2000
	s_add_u32 s50, s54, 0x20080
	v_lshl_add_u64 v[204:205], v[220:221], 0, s[10:11]
	s_addc_u32 s51, s55, 0
	s_add_i32 s54, s83, s21
	global_load_lds_dwordx4 v[204:205], off
	v_lshl_add_u64 v[204:205], s[50:51], 0, v[132:133]
	s_mov_b32 m0, s54
	s_nop 0
	global_load_lds_dwordx4 v[204:205], off
	v_lshl_add_u64 v[204:205], s[50:51], 0, v[128:129]
	s_add_i32 m0, s54, 0x2000
	s_nop 0
	global_load_lds_dwordx4 v[204:205], off
	v_lshl_add_u64 v[204:205], v[222:223], 0, s[10:11]
	s_mov_b32 m0, s60
	s_nop 0
	global_load_lds_dwordx4 v[204:205], off
	v_lshl_add_u64 v[204:205], v[224:225], 0, s[10:11]
	s_mov_b32 m0, s61
	s_nop 0
	global_load_lds_dwordx4 v[204:205], off
	s_waitcnt vmcnt(8)
	s_waitcnt lgkmcnt(0)
	s_barrier
	s_setprio 1
	s_waitcnt lgkmcnt(0)
	v_mfma_f32_16x16x32_bf16 v[60:63], v[152:155], v[184:187], v[60:63]
	v_mfma_f32_16x16x32_bf16 v[56:59], v[160:163], v[184:187], v[56:59]
	v_mfma_f32_16x16x32_bf16 v[52:55], v[152:155], v[192:195], v[52:55]
	v_mfma_f32_16x16x32_bf16 v[48:51], v[160:163], v[192:195], v[48:51]
	v_mfma_f32_16x16x32_bf16 v[40:43], v[152:155], v[200:203], v[40:43]
	v_mfma_f32_16x16x32_bf16 v[32:35], v[160:163], v[200:203], v[32:35]
	v_mfma_f32_16x16x32_bf16 v[24:27], v[152:155], v[212:215], v[24:27]
	v_mfma_f32_16x16x32_bf16 v[16:19], v[160:163], v[212:215], v[16:19]
	v_mfma_f32_16x16x32_bf16 v[60:63], v[156:159], v[188:191], v[60:63]
	v_mfma_f32_16x16x32_bf16 v[56:59], v[164:167], v[188:191], v[56:59]
	v_mfma_f32_16x16x32_bf16 v[52:55], v[156:159], v[196:199], v[52:55]
	v_mfma_f32_16x16x32_bf16 v[48:51], v[164:167], v[196:199], v[48:51]
	v_mfma_f32_16x16x32_bf16 v[40:43], v[156:159], v[208:211], v[40:43]
	v_mfma_f32_16x16x32_bf16 v[32:35], v[164:167], v[208:211], v[32:35]
	v_mfma_f32_16x16x32_bf16 v[24:27], v[156:159], v[216:219], v[24:27]
	v_mfma_f32_16x16x32_bf16 v[16:19], v[164:167], v[216:219], v[16:19]
	v_mfma_f32_16x16x32_bf16 v[44:47], v[168:171], v[184:187], v[44:47]
	v_mfma_f32_16x16x32_bf16 v[36:39], v[176:179], v[184:187], v[36:39]
	v_mfma_f32_16x16x32_bf16 v[28:31], v[168:171], v[192:195], v[28:31]
	v_mfma_f32_16x16x32_bf16 v[20:23], v[176:179], v[192:195], v[20:23]
	v_mfma_f32_16x16x32_bf16 v[12:15], v[168:171], v[200:203], v[12:15]
	v_mfma_f32_16x16x32_bf16 v[8:11], v[176:179], v[200:203], v[8:11]
	v_mfma_f32_16x16x32_bf16 v[4:7], v[168:171], v[212:215], v[4:7]
	v_mfma_f32_16x16x32_bf16 v[0:3], v[176:179], v[212:215], v[0:3]
	v_mfma_f32_16x16x32_bf16 v[44:47], v[172:175], v[188:191], v[44:47]
	v_mfma_f32_16x16x32_bf16 v[36:39], v[180:183], v[188:191], v[36:39]
	v_mfma_f32_16x16x32_bf16 v[28:31], v[172:175], v[196:199], v[28:31]
	v_mfma_f32_16x16x32_bf16 v[20:23], v[180:183], v[196:199], v[20:23]
	v_mfma_f32_16x16x32_bf16 v[12:15], v[172:175], v[208:211], v[12:15]
	v_mfma_f32_16x16x32_bf16 v[8:11], v[180:183], v[208:211], v[8:11]
	v_mfma_f32_16x16x32_bf16 v[4:7], v[172:175], v[216:219], v[4:7]
	v_mfma_f32_16x16x32_bf16 v[0:3], v[180:183], v[216:219], v[0:3]
	s_setprio 0
	s_barrier
	s_add_i32 s81, s81, 2
	s_add_u32 s79, s79, 0x100
	s_addc_u32 s80, s80, 0
	s_cmp_gt_u32 s81, 5
	s_mov_b64 s[50:51], s[52:53]
	s_cbranch_scc0 .LBB0_633
	s_and_b64 vcc, exec, s[12:13]
	s_cbranch_vccz .LBB0_636
	s_barrier

; #define PG8_STAGE(bufoff, gbase, voff) do { _Pragma("unroll") for (int _i = 0; _i < 2; ++_i) \
;         __builtin_amdgcn_global_load_lds((const unsigned*)((const char*)(gbase) + (voff)[_i]), (LAS unsigned*)(lds + (bufoff) + ldsw + _i * 8192), 16, 0, 0); } while (0)
; #define PG8_LDA(dst, b, h) do { _Pragma("unroll") for (int m = 0; m < 4; ++m) _Pragma("unroll") for (int k = 0; k < 2; ++k) dst[m][k] = *(const LAS bf16x8*)(lds + PG8_SA(b, h) + aoff + m * 2048 + k * 1024); } while (0)
; #define PG8_LDB(dst, b, h) do { _Pragma("unroll") for (int n = 0; n < 2; ++n) _Pragma("unroll") for (int k = 0; k < 2; ++k) dst[n][k] = *(const LAS bf16x8*)(lds + PG8_SB(b, h) + boff + n * 2048 + k * 1024); } while (0)
; #define PG8_WAIT_V(n) asm volatile("s_waitcnt vmcnt(" #n ")" ::: "memory")
; #define PG8_WAIT_L(n) asm volatile("s_waitcnt lgkmcnt(" #n ")" ::: "memory")
; #define PG8_BAR __builtin_amdgcn_s_barrier()
; #define PG8_SCHED __builtin_amdgcn_sched_barrier(0)
; template <class Epi, class Sched, bool SWAPD = false>
; __device__ __forceinline__ void gemm_phase(LAS unsigned char* lds, const Gemm g, const Sched& S, const Epi& E) {
;     ...
;             PG8_LDB(B0, 0, 0); PG8_LDB(B1, 0, 1); PG8_SCHED; PG8_LDA(At, 0, 0); PG8_STAGE(PG8_SA(1, 1), a1 + hstepA, voffA);
;             PG8_WAIT_V(8); PG8_WAIT_L(0); PG8_BAR; PG8_MMA(0, 0, At, B0); PG8_MMA(0, 1, At, B1); PG8_BAR; PG8_SCHED;
;             PG8_LDA(At, 0, 1); PG8_STAGE(PG8_SB(0, 0), b2, voffB); PG8_STAGE(PG8_SB(0, 1), b2 + hstepB, voffB); PG8_STAGE(PG8_SA(0, 0), a2, voffA);
;             PG8_WAIT_V(8); PG8_WAIT_L(0); PG8_BAR; PG8_MMA(1, 0, At, B0); PG8_MMA(1, 1, At, B1); PG8_BAR; PG8_SCHED;
.LBB0_766:
	ds_read_b128 v[150:153], v146
	ds_read_b128 v[154:157], v146 offset:1024
	ds_read_b128 v[158:161], v146 offset:2048
	ds_read_b128 v[162:165], v146 offset:3072
	ds_read_b128 v[166:169], v147
	ds_read_b128 v[170:173], v147 offset:1024
	ds_read_b128 v[174:177], v147 offset:2048
	ds_read_b128 v[178:181], v147 offset:3072
	s_add_u32 s42, s40, 0x100
	s_addc_u32 s43, s41, 0
	s_cmp_eq_u32 s67, 8
	s_cselect_b32 s47, s61, s43
	s_cselect_b32 s46, s62, s42
	s_cselect_b32 s45, s63, s66
	s_cselect_b32 s44, s64, s65
	v_lshl_add_u64 v[142:143], s[40:41], 0, v[134:135]
	s_add_i32 m0, s33, 0xc000
	ds_read_b128 v[182:185], v148
	ds_read_b128 v[186:189], v148 offset:1024
	ds_read_b128 v[190:193], v148 offset:2048
	ds_read_b128 v[194:197], v148 offset:3072
	ds_read_b128 v[198:201], v148 offset:4096
	ds_read_b128 v[202:205], v148 offset:5120
	ds_read_b128 v[208:211], v148 offset:6144
	ds_read_b128 v[212:215], v148 offset:7168
	global_load_lds_dwordx4 v[142:143], off
	v_lshl_add_u64 v[142:143], s[40:41], 0, v[136:137]
	s_add_i32 m0, s33, 0xe000
	s_nop 0
	global_load_lds_dwordx4 v[142:143], off
	s_waitcnt vmcnt(8)
	s_waitcnt lgkmcnt(0)
	s_barrier
	s_setprio 1
	s_waitcnt lgkmcnt(0)
	v_mfma_f32_16x16x32_bf16 v[124:127], v[150:153], v[182:185], v[124:127]
	v_mfma_f32_16x16x32_bf16 v[120:123], v[158:161], v[182:185], v[120:123]
	v_mfma_f32_16x16x32_bf16 v[108:111], v[150:153], v[190:193], v[108:111]
	v_mfma_f32_16x16x32_bf16 v[104:107], v[158:161], v[190:193], v[104:107]
	v_mfma_f32_16x16x32_bf16 v[92:95], v[150:153], v[198:201], v[92:95]
	v_mfma_f32_16x16x32_bf16 v[88:91], v[158:161], v[198:201], v[88:91]
	v_mfma_f32_16x16x32_bf16 v[76:79], v[150:153], v[208:211], v[76:79]
	v_mfma_f32_16x16x32_bf16 v[72:75], v[158:161], v[208:211], v[72:75]
	v_mfma_f32_16x16x32_bf16 v[124:127], v[154:157], v[186:189], v[124:127]
	v_mfma_f32_16x16x32_bf16 v[120:123], v[162:165], v[186:189], v[120:123]
	v_mfma_f32_16x16x32_bf16 v[108:111], v[154:157], v[194:197], v[108:111]
	v_mfma_f32_16x16x32_bf16 v[104:107], v[162:165], v[194:197], v[104:107]
	v_mfma_f32_16x16x32_bf16 v[92:95], v[154:157], v[202:205], v[92:95]
	v_mfma_f32_16x16x32_bf16 v[88:91], v[162:165], v[202:205], v[88:91]
	v_mfma_f32_16x16x32_bf16 v[76:79], v[154:157], v[212:215], v[76:79]
	v_mfma_f32_16x16x32_bf16 v[72:75], v[162:165], v[212:215], v[72:75]
	v_mfma_f32_16x16x32_bf16 v[116:119], v[166:169], v[182:185], v[116:119]
	v_mfma_f32_16x16x32_bf16 v[112:115], v[174:177], v[182:185], v[112:115]
	v_mfma_f32_16x16x32_bf16 v[100:103], v[166:169], v[190:193], v[100:103]
	v_mfma_f32_16x16x32_bf16 v[96:99], v[174:177], v[190:193], v[96:99]
	v_mfma_f32_16x16x32_bf16 v[84:87], v[166:169], v[198:201], v[84:87]
	v_mfma_f32_16x16x32_bf16 v[80:83], v[174:177], v[198:201], v[80:83]
	v_mfma_f32_16x16x32_bf16 v[68:71], v[166:169], v[208:211], v[68:71]
	v_mfma_f32_16x16x32_bf16 v[64:67], v[174:177], v[208:211], v[64:67]
	v_mfma_f32_16x16x32_bf16 v[116:119], v[170:173], v[186:189], v[116:119]
	v_mfma_f32_16x16x32_bf16 v[112:115], v[178:181], v[186:189], v[112:115]
	v_mfma_f32_16x16x32_bf16 v[100:103], v[170:173], v[194:197], v[100:103]
	v_mfma_f32_16x16x32_bf16 v[96:99], v[178:181], v[194:197], v[96:99]
	v_mfma_f32_16x16x32_bf16 v[84:87], v[170:173], v[202:205], v[84:87]
	v_mfma_f32_16x16x32_bf16 v[80:83], v[178:181], v[202:205], v[80:83]
	v_mfma_f32_16x16x32_bf16 v[68:71], v[170:173], v[212:215], v[68:71]
	v_mfma_f32_16x16x32_bf16 v[64:67], v[178:181], v[212:215], v[64:67]
	s_setprio 0
	s_barrier
	s_add_i32 s40, s57, s21
	v_lshl_add_u64 v[142:143], s[44:45], 0, v[130:131]
	s_mov_b32 m0, s40
	ds_read_b128 v[182:185], v148 offset:16384
	ds_read_b128 v[186:189], v148 offset:17408
	ds_read_b128 v[190:193], v148 offset:18432
	ds_read_b128 v[194:197], v148 offset:19456
	ds_read_b128 v[198:201], v148 offset:20480
	ds_read_b128 v[202:205], v148 offset:21504
	ds_read_b128 v[208:211], v148 offset:22528
	ds_read_b128 v[212:215], v148 offset:23552
	global_load_lds_dwordx4 v[142:143], off
	s_add_i32 m0, s40, 0x2000
	s_add_u32 s40, s44, 0x30000
	v_lshl_add_u64 v[216:217], s[44:45], 0, v[128:129]
	s_addc_u32 s41, s45, 0
	s_add_i32 s68, s58, s21
	global_load_lds_dwordx4 v[216:217], off
	v_lshl_add_u64 v[218:219], s[40:41], 0, v[130:131]
	s_mov_b32 m0, s68
	v_lshl_add_u64 v[220:221], s[46:47], 0, v[128:129]
	global_load_lds_dwordx4 v[218:219], off
	v_lshl_add_u64 v[218:219], s[40:41], 0, v[128:129]
	s_add_i32 m0, s68, 0x2000
	s_nop 0
	global_load_lds_dwordx4 v[218:219], off
	v_lshl_add_u64 v[218:219], s[46:47], 0, v[130:131]
	s_mov_b32 m0, s33
	s_nop 0
	global_load_lds_dwordx4 v[218:219], off
	s_mov_b32 m0, s50
	s_nop 0
	global_load_lds_dwordx4 v[220:221], off
	s_waitcnt vmcnt(8)
	s_waitcnt lgkmcnt(0)
	s_barrier
; #define PG8_STAGE(bufoff, gbase, voff) do { _Pragma("unroll") for (int _i = 0; _i < 2; ++_i) \
;         __builtin_amdgcn_global_load_lds((const unsigned*)((const char*)(gbase) + (voff)[_i]), (LAS unsigned*)(lds + (bufoff) + ldsw + _i * 8192), 16, 0, 0); } while (0)
; #define PG8_LDA(dst, b, h) do { _Pragma("unroll") for (int m = 0; m < 4; ++m) _Pragma("unroll") for (int k = 0; k < 2; ++k) dst[m][k] = *(const LAS bf16x8*)(lds + PG8_SA(b, h) + aoff + m * 2048 + k * 1024); } while (0)
; #define PG8_LDB(dst, b, h) do { _Pragma("unroll") for (int n = 0; n < 2; ++n) _Pragma("unroll") for (int k = 0; k < 2; ++k) dst[n][k] = *(const LAS bf16x8*)(lds + PG8_SB(b, h) + boff + n * 2048 + k * 1024); } while (0)
; #define PG8_WAIT_V(n) asm volatile("s_waitcnt vmcnt(" #n ")" ::: "memory")
; #define PG8_WAIT_L(n) asm volatile("s_waitcnt lgkmcnt(" #n ")" ::: "memory")
; #define PG8_BAR __builtin_amdgcn_s_barrier()
; #define PG8_SCHED __builtin_amdgcn_sched_barrier(0)
; template <class Epi, class Sched, bool SWAPD = false>
; __device__ __forceinline__ void gemm_phase(LAS unsigned char* lds, const Gemm g, const Sched& S, const Epi& E) {
;     ...
;             PG8_WAIT_V(8); PG8_WAIT_L(0); PG8_BAR; PG8_MMA(1, 0, At, B0); PG8_MMA(1, 1, At, B1); PG8_BAR; PG8_SCHED;
;             PG8_LDB(B0, 1, 0); PG8_LDB(B1, 1, 1); PG8_SCHED; PG8_LDA(At, 1, 0); PG8_STAGE(PG8_SA(0, 1), a2 + hstepA, voffA);
;             PG8_WAIT_V(8); PG8_WAIT_L(0); PG8_BAR; PG8_MMA(0, 0, At, B0); PG8_MMA(0, 1, At, B1); PG8_BAR; PG8_SCHED;
	s_setprio 1
	s_waitcnt lgkmcnt(0)
	v_mfma_f32_16x16x32_bf16 v[60:63], v[150:153], v[182:185], v[60:63]
	v_mfma_f32_16x16x32_bf16 v[56:59], v[158:161], v[182:185], v[56:59]
	v_mfma_f32_16x16x32_bf16 v[44:47], v[150:153], v[190:193], v[44:47]
	v_mfma_f32_16x16x32_bf16 v[40:43], v[158:161], v[190:193], v[40:43]
	v_mfma_f32_16x16x32_bf16 v[28:31], v[150:153], v[198:201], v[28:31]
	v_mfma_f32_16x16x32_bf16 v[24:27], v[158:161], v[198:201], v[24:27]
	v_mfma_f32_16x16x32_bf16 v[12:15], v[150:153], v[208:211], v[12:15]
	v_mfma_f32_16x16x32_bf16 v[8:11], v[158:161], v[208:211], v[8:11]
	v_mfma_f32_16x16x32_bf16 v[60:63], v[154:157], v[186:189], v[60:63]
	v_mfma_f32_16x16x32_bf16 v[56:59], v[162:165], v[186:189], v[56:59]
	v_mfma_f32_16x16x32_bf16 v[44:47], v[154:157], v[194:197], v[44:47]
	v_mfma_f32_16x16x32_bf16 v[40:43], v[162:165], v[194:197], v[40:43]
	v_mfma_f32_16x16x32_bf16 v[28:31], v[154:157], v[202:205], v[28:31]
	v_mfma_f32_16x16x32_bf16 v[24:27], v[162:165], v[202:205], v[24:27]
	v_mfma_f32_16x16x32_bf16 v[12:15], v[154:157], v[212:215], v[12:15]
	v_mfma_f32_16x16x32_bf16 v[8:11], v[162:165], v[212:215], v[8:11]
	v_mfma_f32_16x16x32_bf16 v[52:55], v[166:169], v[182:185], v[52:55]
	v_mfma_f32_16x16x32_bf16 v[48:51], v[174:177], v[182:185], v[48:51]
	v_mfma_f32_16x16x32_bf16 v[36:39], v[166:169], v[190:193], v[36:39]
	v_mfma_f32_16x16x32_bf16 v[32:35], v[174:177], v[190:193], v[32:35]
	v_mfma_f32_16x16x32_bf16 v[20:23], v[166:169], v[198:201], v[20:23]
	v_mfma_f32_16x16x32_bf16 v[16:19], v[174:177], v[198:201], v[16:19]
	v_mfma_f32_16x16x32_bf16 v[4:7], v[166:169], v[208:211], v[4:7]
	v_mfma_f32_16x16x32_bf16 v[0:3], v[174:177], v[208:211], v[0:3]
	v_mfma_f32_16x16x32_bf16 v[52:55], v[170:173], v[186:189], v[52:55]
	v_mfma_f32_16x16x32_bf16 v[48:51], v[178:181], v[186:189], v[48:51]
	v_mfma_f32_16x16x32_bf16 v[36:39], v[170:173], v[194:197], v[36:39]
	v_mfma_f32_16x16x32_bf16 v[32:35], v[178:181], v[194:197], v[32:35]
	v_mfma_f32_16x16x32_bf16 v[20:23], v[170:173], v[202:205], v[20:23]
	v_mfma_f32_16x16x32_bf16 v[16:19], v[178:181], v[202:205], v[16:19]
	v_mfma_f32_16x16x32_bf16 v[4:7], v[170:173], v[212:215], v[4:7]
	v_mfma_f32_16x16x32_bf16 v[0:3], v[178:181], v[212:215], v[0:3]
	s_setprio 0
	s_barrier
	s_add_i32 s68, 0, 0x18000
	v_add_u32_e32 v149, s68, v144
	s_add_i32 s69, 0, 0x1c000
	ds_read_b128 v[150:153], v149
	ds_read_b128 v[154:157], v149 offset:1024
	ds_read_b128 v[158:161], v149 offset:2048
	ds_read_b128 v[162:165], v149 offset:3072
	v_add_u32_e32 v149, s69, v144
	ds_read_b128 v[166:169], v149
	ds_read_b128 v[170:173], v149 offset:1024
	ds_read_b128 v[174:177], v149 offset:2048
	ds_read_b128 v[178:181], v149 offset:3072
	s_add_u32 s40, s46, 0x30000
	s_addc_u32 s41, s47, 0
	s_mov_b32 m0, s51
	v_lshl_add_u64 v[222:223], s[40:41], 0, v[130:131]
	ds_read_b128 v[182:185], v148 offset:32768
	ds_read_b128 v[186:189], v148 offset:33792
	ds_read_b128 v[190:193], v148 offset:34816
	ds_read_b128 v[194:197], v148 offset:35840
	ds_read_b128 v[198:201], v148 offset:36864
	ds_read_b128 v[202:205], v148 offset:37888
	ds_read_b128 v[208:211], v148 offset:38912
	ds_read_b128 v[212:215], v148 offset:39936
	global_load_lds_dwordx4 v[222:223], off
	v_lshl_add_u64 v[222:223], s[40:41], 0, v[128:129]
	s_mov_b32 m0, s52
	s_nop 0
	global_load_lds_dwordx4 v[222:223], off
	s_waitcnt vmcnt(8)
	s_waitcnt lgkmcnt(0)
	s_barrier
	s_setprio 1
	s_waitcnt lgkmcnt(0)
	v_mfma_f32_16x16x32_bf16 v[124:127], v[150:153], v[182:185], v[124:127]
	v_mfma_f32_16x16x32_bf16 v[120:123], v[158:161], v[182:185], v[120:123]
	v_mfma_f32_16x16x32_bf16 v[108:111], v[150:153], v[190:193], v[108:111]
	v_mfma_f32_16x16x32_bf16 v[104:107], v[158:161], v[190:193], v[104:107]
	v_mfma_f32_16x16x32_bf16 v[92:95], v[150:153], v[198:201], v[92:95]
	v_mfma_f32_16x16x32_bf16 v[88:91], v[158:161], v[198:201], v[88:91]
	v_mfma_f32_16x16x32_bf16 v[76:79], v[150:153], v[208:211], v[76:79]
	v_mfma_f32_16x16x32_bf16 v[72:75], v[158:161], v[208:211], v[72:75]
	v_mfma_f32_16x16x32_bf16 v[124:127], v[154:157], v[186:189], v[124:127]
	v_mfma_f32_16x16x32_bf16 v[120:123], v[162:165], v[186:189], v[120:123]
	v_mfma_f32_16x16x32_bf16 v[108:111], v[154:157], v[194:197], v[108:111]
	v_mfma_f32_16x16x32_bf16 v[104:107], v[162:165], v[194:197], v[104:107]
	v_mfma_f32_16x16x32_bf16 v[92:95], v[154:157], v[202:205], v[92:95]
	v_mfma_f32_16x16x32_bf16 v[88:91], v[162:165], v[202:205], v[88:91]
	v_mfma_f32_16x16x32_bf16 v[76:79], v[154:157], v[212:215], v[76:79]
	v_mfma_f32_16x16x32_bf16 v[72:75], v[162:165], v[212:215], v[72:75]
	v_mfma_f32_16x16x32_bf16 v[116:119], v[166:169], v[182:185], v[116:119]
	v_mfma_f32_16x16x32_bf16 v[112:115], v[174:177], v[182:185], v[112:115]
	v_mfma_f32_16x16x32_bf16 v[100:103], v[166:169], v[190:193], v[100:103]
	v_mfma_f32_16x16x32_bf16 v[96:99], v[174:177], v[190:193], v[96:99]
	v_mfma_f32_16x16x32_bf16 v[84:87], v[166:169], v[198:201], v[84:87]
	v_mfma_f32_16x16x32_bf16 v[80:83], v[174:177], v[198:201], v[80:83]
	v_mfma_f32_16x16x32_bf16 v[68:71], v[166:169], v[208:211], v[68:71]
	v_mfma_f32_16x16x32_bf16 v[64:67], v[174:177], v[208:211], v[64:67]
	v_mfma_f32_16x16x32_bf16 v[116:119], v[170:173], v[186:189], v[116:119]
	v_mfma_f32_16x16x32_bf16 v[112:115], v[178:181], v[186:189], v[112:115]
	v_mfma_f32_16x16x32_bf16 v[100:103], v[170:173], v[194:197], v[100:103]
	v_mfma_f32_16x16x32_bf16 v[96:99], v[178:181], v[194:197], v[96:99]
	v_mfma_f32_16x16x32_bf16 v[84:87], v[170:173], v[202:205], v[84:87]
	v_mfma_f32_16x16x32_bf16 v[80:83], v[178:181], v[202:205], v[80:83]
	v_mfma_f32_16x16x32_bf16 v[68:71], v[170:173], v[212:215], v[68:71]
	v_mfma_f32_16x16x32_bf16 v[64:67], v[178:181], v[212:215], v[64:67]
	s_setprio 0
	s_barrier
; #define PG8_STAGE(bufoff, gbase, voff) do { _Pragma("unroll") for (int _i = 0; _i < 2; ++_i) \
;         __builtin_amdgcn_global_load_lds((const unsigned*)((const char*)(gbase) + (voff)[_i]), (LAS unsigned*)(lds + (bufoff) + ldsw + _i * 8192), 16, 0, 0); } while (0)
; #define PG8_LDA(dst, b, h) do { _Pragma("unroll") for (int m = 0; m < 4; ++m) _Pragma("unroll") for (int k = 0; k < 2; ++k) dst[m][k] = *(const LAS bf16x8*)(lds + PG8_SA(b, h) + aoff + m * 2048 + k * 1024); } while (0)
; #define PG8_WAIT_V(n) asm volatile("s_waitcnt vmcnt(" #n ")" ::: "memory")
; #define PG8_WAIT_L(n) asm volatile("s_waitcnt lgkmcnt(" #n ")" ::: "memory")
; #define PG8_BAR __builtin_amdgcn_s_barrier()
; #define PG8_SCHED __builtin_amdgcn_sched_barrier(0)
; template <class Epi, class Sched, bool SWAPD = false>
; __device__ __forceinline__ void gemm_phase(LAS unsigned char* lds, const Gemm g, const Sched& S, const Epi& E) {
;     ...
;             PG8_LDA(At, 1, 1); PG8_STAGE(PG8_SB(1, 0), b3, voffB); PG8_STAGE(PG8_SB(1, 1), b3 + hstepB, voffB); PG8_STAGE(PG8_SA(1, 0), a3, voffA);
;             PG8_WAIT_V(8); PG8_WAIT_L(0); PG8_BAR; PG8_MMA(1, 0, At, B0); PG8_MMA(1, 1, At, B1); PG8_BAR; PG8_SCHED;
;         }
	s_add_i32 s40, s68, s21
	v_lshl_add_u64 v[142:143], v[142:143], 0, s[12:13]
	s_mov_b32 m0, s40
	ds_read_b128 v[182:185], v148 offset:49152
	ds_read_b128 v[186:189], v148 offset:50176
	ds_read_b128 v[190:193], v148 offset:51200
	ds_read_b128 v[194:197], v148 offset:52224
	ds_read_b128 v[198:201], v148 offset:53248
	ds_read_b128 v[202:205], v148 offset:54272
	ds_read_b128 v[208:211], v148 offset:55296
	ds_read_b128 v[212:215], v148 offset:56320
	global_load_lds_dwordx4 v[142:143], off
	s_add_i32 m0, s40, 0x2000
	s_add_u32 s40, s44, 0x30080
	v_lshl_add_u64 v[142:143], v[216:217], 0, s[12:13]
	s_addc_u32 s41, s45, 0
	s_add_i32 s44, s69, s21
	global_load_lds_dwordx4 v[142:143], off
	v_lshl_add_u64 v[142:143], s[40:41], 0, v[130:131]
	s_mov_b32 m0, s44
	s_nop 0
	global_load_lds_dwordx4 v[142:143], off
	v_lshl_add_u64 v[142:143], s[40:41], 0, v[128:129]
	s_add_i32 m0, s44, 0x2000
	s_nop 0
	global_load_lds_dwordx4 v[142:143], off
	v_lshl_add_u64 v[142:143], v[218:219], 0, s[12:13]
	s_mov_b32 m0, s54
	s_nop 0
	global_load_lds_dwordx4 v[142:143], off
	v_lshl_add_u64 v[142:143], v[220:221], 0, s[12:13]
	s_mov_b32 m0, s55
	s_nop 0
	global_load_lds_dwordx4 v[142:143], off
	s_waitcnt vmcnt(8)
	s_waitcnt lgkmcnt(0)
	s_barrier
	s_setprio 1
	s_waitcnt lgkmcnt(0)
	v_mfma_f32_16x16x32_bf16 v[60:63], v[150:153], v[182:185], v[60:63]
	v_mfma_f32_16x16x32_bf16 v[56:59], v[158:161], v[182:185], v[56:59]
	v_mfma_f32_16x16x32_bf16 v[44:47], v[150:153], v[190:193], v[44:47]
	v_mfma_f32_16x16x32_bf16 v[40:43], v[158:161], v[190:193], v[40:43]
	v_mfma_f32_16x16x32_bf16 v[28:31], v[150:153], v[198:201], v[28:31]
	v_mfma_f32_16x16x32_bf16 v[24:27], v[158:161], v[198:201], v[24:27]
	v_mfma_f32_16x16x32_bf16 v[12:15], v[150:153], v[208:211], v[12:15]
	v_mfma_f32_16x16x32_bf16 v[8:11], v[158:161], v[208:211], v[8:11]
	v_mfma_f32_16x16x32_bf16 v[60:63], v[154:157], v[186:189], v[60:63]
	v_mfma_f32_16x16x32_bf16 v[56:59], v[162:165], v[186:189], v[56:59]
	v_mfma_f32_16x16x32_bf16 v[44:47], v[154:157], v[194:197], v[44:47]
	v_mfma_f32_16x16x32_bf16 v[40:43], v[162:165], v[194:197], v[40:43]
	v_mfma_f32_16x16x32_bf16 v[28:31], v[154:157], v[202:205], v[28:31]
	v_mfma_f32_16x16x32_bf16 v[24:27], v[162:165], v[202:205], v[24:27]
	v_mfma_f32_16x16x32_bf16 v[12:15], v[154:157], v[212:215], v[12:15]
	v_mfma_f32_16x16x32_bf16 v[8:11], v[162:165], v[212:215], v[8:11]
	v_mfma_f32_16x16x32_bf16 v[52:55], v[166:169], v[182:185], v[52:55]
	v_mfma_f32_16x16x32_bf16 v[48:51], v[174:177], v[182:185], v[48:51]
	v_mfma_f32_16x16x32_bf16 v[36:39], v[166:169], v[190:193], v[36:39]
	v_mfma_f32_16x16x32_bf16 v[32:35], v[174:177], v[190:193], v[32:35]
	v_mfma_f32_16x16x32_bf16 v[20:23], v[166:169], v[198:201], v[20:23]
	v_mfma_f32_16x16x32_bf16 v[16:19], v[174:177], v[198:201], v[16:19]
	v_mfma_f32_16x16x32_bf16 v[4:7], v[166:169], v[208:211], v[4:7]
	v_mfma_f32_16x16x32_bf16 v[0:3], v[174:177], v[208:211], v[0:3]
	v_mfma_f32_16x16x32_bf16 v[52:55], v[170:173], v[186:189], v[52:55]
	v_mfma_f32_16x16x32_bf16 v[48:51], v[178:181], v[186:189], v[48:51]
	v_mfma_f32_16x16x32_bf16 v[36:39], v[170:173], v[194:197], v[36:39]
	v_mfma_f32_16x16x32_bf16 v[32:35], v[178:181], v[194:197], v[32:35]
	v_mfma_f32_16x16x32_bf16 v[20:23], v[170:173], v[202:205], v[20:23]
	v_mfma_f32_16x16x32_bf16 v[16:19], v[178:181], v[202:205], v[16:19]
	v_mfma_f32_16x16x32_bf16 v[4:7], v[170:173], v[212:215], v[4:7]
	v_mfma_f32_16x16x32_bf16 v[0:3], v[178:181], v[212:215], v[0:3]
	s_setprio 0
	s_barrier
	s_add_i32 s67, s67, 2
	s_add_u32 s65, s65, 0x100
	s_addc_u32 s66, s66, 0
	s_cmp_gt_u32 s67, 9
	s_mov_b64 s[40:41], s[42:43]
	s_cbranch_scc0 .LBB0_766
	s_and_b64 vcc, exec, s[24:25]
	s_cbranch_vccz .LBB0_769
	s_barrier

; #define PG8_STAGE(bufoff, gbase, voff) do { _Pragma("unroll") for (int _i = 0; _i < 2; ++_i) \
;         __builtin_amdgcn_global_load_lds((const unsigned*)((const char*)(gbase) + (voff)[_i]), (LAS unsigned*)(lds + (bufoff) + ldsw + _i * 8192), 16, 0, 0); } while (0)
; #define PG8_LDA(dst, b, h) do { _Pragma("unroll") for (int m = 0; m < 4; ++m) _Pragma("unroll") for (int k = 0; k < 2; ++k) dst[m][k] = *(const LAS bf16x8*)(lds + PG8_SA(b, h) + aoff + m * 2048 + k * 1024); } while (0)
; #define PG8_LDB(dst, b, h) do { _Pragma("unroll") for (int n = 0; n < 2; ++n) _Pragma("unroll") for (int k = 0; k < 2; ++k) dst[n][k] = *(const LAS bf16x8*)(lds + PG8_SB(b, h) + boff + n * 2048 + k * 1024); } while (0)
; #define PG8_WAIT_V(n) asm volatile("s_waitcnt vmcnt(" #n ")" ::: "memory")
; #define PG8_WAIT_L(n) asm volatile("s_waitcnt lgkmcnt(" #n ")" ::: "memory")
; #define PG8_BAR __builtin_amdgcn_s_barrier()
; #define PG8_SCHED __builtin_amdgcn_sched_barrier(0)
; template <class Epi, class Sched, bool SWAPD = false>
; __device__ __forceinline__ void gemm_phase(LAS unsigned char* lds, const Gemm g, const Sched& S, const Epi& E) {
;     ...
;             const bool last = (t == nt - 2);
;             const char* a1 = cA + (size_t)(t + 1) * kstepA;
;             const char* a2 = last ? nA : cA + (size_t)(t + 2) * kstepA; const char* b2 = last ? nB : cB + (size_t)(t + 2) * kstep;
;             const char* a3 = a2 + kstepA; const char* b3 = b2 + kstep;
;             PG8_LDB(B0, 0, 0); PG8_LDB(B1, 0, 1); PG8_SCHED; PG8_LDA(At, 0, 0); PG8_STAGE(PG8_SA(1, 1), a1 + hstepA, voffA);
;             PG8_WAIT_V(8); PG8_WAIT_L(0); PG8_BAR; PG8_MMA(0, 0, At, B0); PG8_MMA(0, 1, At, B1); PG8_BAR; PG8_SCHED;
;             PG8_LDA(At, 0, 1); PG8_STAGE(PG8_SB(0, 0), b2, voffB); PG8_STAGE(PG8_SB(0, 1), b2 + hstepB, voffB); PG8_STAGE(PG8_SA(0, 0), a2, voffA);
.LBB0_842:
	ds_read_b128 v[146:149], v153
	ds_read_b128 v[156:159], v153 offset:1024
	ds_read_b128 v[160:163], v153 offset:2048
	ds_read_b128 v[164:167], v153 offset:3072
	ds_read_b128 v[168:171], v154
	ds_read_b128 v[172:175], v154 offset:1024
	ds_read_b128 v[176:179], v154 offset:2048
	ds_read_b128 v[180:183], v154 offset:3072
	s_add_u32 s44, s42, 0x800000
	s_addc_u32 s45, s43, 0
	s_cmp_eq_u32 s62, 4
	s_cselect_b32 s52, s25, s44
	s_cselect_b32 s53, s23, s45
	s_cselect_b32 s50, s59, s60
	s_cselect_b32 s51, s35, s61
	s_add_u32 s46, s52, 0x400000
	s_addc_u32 s47, s53, 0
	v_lshl_add_u64 v[204:205], s[42:43], 0, v[138:139]
	s_add_i32 m0, s30, 0xc000
	ds_read_b128 v[184:187], v155
	ds_read_b128 v[188:191], v155 offset:1024
	ds_read_b128 v[192:195], v155 offset:2048
	ds_read_b128 v[196:199], v155 offset:3072
	ds_read_b128 v[200:203], v155 offset:4096
	ds_read_b128 v[208:211], v155 offset:5120
	ds_read_b128 v[212:215], v155 offset:6144
	ds_read_b128 v[216:219], v155 offset:7168
	global_load_lds_dwordx4 v[204:205], off
	v_lshl_add_u64 v[204:205], s[42:43], 0, v[140:141]
	s_add_i32 m0, s30, 0xe000
	s_nop 0
	global_load_lds_dwordx4 v[204:205], off
	s_waitcnt vmcnt(8)
	s_waitcnt lgkmcnt(0)
	s_barrier
	s_setprio 1
	s_waitcnt lgkmcnt(0)
	v_mfma_f32_16x16x32_bf16 v[124:127], v[146:149], v[184:187], v[124:127]
	v_mfma_f32_16x16x32_bf16 v[120:123], v[160:163], v[184:187], v[120:123]
	v_mfma_f32_16x16x32_bf16 v[108:111], v[146:149], v[192:195], v[108:111]
	v_mfma_f32_16x16x32_bf16 v[104:107], v[160:163], v[192:195], v[104:107]
	v_mfma_f32_16x16x32_bf16 v[92:95], v[146:149], v[200:203], v[92:95]
	v_mfma_f32_16x16x32_bf16 v[88:91], v[160:163], v[200:203], v[88:91]
	v_mfma_f32_16x16x32_bf16 v[76:79], v[146:149], v[212:215], v[76:79]
	v_mfma_f32_16x16x32_bf16 v[72:75], v[160:163], v[212:215], v[72:75]
	v_mfma_f32_16x16x32_bf16 v[124:127], v[156:159], v[188:191], v[124:127]
	v_mfma_f32_16x16x32_bf16 v[120:123], v[164:167], v[188:191], v[120:123]
	v_mfma_f32_16x16x32_bf16 v[108:111], v[156:159], v[196:199], v[108:111]
	v_mfma_f32_16x16x32_bf16 v[104:107], v[164:167], v[196:199], v[104:107]
	v_mfma_f32_16x16x32_bf16 v[92:95], v[156:159], v[208:211], v[92:95]
	v_mfma_f32_16x16x32_bf16 v[88:91], v[164:167], v[208:211], v[88:91]
	v_mfma_f32_16x16x32_bf16 v[76:79], v[156:159], v[216:219], v[76:79]
	v_mfma_f32_16x16x32_bf16 v[72:75], v[164:167], v[216:219], v[72:75]
	v_mfma_f32_16x16x32_bf16 v[116:119], v[168:171], v[184:187], v[116:119]
	v_mfma_f32_16x16x32_bf16 v[112:115], v[176:179], v[184:187], v[112:115]
	v_mfma_f32_16x16x32_bf16 v[100:103], v[168:171], v[192:195], v[100:103]
	v_mfma_f32_16x16x32_bf16 v[96:99], v[176:179], v[192:195], v[96:99]
	v_mfma_f32_16x16x32_bf16 v[84:87], v[168:171], v[200:203], v[84:87]
	v_mfma_f32_16x16x32_bf16 v[80:83], v[176:179], v[200:203], v[80:83]
	v_mfma_f32_16x16x32_bf16 v[68:71], v[168:171], v[212:215], v[68:71]
	v_mfma_f32_16x16x32_bf16 v[64:67], v[176:179], v[212:215], v[64:67]
	v_mfma_f32_16x16x32_bf16 v[116:119], v[172:175], v[188:191], v[116:119]
	v_mfma_f32_16x16x32_bf16 v[112:115], v[180:183], v[188:191], v[112:115]
	v_mfma_f32_16x16x32_bf16 v[100:103], v[172:175], v[196:199], v[100:103]
	v_mfma_f32_16x16x32_bf16 v[96:99], v[180:183], v[196:199], v[96:99]
	v_mfma_f32_16x16x32_bf16 v[84:87], v[172:175], v[208:211], v[84:87]
	v_mfma_f32_16x16x32_bf16 v[80:83], v[180:183], v[208:211], v[80:83]
	v_mfma_f32_16x16x32_bf16 v[68:71], v[172:175], v[216:219], v[68:71]
	v_mfma_f32_16x16x32_bf16 v[64:67], v[180:183], v[216:219], v[64:67]
	s_setprio 0
	s_barrier
	s_add_i32 s42, s57, s21
	v_lshl_add_u64 v[204:205], s[50:51], 0, v[130:131]
	s_mov_b32 m0, s42
	ds_read_b128 v[184:187], v155 offset:16384
	ds_read_b128 v[188:191], v155 offset:17408
	ds_read_b128 v[192:195], v155 offset:18432
	ds_read_b128 v[196:199], v155 offset:19456
	ds_read_b128 v[200:203], v155 offset:20480
	ds_read_b128 v[208:211], v155 offset:21504
	ds_read_b128 v[212:215], v155 offset:22528
	ds_read_b128 v[216:219], v155 offset:23552
	global_load_lds_dwordx4 v[204:205], off
	s_add_i32 m0, s42, 0x2000
	s_add_u32 s42, s50, 0x20000
	v_lshl_add_u64 v[220:221], s[50:51], 0, v[134:135]
	s_addc_u32 s43, s51, 0
	s_add_i32 s63, s58, s21
	global_load_lds_dwordx4 v[220:221], off
	v_lshl_add_u64 v[222:223], s[42:43], 0, v[130:131]
	s_mov_b32 m0, s63
	s_nop 0
	global_load_lds_dwordx4 v[222:223], off
	v_lshl_add_u64 v[222:223], s[42:43], 0, v[134:135]
	s_add_i32 m0, s63, 0x2000
	s_nop 0
	global_load_lds_dwordx4 v[222:223], off
	v_lshl_add_u64 v[222:223], s[52:53], 0, v[128:129]
	s_mov_b32 m0, s30
	s_nop 0
	global_load_lds_dwordx4 v[222:223], off
	v_lshl_add_u64 v[222:223], s[52:53], 0, v[132:133]
	s_mov_b32 m0, s31
	s_nop 0
	global_load_lds_dwordx4 v[222:223], off
	s_waitcnt vmcnt(8)
	s_waitcnt lgkmcnt(0)
	s_barrier
; #define PG8_STAGE(bufoff, gbase, voff) do { _Pragma("unroll") for (int _i = 0; _i < 2; ++_i) \
;         __builtin_amdgcn_global_load_lds((const unsigned*)((const char*)(gbase) + (voff)[_i]), (LAS unsigned*)(lds + (bufoff) + ldsw + _i * 8192), 16, 0, 0); } while (0)
; #define PG8_LDA(dst, b, h) do { _Pragma("unroll") for (int m = 0; m < 4; ++m) _Pragma("unroll") for (int k = 0; k < 2; ++k) dst[m][k] = *(const LAS bf16x8*)(lds + PG8_SA(b, h) + aoff + m * 2048 + k * 1024); } while (0)
; #define PG8_LDB(dst, b, h) do { _Pragma("unroll") for (int n = 0; n < 2; ++n) _Pragma("unroll") for (int k = 0; k < 2; ++k) dst[n][k] = *(const LAS bf16x8*)(lds + PG8_SB(b, h) + boff + n * 2048 + k * 1024); } while (0)
; #define PG8_WAIT_V(n) asm volatile("s_waitcnt vmcnt(" #n ")" ::: "memory")
; #define PG8_WAIT_L(n) asm volatile("s_waitcnt lgkmcnt(" #n ")" ::: "memory")
; #define PG8_BAR __builtin_amdgcn_s_barrier()
; #define PG8_SCHED __builtin_amdgcn_sched_barrier(0)
; template <class Epi, class Sched, bool SWAPD = false>
; __device__ __forceinline__ void gemm_phase(LAS unsigned char* lds, const Gemm g, const Sched& S, const Epi& E) {
;     ...
;             PG8_WAIT_V(8); PG8_WAIT_L(0); PG8_BAR; PG8_MMA(1, 0, At, B0); PG8_MMA(1, 1, At, B1); PG8_BAR; PG8_SCHED;
;             PG8_LDB(B0, 1, 0); PG8_LDB(B1, 1, 1); PG8_SCHED; PG8_LDA(At, 1, 0); PG8_STAGE(PG8_SA(0, 1), a2 + hstepA, voffA);
;             PG8_WAIT_V(8); PG8_WAIT_L(0); PG8_BAR; PG8_MMA(0, 0, At, B0); PG8_MMA(0, 1, At, B1); PG8_BAR; PG8_SCHED;
	s_setprio 1
	s_waitcnt lgkmcnt(0)
	v_mfma_f32_16x16x32_bf16 v[60:63], v[146:149], v[184:187], v[60:63]
	v_mfma_f32_16x16x32_bf16 v[56:59], v[160:163], v[184:187], v[56:59]
	v_mfma_f32_16x16x32_bf16 v[44:47], v[146:149], v[192:195], v[44:47]
	v_mfma_f32_16x16x32_bf16 v[40:43], v[160:163], v[192:195], v[40:43]
	v_mfma_f32_16x16x32_bf16 v[28:31], v[146:149], v[200:203], v[28:31]
	v_mfma_f32_16x16x32_bf16 v[24:27], v[160:163], v[200:203], v[24:27]
	v_mfma_f32_16x16x32_bf16 v[12:15], v[146:149], v[212:215], v[12:15]
	v_mfma_f32_16x16x32_bf16 v[8:11], v[160:163], v[212:215], v[8:11]
	v_mfma_f32_16x16x32_bf16 v[60:63], v[156:159], v[188:191], v[60:63]
	v_mfma_f32_16x16x32_bf16 v[56:59], v[164:167], v[188:191], v[56:59]
	v_mfma_f32_16x16x32_bf16 v[44:47], v[156:159], v[196:199], v[44:47]
	v_mfma_f32_16x16x32_bf16 v[40:43], v[164:167], v[196:199], v[40:43]
	v_mfma_f32_16x16x32_bf16 v[28:31], v[156:159], v[208:211], v[28:31]
	v_mfma_f32_16x16x32_bf16 v[24:27], v[164:167], v[208:211], v[24:27]
	v_mfma_f32_16x16x32_bf16 v[12:15], v[156:159], v[216:219], v[12:15]
	v_mfma_f32_16x16x32_bf16 v[8:11], v[164:167], v[216:219], v[8:11]
	v_mfma_f32_16x16x32_bf16 v[52:55], v[168:171], v[184:187], v[52:55]
	v_mfma_f32_16x16x32_bf16 v[48:51], v[176:179], v[184:187], v[48:51]
	v_mfma_f32_16x16x32_bf16 v[36:39], v[168:171], v[192:195], v[36:39]
	v_mfma_f32_16x16x32_bf16 v[32:35], v[176:179], v[192:195], v[32:35]
	v_mfma_f32_16x16x32_bf16 v[20:23], v[168:171], v[200:203], v[20:23]
	v_mfma_f32_16x16x32_bf16 v[16:19], v[176:179], v[200:203], v[16:19]
	v_mfma_f32_16x16x32_bf16 v[4:7], v[168:171], v[212:215], v[4:7]
	v_mfma_f32_16x16x32_bf16 v[0:3], v[176:179], v[212:215], v[0:3]
	v_mfma_f32_16x16x32_bf16 v[52:55], v[172:175], v[188:191], v[52:55]
	v_mfma_f32_16x16x32_bf16 v[48:51], v[180:183], v[188:191], v[48:51]
	v_mfma_f32_16x16x32_bf16 v[36:39], v[172:175], v[196:199], v[36:39]
	v_mfma_f32_16x16x32_bf16 v[32:35], v[180:183], v[196:199], v[32:35]
	v_mfma_f32_16x16x32_bf16 v[20:23], v[172:175], v[208:211], v[20:23]
	v_mfma_f32_16x16x32_bf16 v[16:19], v[180:183], v[208:211], v[16:19]
	v_mfma_f32_16x16x32_bf16 v[4:7], v[172:175], v[216:219], v[4:7]
	v_mfma_f32_16x16x32_bf16 v[0:3], v[180:183], v[216:219], v[0:3]
	s_setprio 0
	s_barrier
	s_add_i32 s63, 0, 0x18000
	s_add_i32 s64, 0, 0x1c000
	v_add_u32_e32 v164, s63, v151
	v_add_u32_e32 v180, s64, v151
	ds_read_b128 v[146:149], v164
	ds_read_b128 v[156:159], v164 offset:1024
	ds_read_b128 v[160:163], v164 offset:2048
	ds_read_b128 v[164:167], v164 offset:3072
	ds_read_b128 v[168:171], v180
	ds_read_b128 v[172:175], v180 offset:1024
	ds_read_b128 v[176:179], v180 offset:2048
	ds_read_b128 v[180:183], v180 offset:3072
	s_add_u32 s42, s52, 0x1000
	s_addc_u32 s43, s53, 0
	s_mov_b32 m0, s33
	v_lshl_add_u64 v[222:223], s[42:43], 0, v[128:129]
	ds_read_b128 v[184:187], v155 offset:32768
	ds_read_b128 v[188:191], v155 offset:33792
	ds_read_b128 v[192:195], v155 offset:34816
	ds_read_b128 v[196:199], v155 offset:35840
	ds_read_b128 v[200:203], v155 offset:36864
	ds_read_b128 v[208:211], v155 offset:37888
	ds_read_b128 v[212:215], v155 offset:38912
	ds_read_b128 v[216:219], v155 offset:39936
	global_load_lds_dwordx4 v[222:223], off
	v_lshl_add_u64 v[222:223], s[42:43], 0, v[132:133]
	s_mov_b32 m0, s41
	s_nop 0
	global_load_lds_dwordx4 v[222:223], off
	s_waitcnt vmcnt(8)
	s_waitcnt lgkmcnt(0)
	s_barrier
	s_setprio 1
	s_waitcnt lgkmcnt(0)
	v_mfma_f32_16x16x32_bf16 v[124:127], v[146:149], v[184:187], v[124:127]
	v_mfma_f32_16x16x32_bf16 v[120:123], v[160:163], v[184:187], v[120:123]
	v_mfma_f32_16x16x32_bf16 v[108:111], v[146:149], v[192:195], v[108:111]
	v_mfma_f32_16x16x32_bf16 v[104:107], v[160:163], v[192:195], v[104:107]
	v_mfma_f32_16x16x32_bf16 v[92:95], v[146:149], v[200:203], v[92:95]
	v_mfma_f32_16x16x32_bf16 v[88:91], v[160:163], v[200:203], v[88:91]
	v_mfma_f32_16x16x32_bf16 v[76:79], v[146:149], v[212:215], v[76:79]
	v_mfma_f32_16x16x32_bf16 v[72:75], v[160:163], v[212:215], v[72:75]
	v_mfma_f32_16x16x32_bf16 v[124:127], v[156:159], v[188:191], v[124:127]
	v_mfma_f32_16x16x32_bf16 v[120:123], v[164:167], v[188:191], v[120:123]
	v_mfma_f32_16x16x32_bf16 v[108:111], v[156:159], v[196:199], v[108:111]
	v_mfma_f32_16x16x32_bf16 v[104:107], v[164:167], v[196:199], v[104:107]
	v_mfma_f32_16x16x32_bf16 v[92:95], v[156:159], v[208:211], v[92:95]
	v_mfma_f32_16x16x32_bf16 v[88:91], v[164:167], v[208:211], v[88:91]
	v_mfma_f32_16x16x32_bf16 v[76:79], v[156:159], v[216:219], v[76:79]
	v_mfma_f32_16x16x32_bf16 v[72:75], v[164:167], v[216:219], v[72:75]
	v_mfma_f32_16x16x32_bf16 v[116:119], v[168:171], v[184:187], v[116:119]
	v_mfma_f32_16x16x32_bf16 v[112:115], v[176:179], v[184:187], v[112:115]
	v_mfma_f32_16x16x32_bf16 v[100:103], v[168:171], v[192:195], v[100:103]
	v_mfma_f32_16x16x32_bf16 v[96:99], v[176:179], v[192:195], v[96:99]
	v_mfma_f32_16x16x32_bf16 v[84:87], v[168:171], v[200:203], v[84:87]
	v_mfma_f32_16x16x32_bf16 v[80:83], v[176:179], v[200:203], v[80:83]
	v_mfma_f32_16x16x32_bf16 v[68:71], v[168:171], v[212:215], v[68:71]
	v_mfma_f32_16x16x32_bf16 v[64:67], v[176:179], v[212:215], v[64:67]
	v_mfma_f32_16x16x32_bf16 v[116:119], v[172:175], v[188:191], v[116:119]
	v_mfma_f32_16x16x32_bf16 v[112:115], v[180:183], v[188:191], v[112:115]
	v_mfma_f32_16x16x32_bf16 v[100:103], v[172:175], v[196:199], v[100:103]
	v_mfma_f32_16x16x32_bf16 v[96:99], v[180:183], v[196:199], v[96:99]
	v_mfma_f32_16x16x32_bf16 v[84:87], v[172:175], v[208:211], v[84:87]
	v_mfma_f32_16x16x32_bf16 v[80:83], v[180:183], v[208:211], v[80:83]
	v_mfma_f32_16x16x32_bf16 v[68:71], v[172:175], v[216:219], v[68:71]
	v_mfma_f32_16x16x32_bf16 v[64:67], v[180:183], v[216:219], v[64:67]
	s_setprio 0
	s_barrier
; #define PG8_STAGE(bufoff, gbase, voff) do { _Pragma("unroll") for (int _i = 0; _i < 2; ++_i) \
;         __builtin_amdgcn_global_load_lds((const unsigned*)((const char*)(gbase) + (voff)[_i]), (LAS unsigned*)(lds + (bufoff) + ldsw + _i * 8192), 16, 0, 0); } while (0)
; #define PG8_LDA(dst, b, h) do { _Pragma("unroll") for (int m = 0; m < 4; ++m) _Pragma("unroll") for (int k = 0; k < 2; ++k) dst[m][k] = *(const LAS bf16x8*)(lds + PG8_SA(b, h) + aoff + m * 2048 + k * 1024); } while (0)
; #define PG8_WAIT_V(n) asm volatile("s_waitcnt vmcnt(" #n ")" ::: "memory")
; #define PG8_WAIT_L(n) asm volatile("s_waitcnt lgkmcnt(" #n ")" ::: "memory")
; #define PG8_BAR __builtin_amdgcn_s_barrier()
; #define PG8_SCHED __builtin_amdgcn_sched_barrier(0)
; template <class Epi, class Sched, bool SWAPD = false>
; __device__ __forceinline__ void gemm_phase(LAS unsigned char* lds, const Gemm g, const Sched& S, const Epi& E) {
;     ...
;             PG8_LDA(At, 1, 1); PG8_STAGE(PG8_SB(1, 0), b3, voffB); PG8_STAGE(PG8_SB(1, 1), b3 + hstepB, voffB); PG8_STAGE(PG8_SA(1, 0), a3, voffA);
;             PG8_WAIT_V(8); PG8_WAIT_L(0); PG8_BAR; PG8_MMA(1, 0, At, B0); PG8_MMA(1, 1, At, B1); PG8_BAR; PG8_SCHED;
;         }
	s_add_i32 s42, s63, s21
	v_lshl_add_u64 v[204:205], v[204:205], 0, s[10:11]
	s_mov_b32 m0, s42
	ds_read_b128 v[184:187], v155 offset:49152
	ds_read_b128 v[188:191], v155 offset:50176
	ds_read_b128 v[192:195], v155 offset:51200
	ds_read_b128 v[196:199], v155 offset:52224
	ds_read_b128 v[200:203], v155 offset:53248
	ds_read_b128 v[208:211], v155 offset:54272
	ds_read_b128 v[212:215], v155 offset:55296
	ds_read_b128 v[216:219], v155 offset:56320
	global_load_lds_dwordx4 v[204:205], off
	s_add_i32 m0, s42, 0x2000
	s_add_u32 s42, s50, 0x20080
	v_lshl_add_u64 v[204:205], v[220:221], 0, s[10:11]
	s_addc_u32 s43, s51, 0
	s_add_i32 s50, s64, s21
	global_load_lds_dwordx4 v[204:205], off
	v_lshl_add_u64 v[204:205], s[42:43], 0, v[130:131]
	s_mov_b32 m0, s50
	s_nop 0
	global_load_lds_dwordx4 v[204:205], off
	v_lshl_add_u64 v[204:205], s[42:43], 0, v[134:135]
	s_add_i32 m0, s50, 0x2000
	s_nop 0
	global_load_lds_dwordx4 v[204:205], off
	v_lshl_add_u64 v[204:205], s[46:47], 0, v[128:129]
	s_mov_b32 m0, s55
	s_nop 0
	global_load_lds_dwordx4 v[204:205], off
	v_lshl_add_u64 v[204:205], s[46:47], 0, v[132:133]
	s_mov_b32 m0, s56
	s_nop 0
	global_load_lds_dwordx4 v[204:205], off
	s_waitcnt vmcnt(8)
	s_waitcnt lgkmcnt(0)
	s_barrier
	s_setprio 1
	s_waitcnt lgkmcnt(0)
	v_mfma_f32_16x16x32_bf16 v[60:63], v[146:149], v[184:187], v[60:63]
	v_mfma_f32_16x16x32_bf16 v[56:59], v[160:163], v[184:187], v[56:59]
	v_mfma_f32_16x16x32_bf16 v[44:47], v[146:149], v[192:195], v[44:47]
	v_mfma_f32_16x16x32_bf16 v[40:43], v[160:163], v[192:195], v[40:43]
	v_mfma_f32_16x16x32_bf16 v[28:31], v[146:149], v[200:203], v[28:31]
	v_mfma_f32_16x16x32_bf16 v[24:27], v[160:163], v[200:203], v[24:27]
	v_mfma_f32_16x16x32_bf16 v[12:15], v[146:149], v[212:215], v[12:15]
	v_mfma_f32_16x16x32_bf16 v[8:11], v[160:163], v[212:215], v[8:11]
	v_mfma_f32_16x16x32_bf16 v[60:63], v[156:159], v[188:191], v[60:63]
	v_mfma_f32_16x16x32_bf16 v[56:59], v[164:167], v[188:191], v[56:59]
	v_mfma_f32_16x16x32_bf16 v[44:47], v[156:159], v[196:199], v[44:47]
	v_mfma_f32_16x16x32_bf16 v[40:43], v[164:167], v[196:199], v[40:43]
	v_mfma_f32_16x16x32_bf16 v[28:31], v[156:159], v[208:211], v[28:31]
	v_mfma_f32_16x16x32_bf16 v[24:27], v[164:167], v[208:211], v[24:27]
	v_mfma_f32_16x16x32_bf16 v[12:15], v[156:159], v[216:219], v[12:15]
	v_mfma_f32_16x16x32_bf16 v[8:11], v[164:167], v[216:219], v[8:11]
	v_mfma_f32_16x16x32_bf16 v[52:55], v[168:171], v[184:187], v[52:55]
	v_mfma_f32_16x16x32_bf16 v[48:51], v[176:179], v[184:187], v[48:51]
	v_mfma_f32_16x16x32_bf16 v[36:39], v[168:171], v[192:195], v[36:39]
	v_mfma_f32_16x16x32_bf16 v[32:35], v[176:179], v[192:195], v[32:35]
	v_mfma_f32_16x16x32_bf16 v[20:23], v[168:171], v[200:203], v[20:23]
	v_mfma_f32_16x16x32_bf16 v[16:19], v[176:179], v[200:203], v[16:19]
	v_mfma_f32_16x16x32_bf16 v[4:7], v[168:171], v[212:215], v[4:7]
	v_mfma_f32_16x16x32_bf16 v[0:3], v[176:179], v[212:215], v[0:3]
	v_mfma_f32_16x16x32_bf16 v[52:55], v[172:175], v[188:191], v[52:55]
	v_mfma_f32_16x16x32_bf16 v[48:51], v[180:183], v[188:191], v[48:51]
	v_mfma_f32_16x16x32_bf16 v[36:39], v[172:175], v[196:199], v[36:39]
	v_mfma_f32_16x16x32_bf16 v[32:35], v[180:183], v[196:199], v[32:35]
	v_mfma_f32_16x16x32_bf16 v[20:23], v[172:175], v[208:211], v[20:23]
	v_mfma_f32_16x16x32_bf16 v[16:19], v[180:183], v[208:211], v[16:19]
	v_mfma_f32_16x16x32_bf16 v[4:7], v[172:175], v[216:219], v[4:7]
	v_mfma_f32_16x16x32_bf16 v[0:3], v[180:183], v[216:219], v[0:3]
	s_setprio 0
	s_barrier
	s_add_i32 s62, s62, 2
	s_add_u32 s60, s60, 0x100
	s_addc_u32 s61, s61, 0
	s_cmp_gt_u32 s62, 5
	s_mov_b64 s[42:43], s[44:45]
	s_cbranch_scc0 .LBB0_842
	s_and_b64 vcc, exec, s[12:13]
	s_cbranch_vccz .LBB0_845
	s_barrier

; #define PG8_STAGE(bufoff, gbase, voff) do { _Pragma("unroll") for (int _i = 0; _i < 2; ++_i) \
;         __builtin_amdgcn_global_load_lds((const unsigned*)((const char*)(gbase) + (voff)[_i]), (LAS unsigned*)(lds + (bufoff) + ldsw + _i * 8192), 16, 0, 0); } while (0)
; #define PG8_LDA(dst, b, h) do { _Pragma("unroll") for (int m = 0; m < 4; ++m) _Pragma("unroll") for (int k = 0; k < 2; ++k) dst[m][k] = *(const LAS bf16x8*)(lds + PG8_SA(b, h) + aoff + m * 2048 + k * 1024); } while (0)
; #define PG8_LDB(dst, b, h) do { _Pragma("unroll") for (int n = 0; n < 2; ++n) _Pragma("unroll") for (int k = 0; k < 2; ++k) dst[n][k] = *(const LAS bf16x8*)(lds + PG8_SB(b, h) + boff + n * 2048 + k * 1024); } while (0)
; #define PG8_WAIT_V(n) asm volatile("s_waitcnt vmcnt(" #n ")" ::: "memory")
; #define PG8_WAIT_L(n) asm volatile("s_waitcnt lgkmcnt(" #n ")" ::: "memory")
; #define PG8_BAR __builtin_amdgcn_s_barrier()
; #define PG8_SCHED __builtin_amdgcn_sched_barrier(0)
; template <class Epi, class Sched, bool SWAPD = false>
; __device__ __forceinline__ void gemm_phase(LAS unsigned char* lds, const Gemm g, const Sched& S, const Epi& E) {
;     ...
;             const bool last = (t == nt - 2);
;             const char* a1 = cA + (size_t)(t + 1) * kstepA;
;             const char* a2 = last ? nA : cA + (size_t)(t + 2) * kstepA; const char* b2 = last ? nB : cB + (size_t)(t + 2) * kstep;
;             const char* a3 = a2 + kstepA; const char* b3 = b2 + kstep;
;             PG8_LDB(B0, 0, 0); PG8_LDB(B1, 0, 1); PG8_SCHED; PG8_LDA(At, 0, 0); PG8_STAGE(PG8_SA(1, 1), a1 + hstepA, voffA);
;             PG8_WAIT_V(8); PG8_WAIT_L(0); PG8_BAR; PG8_MMA(0, 0, At, B0); PG8_MMA(0, 1, At, B1); PG8_BAR; PG8_SCHED;
;             PG8_LDA(At, 0, 1); PG8_STAGE(PG8_SB(0, 0), b2, voffB); PG8_STAGE(PG8_SB(0, 1), b2 + hstepB, voffB); PG8_STAGE(PG8_SA(0, 0), a2, voffA);
.LBB0_918:
	ds_read_b128 v[128:131], v200
	ds_read_b128 v[132:135], v200 offset:1024
	ds_read_b128 v[136:139], v200 offset:2048
	ds_read_b128 v[140:143], v200 offset:3072
	ds_read_b128 v[144:147], v201
	ds_read_b128 v[148:151], v201 offset:1024
	ds_read_b128 v[152:155], v201 offset:2048
	ds_read_b128 v[156:159], v201 offset:3072
	s_add_u32 s44, s42, 0xfffc0080
	s_addc_u32 s45, s43, -1
	s_cmp_eq_u32 s60, 12
	s_cselect_b32 s47, s23, s45
	s_cselect_b32 s46, s25, s44
	s_cselect_b32 s45, s35, s59
	s_cselect_b32 s44, s41, s58
	v_lshl_add_u64 v[196:197], s[42:43], 0, v[180:181]
	s_add_i32 m0, s30, 0xc000
	ds_read_b128 v[188:191], v202
	ds_read_b128 v[192:195], v202 offset:1024
	ds_read_b128 v[208:211], v202 offset:2048
	ds_read_b128 v[212:215], v202 offset:3072
	ds_read_b128 v[216:219], v202 offset:4096
	ds_read_b128 v[220:223], v202 offset:5120
	ds_read_b128 v[224:227], v202 offset:6144
	ds_read_b128 v[228:231], v202 offset:7168
	global_load_lds_dwordx4 v[196:197], off
	v_lshl_add_u64 v[196:197], s[42:43], 0, v[182:183]
	s_add_i32 m0, s30, 0xe000
	s_nop 0
	global_load_lds_dwordx4 v[196:197], off
	s_waitcnt vmcnt(8)
	s_waitcnt lgkmcnt(0)
	s_barrier
	s_setprio 1
	s_waitcnt lgkmcnt(0)
	v_mfma_f32_16x16x32_bf16 v[124:127], v[128:131], v[188:191], v[124:127]
	v_mfma_f32_16x16x32_bf16 v[120:123], v[136:139], v[188:191], v[120:123]
	v_mfma_f32_16x16x32_bf16 v[116:119], v[128:131], v[208:211], v[116:119]
	v_mfma_f32_16x16x32_bf16 v[112:115], v[136:139], v[208:211], v[112:115]
	v_mfma_f32_16x16x32_bf16 v[92:95], v[128:131], v[216:219], v[92:95]
	v_mfma_f32_16x16x32_bf16 v[88:91], v[136:139], v[216:219], v[88:91]
	v_mfma_f32_16x16x32_bf16 v[76:79], v[128:131], v[224:227], v[76:79]
	v_mfma_f32_16x16x32_bf16 v[72:75], v[136:139], v[224:227], v[72:75]
	v_mfma_f32_16x16x32_bf16 v[124:127], v[132:135], v[192:195], v[124:127]
	v_mfma_f32_16x16x32_bf16 v[120:123], v[140:143], v[192:195], v[120:123]
	v_mfma_f32_16x16x32_bf16 v[116:119], v[132:135], v[212:215], v[116:119]
	v_mfma_f32_16x16x32_bf16 v[112:115], v[140:143], v[212:215], v[112:115]
	v_mfma_f32_16x16x32_bf16 v[92:95], v[132:135], v[220:223], v[92:95]
	v_mfma_f32_16x16x32_bf16 v[88:91], v[140:143], v[220:223], v[88:91]
	v_mfma_f32_16x16x32_bf16 v[76:79], v[132:135], v[228:231], v[76:79]
	v_mfma_f32_16x16x32_bf16 v[72:75], v[140:143], v[228:231], v[72:75]
	v_mfma_f32_16x16x32_bf16 v[108:111], v[144:147], v[188:191], v[108:111]
	v_mfma_f32_16x16x32_bf16 v[104:107], v[152:155], v[188:191], v[104:107]
	v_mfma_f32_16x16x32_bf16 v[100:103], v[144:147], v[208:211], v[100:103]
	v_mfma_f32_16x16x32_bf16 v[96:99], v[152:155], v[208:211], v[96:99]
	v_mfma_f32_16x16x32_bf16 v[84:87], v[144:147], v[216:219], v[84:87]
	v_mfma_f32_16x16x32_bf16 v[80:83], v[152:155], v[216:219], v[80:83]
	v_mfma_f32_16x16x32_bf16 v[68:71], v[144:147], v[224:227], v[68:71]
	v_mfma_f32_16x16x32_bf16 v[64:67], v[152:155], v[224:227], v[64:67]
	v_mfma_f32_16x16x32_bf16 v[108:111], v[148:151], v[192:195], v[108:111]
	v_mfma_f32_16x16x32_bf16 v[104:107], v[156:159], v[192:195], v[104:107]
	v_mfma_f32_16x16x32_bf16 v[100:103], v[148:151], v[212:215], v[100:103]
	v_mfma_f32_16x16x32_bf16 v[96:99], v[156:159], v[212:215], v[96:99]
	v_mfma_f32_16x16x32_bf16 v[84:87], v[148:151], v[220:223], v[84:87]
	v_mfma_f32_16x16x32_bf16 v[80:83], v[156:159], v[220:223], v[80:83]
	v_mfma_f32_16x16x32_bf16 v[68:71], v[148:151], v[228:231], v[68:71]
	v_mfma_f32_16x16x32_bf16 v[64:67], v[156:159], v[228:231], v[64:67]
	s_setprio 0
	s_barrier
	s_add_i32 s61, s56, s21
	v_lshl_add_u64 v[196:197], s[44:45], 0, v[160:161]
	s_mov_b32 m0, s61
	ds_read_b128 v[188:191], v202 offset:16384
	ds_read_b128 v[192:195], v202 offset:17408
	ds_read_b128 v[208:211], v202 offset:18432
	ds_read_b128 v[212:215], v202 offset:19456
	ds_read_b128 v[216:219], v202 offset:20480
	ds_read_b128 v[220:223], v202 offset:21504
	ds_read_b128 v[224:227], v202 offset:22528
	ds_read_b128 v[228:231], v202 offset:23552
	global_load_lds_dwordx4 v[196:197], off
	s_add_i32 m0, s61, 0x2000
	s_add_u32 s62, s44, 0x40000
	v_lshl_add_u64 v[204:205], s[44:45], 0, v[162:163]
	s_addc_u32 s63, s45, 0
	s_add_i32 s61, s57, s21
	global_load_lds_dwordx4 v[204:205], off
	v_lshl_add_u64 v[232:233], s[62:63], 0, v[160:161]
	s_mov_b32 m0, s61
	v_lshl_add_u64 v[234:235], s[46:47], 0, v[162:163]
	global_load_lds_dwordx4 v[232:233], off
	v_lshl_add_u64 v[232:233], s[62:63], 0, v[162:163]
	s_add_i32 m0, s61, 0x2000
	s_nop 0
	global_load_lds_dwordx4 v[232:233], off
	v_lshl_add_u64 v[232:233], s[46:47], 0, v[160:161]
	s_mov_b32 m0, s30
	s_nop 0
	global_load_lds_dwordx4 v[232:233], off
	s_mov_b32 m0, s31
	s_nop 0
	global_load_lds_dwordx4 v[234:235], off
	s_waitcnt vmcnt(8)
	s_waitcnt lgkmcnt(0)
	s_barrier
; #define PG8_STAGE(bufoff, gbase, voff) do { _Pragma("unroll") for (int _i = 0; _i < 2; ++_i) \
;         __builtin_amdgcn_global_load_lds((const unsigned*)((const char*)(gbase) + (voff)[_i]), (LAS unsigned*)(lds + (bufoff) + ldsw + _i * 8192), 16, 0, 0); } while (0)
; #define PG8_LDA(dst, b, h) do { _Pragma("unroll") for (int m = 0; m < 4; ++m) _Pragma("unroll") for (int k = 0; k < 2; ++k) dst[m][k] = *(const LAS bf16x8*)(lds + PG8_SA(b, h) + aoff + m * 2048 + k * 1024); } while (0)
; #define PG8_LDB(dst, b, h) do { _Pragma("unroll") for (int n = 0; n < 2; ++n) _Pragma("unroll") for (int k = 0; k < 2; ++k) dst[n][k] = *(const LAS bf16x8*)(lds + PG8_SB(b, h) + boff + n * 2048 + k * 1024); } while (0)
; #define PG8_WAIT_V(n) asm volatile("s_waitcnt vmcnt(" #n ")" ::: "memory")
; #define PG8_WAIT_L(n) asm volatile("s_waitcnt lgkmcnt(" #n ")" ::: "memory")
; #define PG8_BAR __builtin_amdgcn_s_barrier()
; #define PG8_SCHED __builtin_amdgcn_sched_barrier(0)
; template <class Epi, class Sched, bool SWAPD = false>
; __device__ __forceinline__ void gemm_phase(LAS unsigned char* lds, const Gemm g, const Sched& S, const Epi& E) {
;     ...
;             PG8_WAIT_V(8); PG8_WAIT_L(0); PG8_BAR; PG8_MMA(1, 0, At, B0); PG8_MMA(1, 1, At, B1); PG8_BAR; PG8_SCHED;
;             PG8_LDB(B0, 1, 0); PG8_LDB(B1, 1, 1); PG8_SCHED; PG8_LDA(At, 1, 0); PG8_STAGE(PG8_SA(0, 1), a2 + hstepA, voffA);
;             PG8_WAIT_V(8); PG8_WAIT_L(0); PG8_BAR; PG8_MMA(0, 0, At, B0); PG8_MMA(0, 1, At, B1); PG8_BAR; PG8_SCHED;
	s_setprio 1
	s_waitcnt lgkmcnt(0)
	v_mfma_f32_16x16x32_bf16 v[60:63], v[128:131], v[188:191], v[60:63]
	v_mfma_f32_16x16x32_bf16 v[56:59], v[136:139], v[188:191], v[56:59]
	v_mfma_f32_16x16x32_bf16 v[44:47], v[128:131], v[208:211], v[44:47]
	v_mfma_f32_16x16x32_bf16 v[40:43], v[136:139], v[208:211], v[40:43]
	v_mfma_f32_16x16x32_bf16 v[36:39], v[128:131], v[216:219], v[36:39]
	v_mfma_f32_16x16x32_bf16 v[32:35], v[136:139], v[216:219], v[32:35]
	v_mfma_f32_16x16x32_bf16 v[20:23], v[128:131], v[224:227], v[20:23]
	v_mfma_f32_16x16x32_bf16 v[16:19], v[136:139], v[224:227], v[16:19]
	v_mfma_f32_16x16x32_bf16 v[60:63], v[132:135], v[192:195], v[60:63]
	v_mfma_f32_16x16x32_bf16 v[56:59], v[140:143], v[192:195], v[56:59]
	v_mfma_f32_16x16x32_bf16 v[44:47], v[132:135], v[212:215], v[44:47]
	v_mfma_f32_16x16x32_bf16 v[40:43], v[140:143], v[212:215], v[40:43]
	v_mfma_f32_16x16x32_bf16 v[36:39], v[132:135], v[220:223], v[36:39]
	v_mfma_f32_16x16x32_bf16 v[32:35], v[140:143], v[220:223], v[32:35]
	v_mfma_f32_16x16x32_bf16 v[20:23], v[132:135], v[228:231], v[20:23]
	v_mfma_f32_16x16x32_bf16 v[16:19], v[140:143], v[228:231], v[16:19]
	v_mfma_f32_16x16x32_bf16 v[52:55], v[144:147], v[188:191], v[52:55]
	v_mfma_f32_16x16x32_bf16 v[48:51], v[152:155], v[188:191], v[48:51]
	v_mfma_f32_16x16x32_bf16 v[28:31], v[144:147], v[208:211], v[28:31]
	v_mfma_f32_16x16x32_bf16 v[24:27], v[152:155], v[208:211], v[24:27]
	v_mfma_f32_16x16x32_bf16 v[12:15], v[144:147], v[216:219], v[12:15]
	v_mfma_f32_16x16x32_bf16 v[8:11], v[152:155], v[216:219], v[8:11]
	v_mfma_f32_16x16x32_bf16 v[4:7], v[144:147], v[224:227], v[4:7]
	v_mfma_f32_16x16x32_bf16 v[0:3], v[152:155], v[224:227], v[0:3]
	v_mfma_f32_16x16x32_bf16 v[52:55], v[148:151], v[192:195], v[52:55]
	v_mfma_f32_16x16x32_bf16 v[48:51], v[156:159], v[192:195], v[48:51]
	v_mfma_f32_16x16x32_bf16 v[28:31], v[148:151], v[212:215], v[28:31]
	v_mfma_f32_16x16x32_bf16 v[24:27], v[156:159], v[212:215], v[24:27]
	v_mfma_f32_16x16x32_bf16 v[12:15], v[148:151], v[220:223], v[12:15]
	v_mfma_f32_16x16x32_bf16 v[8:11], v[156:159], v[220:223], v[8:11]
	v_mfma_f32_16x16x32_bf16 v[4:7], v[148:151], v[228:231], v[4:7]
	v_mfma_f32_16x16x32_bf16 v[0:3], v[156:159], v[228:231], v[0:3]
	s_setprio 0
	s_barrier
	s_add_i32 s61, 0, 0x18000
	s_add_i32 s62, 0, 0x1c000
	v_add_u32_e32 v140, s61, v198
	v_add_u32_e32 v156, s62, v198
	ds_read_b128 v[128:131], v140
	ds_read_b128 v[132:135], v140 offset:1024
	ds_read_b128 v[136:139], v140 offset:2048
	ds_read_b128 v[140:143], v140 offset:3072
	ds_read_b128 v[144:147], v156
	ds_read_b128 v[148:151], v156 offset:1024
	ds_read_b128 v[152:155], v156 offset:2048
	ds_read_b128 v[156:159], v156 offset:3072
	s_add_u32 s46, s46, 0x40000
	s_addc_u32 s47, s47, 0
	s_mov_b32 m0, s33
	v_lshl_add_u64 v[236:237], s[46:47], 0, v[160:161]
	ds_read_b128 v[188:191], v202 offset:32768
	ds_read_b128 v[192:195], v202 offset:33792
	ds_read_b128 v[208:211], v202 offset:34816
	ds_read_b128 v[212:215], v202 offset:35840
	ds_read_b128 v[216:219], v202 offset:36864
	ds_read_b128 v[220:223], v202 offset:37888
	ds_read_b128 v[224:227], v202 offset:38912
	ds_read_b128 v[228:231], v202 offset:39936
	global_load_lds_dwordx4 v[236:237], off
	v_lshl_add_u64 v[236:237], s[46:47], 0, v[162:163]
	s_mov_b32 m0, s50
	s_nop 0
	global_load_lds_dwordx4 v[236:237], off
	s_waitcnt vmcnt(8)
	s_waitcnt lgkmcnt(0)
	s_barrier
	s_setprio 1
	s_waitcnt lgkmcnt(0)
	v_mfma_f32_16x16x32_bf16 v[124:127], v[128:131], v[188:191], v[124:127]
	v_mfma_f32_16x16x32_bf16 v[120:123], v[136:139], v[188:191], v[120:123]
	v_mfma_f32_16x16x32_bf16 v[116:119], v[128:131], v[208:211], v[116:119]
	v_mfma_f32_16x16x32_bf16 v[112:115], v[136:139], v[208:211], v[112:115]
	v_mfma_f32_16x16x32_bf16 v[92:95], v[128:131], v[216:219], v[92:95]
	v_mfma_f32_16x16x32_bf16 v[88:91], v[136:139], v[216:219], v[88:91]
	v_mfma_f32_16x16x32_bf16 v[76:79], v[128:131], v[224:227], v[76:79]
	v_mfma_f32_16x16x32_bf16 v[72:75], v[136:139], v[224:227], v[72:75]
	v_mfma_f32_16x16x32_bf16 v[124:127], v[132:135], v[192:195], v[124:127]
	v_mfma_f32_16x16x32_bf16 v[120:123], v[140:143], v[192:195], v[120:123]
	v_mfma_f32_16x16x32_bf16 v[116:119], v[132:135], v[212:215], v[116:119]
	v_mfma_f32_16x16x32_bf16 v[112:115], v[140:143], v[212:215], v[112:115]
	v_mfma_f32_16x16x32_bf16 v[92:95], v[132:135], v[220:223], v[92:95]
	v_mfma_f32_16x16x32_bf16 v[88:91], v[140:143], v[220:223], v[88:91]
	v_mfma_f32_16x16x32_bf16 v[76:79], v[132:135], v[228:231], v[76:79]
	v_mfma_f32_16x16x32_bf16 v[72:75], v[140:143], v[228:231], v[72:75]
	v_mfma_f32_16x16x32_bf16 v[108:111], v[144:147], v[188:191], v[108:111]
	v_mfma_f32_16x16x32_bf16 v[104:107], v[152:155], v[188:191], v[104:107]
	v_mfma_f32_16x16x32_bf16 v[100:103], v[144:147], v[208:211], v[100:103]
	v_mfma_f32_16x16x32_bf16 v[96:99], v[152:155], v[208:211], v[96:99]
	v_mfma_f32_16x16x32_bf16 v[84:87], v[144:147], v[216:219], v[84:87]
	v_mfma_f32_16x16x32_bf16 v[80:83], v[152:155], v[216:219], v[80:83]
	v_mfma_f32_16x16x32_bf16 v[68:71], v[144:147], v[224:227], v[68:71]
	v_mfma_f32_16x16x32_bf16 v[64:67], v[152:155], v[224:227], v[64:67]
	v_mfma_f32_16x16x32_bf16 v[108:111], v[148:151], v[192:195], v[108:111]
	v_mfma_f32_16x16x32_bf16 v[104:107], v[156:159], v[192:195], v[104:107]
	v_mfma_f32_16x16x32_bf16 v[100:103], v[148:151], v[212:215], v[100:103]
	v_mfma_f32_16x16x32_bf16 v[96:99], v[156:159], v[212:215], v[96:99]
	v_mfma_f32_16x16x32_bf16 v[84:87], v[148:151], v[220:223], v[84:87]
	v_mfma_f32_16x16x32_bf16 v[80:83], v[156:159], v[220:223], v[80:83]
	v_mfma_f32_16x16x32_bf16 v[68:71], v[148:151], v[228:231], v[68:71]
	v_mfma_f32_16x16x32_bf16 v[64:67], v[156:159], v[228:231], v[64:67]
	s_setprio 0
	s_barrier
; #define PG8_STAGE(bufoff, gbase, voff) do { _Pragma("unroll") for (int _i = 0; _i < 2; ++_i) \
;         __builtin_amdgcn_global_load_lds((const unsigned*)((const char*)(gbase) + (voff)[_i]), (LAS unsigned*)(lds + (bufoff) + ldsw + _i * 8192), 16, 0, 0); } while (0)
; #define PG8_LDA(dst, b, h) do { _Pragma("unroll") for (int m = 0; m < 4; ++m) _Pragma("unroll") for (int k = 0; k < 2; ++k) dst[m][k] = *(const LAS bf16x8*)(lds + PG8_SA(b, h) + aoff + m * 2048 + k * 1024); } while (0)
; #define PG8_WAIT_V(n) asm volatile("s_waitcnt vmcnt(" #n ")" ::: "memory")
; #define PG8_WAIT_L(n) asm volatile("s_waitcnt lgkmcnt(" #n ")" ::: "memory")
; #define PG8_BAR __builtin_amdgcn_s_barrier()
; #define PG8_SCHED __builtin_amdgcn_sched_barrier(0)
; template <class Epi, class Sched, bool SWAPD = false>
; __device__ __forceinline__ void gemm_phase(LAS unsigned char* lds, const Gemm g, const Sched& S, const Epi& E) {
;     ...
;             PG8_LDA(At, 1, 1); PG8_STAGE(PG8_SB(1, 0), b3, voffB); PG8_STAGE(PG8_SB(1, 1), b3 + hstepB, voffB); PG8_STAGE(PG8_SA(1, 0), a3, voffA);
;             PG8_WAIT_V(8); PG8_WAIT_L(0); PG8_BAR; PG8_MMA(1, 0, At, B0); PG8_MMA(1, 1, At, B1); PG8_BAR; PG8_SCHED;
;         }
	s_add_i32 s46, s61, s21
	v_lshl_add_u64 v[196:197], v[196:197], 0, s[10:11]
	s_mov_b32 m0, s46
	ds_read_b128 v[188:191], v202 offset:49152
	ds_read_b128 v[192:195], v202 offset:50176
	ds_read_b128 v[208:211], v202 offset:51200
	ds_read_b128 v[212:215], v202 offset:52224
	ds_read_b128 v[216:219], v202 offset:53248
	ds_read_b128 v[220:223], v202 offset:54272
	ds_read_b128 v[224:227], v202 offset:55296
	ds_read_b128 v[228:231], v202 offset:56320
	global_load_lds_dwordx4 v[196:197], off
	s_add_i32 m0, s46, 0x2000
	s_add_u32 s44, s44, 0x40080
	v_lshl_add_u64 v[196:197], v[204:205], 0, s[10:11]
	s_addc_u32 s45, s45, 0
	s_add_i32 s46, s62, s21
	global_load_lds_dwordx4 v[196:197], off
	v_lshl_add_u64 v[196:197], s[44:45], 0, v[160:161]
	s_mov_b32 m0, s46
	s_nop 0
	global_load_lds_dwordx4 v[196:197], off
	v_lshl_add_u64 v[196:197], s[44:45], 0, v[162:163]
	s_add_i32 m0, s46, 0x2000
	s_nop 0
	global_load_lds_dwordx4 v[196:197], off
	v_lshl_add_u64 v[196:197], v[232:233], 0, s[10:11]
	s_mov_b32 m0, s54
	s_nop 0
	global_load_lds_dwordx4 v[196:197], off
	v_lshl_add_u64 v[196:197], v[234:235], 0, s[10:11]
	s_mov_b32 m0, s55
	s_nop 0
	global_load_lds_dwordx4 v[196:197], off
	s_waitcnt vmcnt(8)
	s_waitcnt lgkmcnt(0)
	s_barrier
	s_setprio 1
	s_waitcnt lgkmcnt(0)
	v_mfma_f32_16x16x32_bf16 v[60:63], v[128:131], v[188:191], v[60:63]
	v_mfma_f32_16x16x32_bf16 v[56:59], v[136:139], v[188:191], v[56:59]
	v_mfma_f32_16x16x32_bf16 v[44:47], v[128:131], v[208:211], v[44:47]
	v_mfma_f32_16x16x32_bf16 v[40:43], v[136:139], v[208:211], v[40:43]
	v_mfma_f32_16x16x32_bf16 v[36:39], v[128:131], v[216:219], v[36:39]
	v_mfma_f32_16x16x32_bf16 v[32:35], v[136:139], v[216:219], v[32:35]
	v_mfma_f32_16x16x32_bf16 v[20:23], v[128:131], v[224:227], v[20:23]
	v_mfma_f32_16x16x32_bf16 v[16:19], v[136:139], v[224:227], v[16:19]
	v_mfma_f32_16x16x32_bf16 v[60:63], v[132:135], v[192:195], v[60:63]
	v_mfma_f32_16x16x32_bf16 v[56:59], v[140:143], v[192:195], v[56:59]
	v_mfma_f32_16x16x32_bf16 v[44:47], v[132:135], v[212:215], v[44:47]
	v_mfma_f32_16x16x32_bf16 v[40:43], v[140:143], v[212:215], v[40:43]
	v_mfma_f32_16x16x32_bf16 v[36:39], v[132:135], v[220:223], v[36:39]
	v_mfma_f32_16x16x32_bf16 v[32:35], v[140:143], v[220:223], v[32:35]
	v_mfma_f32_16x16x32_bf16 v[20:23], v[132:135], v[228:231], v[20:23]
	v_mfma_f32_16x16x32_bf16 v[16:19], v[140:143], v[228:231], v[16:19]
	v_mfma_f32_16x16x32_bf16 v[52:55], v[144:147], v[188:191], v[52:55]
	v_mfma_f32_16x16x32_bf16 v[48:51], v[152:155], v[188:191], v[48:51]
	v_mfma_f32_16x16x32_bf16 v[28:31], v[144:147], v[208:211], v[28:31]
	v_mfma_f32_16x16x32_bf16 v[24:27], v[152:155], v[208:211], v[24:27]
	v_mfma_f32_16x16x32_bf16 v[12:15], v[144:147], v[216:219], v[12:15]
	v_mfma_f32_16x16x32_bf16 v[8:11], v[152:155], v[216:219], v[8:11]
	v_mfma_f32_16x16x32_bf16 v[4:7], v[144:147], v[224:227], v[4:7]
	v_mfma_f32_16x16x32_bf16 v[0:3], v[152:155], v[224:227], v[0:3]
	v_mfma_f32_16x16x32_bf16 v[52:55], v[148:151], v[192:195], v[52:55]
	v_mfma_f32_16x16x32_bf16 v[48:51], v[156:159], v[192:195], v[48:51]
	v_mfma_f32_16x16x32_bf16 v[28:31], v[148:151], v[212:215], v[28:31]
	v_mfma_f32_16x16x32_bf16 v[24:27], v[156:159], v[212:215], v[24:27]
	v_mfma_f32_16x16x32_bf16 v[12:15], v[148:151], v[220:223], v[12:15]
	v_mfma_f32_16x16x32_bf16 v[8:11], v[156:159], v[220:223], v[8:11]
	v_mfma_f32_16x16x32_bf16 v[4:7], v[148:151], v[228:231], v[4:7]
	v_mfma_f32_16x16x32_bf16 v[0:3], v[156:159], v[228:231], v[0:3]
	s_setprio 0
	s_barrier
	s_add_i32 s60, s60, 2
	s_add_u32 s42, s42, 0x100
	s_addc_u32 s43, s43, 0
	s_add_u32 s58, s58, 0x100
	s_addc_u32 s59, s59, 0
	s_cmp_gt_u32 s60, 13
	s_cbranch_scc0 .LBB0_918
	s_and_b64 vcc, exec, s[12:13]
	s_cbranch_vccz .LBB0_921
	s_barrier

; #define PG8_STAGE(bufoff, gbase, voff) do { _Pragma("unroll") for (int _i = 0; _i < 2; ++_i) \
;         __builtin_amdgcn_global_load_lds((const unsigned*)((const char*)(gbase) + (voff)[_i]), (LAS unsigned*)(lds + (bufoff) + ldsw + _i * 8192), 16, 0, 0); } while (0)
; #define PG8_LDA(dst, b, h) do { _Pragma("unroll") for (int m = 0; m < 4; ++m) _Pragma("unroll") for (int k = 0; k < 2; ++k) dst[m][k] = *(const LAS bf16x8*)(lds + PG8_SA(b, h) + aoff + m * 2048 + k * 1024); } while (0)
; #define PG8_LDB(dst, b, h) do { _Pragma("unroll") for (int n = 0; n < 2; ++n) _Pragma("unroll") for (int k = 0; k < 2; ++k) dst[n][k] = *(const LAS bf16x8*)(lds + PG8_SB(b, h) + boff + n * 2048 + k * 1024); } while (0)
; #define PG8_WAIT_V(n) asm volatile("s_waitcnt vmcnt(" #n ")" ::: "memory")
; #define PG8_WAIT_L(n) asm volatile("s_waitcnt lgkmcnt(" #n ")" ::: "memory")
; #define PG8_BAR __builtin_amdgcn_s_barrier()
; #define PG8_SCHED __builtin_amdgcn_sched_barrier(0)
; template <class Epi, class Sched, bool SWAPD = false>
; __device__ __forceinline__ void gemm_phase(LAS unsigned char* lds, const Gemm g, const Sched& S, const Epi& E) {
;     ...
;             const bool last = (t == nt - 2);
;             const char* a1 = cA + (size_t)(t + 1) * kstepA;
;             const char* a2 = last ? nA : cA + (size_t)(t + 2) * kstepA; const char* b2 = last ? nB : cB + (size_t)(t + 2) * kstep;
;             const char* a3 = a2 + kstepA; const char* b3 = b2 + kstep;
;             PG8_LDB(B0, 0, 0); PG8_LDB(B1, 0, 1); PG8_SCHED; PG8_LDA(At, 0, 0); PG8_STAGE(PG8_SA(1, 1), a1 + hstepA, voffA);
;             PG8_WAIT_V(8); PG8_WAIT_L(0); PG8_BAR; PG8_MMA(0, 0, At, B0); PG8_MMA(0, 1, At, B1); PG8_BAR; PG8_SCHED;
;             PG8_LDA(At, 0, 1); PG8_STAGE(PG8_SB(0, 0), b2, voffB); PG8_STAGE(PG8_SB(0, 1), b2 + hstepB, voffB); PG8_STAGE(PG8_SA(0, 0), a2, voffA);
.LBB0_1044:
	ds_read_b128 v[148:151], v145
	ds_read_b128 v[152:155], v145 offset:1024
	ds_read_b128 v[156:159], v145 offset:2048
	ds_read_b128 v[160:163], v145 offset:3072
	ds_read_b128 v[164:167], v146
	ds_read_b128 v[168:171], v146 offset:1024
	ds_read_b128 v[172:175], v146 offset:2048
	ds_read_b128 v[176:179], v146 offset:3072
	s_add_u32 s44, s42, 0xfffc0080
	s_addc_u32 s45, s43, -1
	s_cmp_eq_u32 s63, 12
	s_cselect_b32 s47, s25, s45
	s_cselect_b32 s46, s27, s44
	s_cselect_b32 s45, s59, s62
	s_cselect_b32 s44, s60, s61
	v_lshl_add_u64 v[140:141], s[42:43], 0, v[132:133]
	s_add_i32 m0, s33, 0xc000
	ds_read_b128 v[180:183], v147
	ds_read_b128 v[184:187], v147 offset:1024
	ds_read_b128 v[188:191], v147 offset:2048
	ds_read_b128 v[192:195], v147 offset:3072
	ds_read_b128 v[196:199], v147 offset:4096
	ds_read_b128 v[200:203], v147 offset:5120
	ds_read_b128 v[208:211], v147 offset:6144
	ds_read_b128 v[212:215], v147 offset:7168
	global_load_lds_dwordx4 v[140:141], off
	v_lshl_add_u64 v[140:141], s[42:43], 0, v[134:135]
	s_add_i32 m0, s33, 0xe000
	s_nop 0
	global_load_lds_dwordx4 v[140:141], off
	s_waitcnt vmcnt(8)
	s_waitcnt lgkmcnt(0)
	s_barrier
	s_setprio 1
	s_waitcnt lgkmcnt(0)
	v_mfma_f32_16x16x32_bf16 v[124:127], v[148:151], v[180:183], v[124:127]
	v_mfma_f32_16x16x32_bf16 v[116:119], v[156:159], v[180:183], v[116:119]
	v_mfma_f32_16x16x32_bf16 v[108:111], v[148:151], v[188:191], v[108:111]
	v_mfma_f32_16x16x32_bf16 v[100:103], v[156:159], v[188:191], v[100:103]
	v_mfma_f32_16x16x32_bf16 v[92:95], v[148:151], v[196:199], v[92:95]
	v_mfma_f32_16x16x32_bf16 v[84:87], v[156:159], v[196:199], v[84:87]
	v_mfma_f32_16x16x32_bf16 v[76:79], v[148:151], v[208:211], v[76:79]
	v_mfma_f32_16x16x32_bf16 v[68:71], v[156:159], v[208:211], v[68:71]
	v_mfma_f32_16x16x32_bf16 v[124:127], v[152:155], v[184:187], v[124:127]
	v_mfma_f32_16x16x32_bf16 v[116:119], v[160:163], v[184:187], v[116:119]
	v_mfma_f32_16x16x32_bf16 v[108:111], v[152:155], v[192:195], v[108:111]
	v_mfma_f32_16x16x32_bf16 v[100:103], v[160:163], v[192:195], v[100:103]
	v_mfma_f32_16x16x32_bf16 v[92:95], v[152:155], v[200:203], v[92:95]
	v_mfma_f32_16x16x32_bf16 v[84:87], v[160:163], v[200:203], v[84:87]
	v_mfma_f32_16x16x32_bf16 v[76:79], v[152:155], v[212:215], v[76:79]
	v_mfma_f32_16x16x32_bf16 v[68:71], v[160:163], v[212:215], v[68:71]
	v_mfma_f32_16x16x32_bf16 v[120:123], v[164:167], v[180:183], v[120:123]
	v_mfma_f32_16x16x32_bf16 v[112:115], v[172:175], v[180:183], v[112:115]
	v_mfma_f32_16x16x32_bf16 v[104:107], v[164:167], v[188:191], v[104:107]
	v_mfma_f32_16x16x32_bf16 v[96:99], v[172:175], v[188:191], v[96:99]
	v_mfma_f32_16x16x32_bf16 v[88:91], v[164:167], v[196:199], v[88:91]
	v_mfma_f32_16x16x32_bf16 v[80:83], v[172:175], v[196:199], v[80:83]
	v_mfma_f32_16x16x32_bf16 v[72:75], v[164:167], v[208:211], v[72:75]
	v_mfma_f32_16x16x32_bf16 v[64:67], v[172:175], v[208:211], v[64:67]
	v_mfma_f32_16x16x32_bf16 v[120:123], v[168:171], v[184:187], v[120:123]
	v_mfma_f32_16x16x32_bf16 v[112:115], v[176:179], v[184:187], v[112:115]
	v_mfma_f32_16x16x32_bf16 v[104:107], v[168:171], v[192:195], v[104:107]
	v_mfma_f32_16x16x32_bf16 v[96:99], v[176:179], v[192:195], v[96:99]
	v_mfma_f32_16x16x32_bf16 v[88:91], v[168:171], v[200:203], v[88:91]
	v_mfma_f32_16x16x32_bf16 v[80:83], v[176:179], v[200:203], v[80:83]
	v_mfma_f32_16x16x32_bf16 v[72:75], v[168:171], v[212:215], v[72:75]
	v_mfma_f32_16x16x32_bf16 v[64:67], v[176:179], v[212:215], v[64:67]
	s_setprio 0
	s_barrier
	s_add_i32 s64, s55, s30
	v_lshl_add_u64 v[140:141], s[44:45], 0, v[130:131]
	s_mov_b32 m0, s64
	ds_read_b128 v[180:183], v147 offset:16384
	ds_read_b128 v[184:187], v147 offset:17408
	ds_read_b128 v[188:191], v147 offset:18432
	ds_read_b128 v[192:195], v147 offset:19456
	ds_read_b128 v[196:199], v147 offset:20480
	ds_read_b128 v[200:203], v147 offset:21504
	ds_read_b128 v[208:211], v147 offset:22528
	ds_read_b128 v[212:215], v147 offset:23552
	global_load_lds_dwordx4 v[140:141], off
	s_add_i32 m0, s64, 0x2000
	s_add_u32 s64, s44, 0x40000
	v_lshl_add_u64 v[204:205], s[44:45], 0, v[128:129]
	s_addc_u32 s65, s45, 0
	s_add_i32 s66, s56, s30
	global_load_lds_dwordx4 v[204:205], off
	v_lshl_add_u64 v[216:217], s[64:65], 0, v[130:131]
	s_mov_b32 m0, s66
	v_lshl_add_u64 v[218:219], s[46:47], 0, v[128:129]
	global_load_lds_dwordx4 v[216:217], off
	v_lshl_add_u64 v[216:217], s[64:65], 0, v[128:129]
	s_add_i32 m0, s66, 0x2000
	s_nop 0
	global_load_lds_dwordx4 v[216:217], off
	v_lshl_add_u64 v[216:217], s[46:47], 0, v[130:131]
	s_mov_b32 m0, s33
	s_nop 0
	global_load_lds_dwordx4 v[216:217], off
	s_mov_b32 m0, s41
	s_nop 0
	global_load_lds_dwordx4 v[218:219], off
	s_waitcnt vmcnt(8)
	s_waitcnt lgkmcnt(0)
	s_barrier
; #define PG8_STAGE(bufoff, gbase, voff) do { _Pragma("unroll") for (int _i = 0; _i < 2; ++_i) \
;         __builtin_amdgcn_global_load_lds((const unsigned*)((const char*)(gbase) + (voff)[_i]), (LAS unsigned*)(lds + (bufoff) + ldsw + _i * 8192), 16, 0, 0); } while (0)
; #define PG8_LDA(dst, b, h) do { _Pragma("unroll") for (int m = 0; m < 4; ++m) _Pragma("unroll") for (int k = 0; k < 2; ++k) dst[m][k] = *(const LAS bf16x8*)(lds + PG8_SA(b, h) + aoff + m * 2048 + k * 1024); } while (0)
; #define PG8_LDB(dst, b, h) do { _Pragma("unroll") for (int n = 0; n < 2; ++n) _Pragma("unroll") for (int k = 0; k < 2; ++k) dst[n][k] = *(const LAS bf16x8*)(lds + PG8_SB(b, h) + boff + n * 2048 + k * 1024); } while (0)
; #define PG8_WAIT_V(n) asm volatile("s_waitcnt vmcnt(" #n ")" ::: "memory")
; #define PG8_WAIT_L(n) asm volatile("s_waitcnt lgkmcnt(" #n ")" ::: "memory")
; #define PG8_BAR __builtin_amdgcn_s_barrier()
; #define PG8_SCHED __builtin_amdgcn_sched_barrier(0)
; template <class Epi, class Sched, bool SWAPD = false>
; __device__ __forceinline__ void gemm_phase(LAS unsigned char* lds, const Gemm g, const Sched& S, const Epi& E) {
;     ...
;             PG8_WAIT_V(8); PG8_WAIT_L(0); PG8_BAR; PG8_MMA(1, 0, At, B0); PG8_MMA(1, 1, At, B1); PG8_BAR; PG8_SCHED;
;             PG8_LDB(B0, 1, 0); PG8_LDB(B1, 1, 1); PG8_SCHED; PG8_LDA(At, 1, 0); PG8_STAGE(PG8_SA(0, 1), a2 + hstepA, voffA);
;             PG8_WAIT_V(8); PG8_WAIT_L(0); PG8_BAR; PG8_MMA(0, 0, At, B0); PG8_MMA(0, 1, At, B1); PG8_BAR; PG8_SCHED;
	s_setprio 1
	s_waitcnt lgkmcnt(0)
	v_mfma_f32_16x16x32_bf16 v[60:63], v[148:151], v[180:183], v[60:63]
	v_mfma_f32_16x16x32_bf16 v[52:55], v[156:159], v[180:183], v[52:55]
	v_mfma_f32_16x16x32_bf16 v[44:47], v[148:151], v[188:191], v[44:47]
	v_mfma_f32_16x16x32_bf16 v[36:39], v[156:159], v[188:191], v[36:39]
	v_mfma_f32_16x16x32_bf16 v[28:31], v[148:151], v[196:199], v[28:31]
	v_mfma_f32_16x16x32_bf16 v[20:23], v[156:159], v[196:199], v[20:23]
	v_mfma_f32_16x16x32_bf16 v[12:15], v[148:151], v[208:211], v[12:15]
	v_mfma_f32_16x16x32_bf16 v[4:7], v[156:159], v[208:211], v[4:7]
	v_mfma_f32_16x16x32_bf16 v[60:63], v[152:155], v[184:187], v[60:63]
	v_mfma_f32_16x16x32_bf16 v[52:55], v[160:163], v[184:187], v[52:55]
	v_mfma_f32_16x16x32_bf16 v[44:47], v[152:155], v[192:195], v[44:47]
	v_mfma_f32_16x16x32_bf16 v[36:39], v[160:163], v[192:195], v[36:39]
	v_mfma_f32_16x16x32_bf16 v[28:31], v[152:155], v[200:203], v[28:31]
	v_mfma_f32_16x16x32_bf16 v[20:23], v[160:163], v[200:203], v[20:23]
	v_mfma_f32_16x16x32_bf16 v[12:15], v[152:155], v[212:215], v[12:15]
	v_mfma_f32_16x16x32_bf16 v[4:7], v[160:163], v[212:215], v[4:7]
	v_mfma_f32_16x16x32_bf16 v[56:59], v[164:167], v[180:183], v[56:59]
	v_mfma_f32_16x16x32_bf16 v[48:51], v[172:175], v[180:183], v[48:51]
	v_mfma_f32_16x16x32_bf16 v[40:43], v[164:167], v[188:191], v[40:43]
	v_mfma_f32_16x16x32_bf16 v[32:35], v[172:175], v[188:191], v[32:35]
	v_mfma_f32_16x16x32_bf16 v[24:27], v[164:167], v[196:199], v[24:27]
	v_mfma_f32_16x16x32_bf16 v[16:19], v[172:175], v[196:199], v[16:19]
	v_mfma_f32_16x16x32_bf16 v[8:11], v[164:167], v[208:211], v[8:11]
	v_mfma_f32_16x16x32_bf16 v[0:3], v[172:175], v[208:211], v[0:3]
	v_mfma_f32_16x16x32_bf16 v[56:59], v[168:171], v[184:187], v[56:59]
	v_mfma_f32_16x16x32_bf16 v[48:51], v[176:179], v[184:187], v[48:51]
	v_mfma_f32_16x16x32_bf16 v[40:43], v[168:171], v[192:195], v[40:43]
	v_mfma_f32_16x16x32_bf16 v[32:35], v[176:179], v[192:195], v[32:35]
	v_mfma_f32_16x16x32_bf16 v[24:27], v[168:171], v[200:203], v[24:27]
	v_mfma_f32_16x16x32_bf16 v[16:19], v[176:179], v[200:203], v[16:19]
	v_mfma_f32_16x16x32_bf16 v[8:11], v[168:171], v[212:215], v[8:11]
	v_mfma_f32_16x16x32_bf16 v[0:3], v[176:179], v[212:215], v[0:3]
	s_setprio 0
	s_barrier
	s_add_i32 s64, 0, 0x18000
	s_add_i32 s65, 0, 0x1c000
	v_add_u32_e32 v160, s64, v143
	v_add_u32_e32 v176, s65, v143
	ds_read_b128 v[148:151], v160
	ds_read_b128 v[152:155], v160 offset:1024
	ds_read_b128 v[156:159], v160 offset:2048
	ds_read_b128 v[160:163], v160 offset:3072
	ds_read_b128 v[164:167], v176
	ds_read_b128 v[168:171], v176 offset:1024
	ds_read_b128 v[172:175], v176 offset:2048
	ds_read_b128 v[176:179], v176 offset:3072
	s_add_u32 s46, s46, 0x40000
	s_addc_u32 s47, s47, 0
	s_mov_b32 m0, s50
	v_lshl_add_u64 v[220:221], s[46:47], 0, v[130:131]
	ds_read_b128 v[180:183], v147 offset:32768
	ds_read_b128 v[184:187], v147 offset:33792
	ds_read_b128 v[188:191], v147 offset:34816
	ds_read_b128 v[192:195], v147 offset:35840
	ds_read_b128 v[196:199], v147 offset:36864
	ds_read_b128 v[200:203], v147 offset:37888
	ds_read_b128 v[208:211], v147 offset:38912
	ds_read_b128 v[212:215], v147 offset:39936
	global_load_lds_dwordx4 v[220:221], off
	v_lshl_add_u64 v[220:221], s[46:47], 0, v[128:129]
	s_mov_b32 m0, s51
	s_nop 0
	global_load_lds_dwordx4 v[220:221], off
	s_waitcnt vmcnt(8)
	s_waitcnt lgkmcnt(0)
	s_barrier
	s_setprio 1
	s_waitcnt lgkmcnt(0)
	v_mfma_f32_16x16x32_bf16 v[124:127], v[148:151], v[180:183], v[124:127]
	v_mfma_f32_16x16x32_bf16 v[116:119], v[156:159], v[180:183], v[116:119]
	v_mfma_f32_16x16x32_bf16 v[108:111], v[148:151], v[188:191], v[108:111]
	v_mfma_f32_16x16x32_bf16 v[100:103], v[156:159], v[188:191], v[100:103]
	v_mfma_f32_16x16x32_bf16 v[92:95], v[148:151], v[196:199], v[92:95]
	v_mfma_f32_16x16x32_bf16 v[84:87], v[156:159], v[196:199], v[84:87]
	v_mfma_f32_16x16x32_bf16 v[76:79], v[148:151], v[208:211], v[76:79]
	v_mfma_f32_16x16x32_bf16 v[68:71], v[156:159], v[208:211], v[68:71]
	v_mfma_f32_16x16x32_bf16 v[124:127], v[152:155], v[184:187], v[124:127]
	v_mfma_f32_16x16x32_bf16 v[116:119], v[160:163], v[184:187], v[116:119]
	v_mfma_f32_16x16x32_bf16 v[108:111], v[152:155], v[192:195], v[108:111]
	v_mfma_f32_16x16x32_bf16 v[100:103], v[160:163], v[192:195], v[100:103]
	v_mfma_f32_16x16x32_bf16 v[92:95], v[152:155], v[200:203], v[92:95]
	v_mfma_f32_16x16x32_bf16 v[84:87], v[160:163], v[200:203], v[84:87]
	v_mfma_f32_16x16x32_bf16 v[76:79], v[152:155], v[212:215], v[76:79]
	v_mfma_f32_16x16x32_bf16 v[68:71], v[160:163], v[212:215], v[68:71]
	v_mfma_f32_16x16x32_bf16 v[120:123], v[164:167], v[180:183], v[120:123]
	v_mfma_f32_16x16x32_bf16 v[112:115], v[172:175], v[180:183], v[112:115]
	v_mfma_f32_16x16x32_bf16 v[104:107], v[164:167], v[188:191], v[104:107]
	v_mfma_f32_16x16x32_bf16 v[96:99], v[172:175], v[188:191], v[96:99]
	v_mfma_f32_16x16x32_bf16 v[88:91], v[164:167], v[196:199], v[88:91]
	v_mfma_f32_16x16x32_bf16 v[80:83], v[172:175], v[196:199], v[80:83]
	v_mfma_f32_16x16x32_bf16 v[72:75], v[164:167], v[208:211], v[72:75]
	v_mfma_f32_16x16x32_bf16 v[64:67], v[172:175], v[208:211], v[64:67]
	v_mfma_f32_16x16x32_bf16 v[120:123], v[168:171], v[184:187], v[120:123]
	v_mfma_f32_16x16x32_bf16 v[112:115], v[176:179], v[184:187], v[112:115]
	v_mfma_f32_16x16x32_bf16 v[104:107], v[168:171], v[192:195], v[104:107]
	v_mfma_f32_16x16x32_bf16 v[96:99], v[176:179], v[192:195], v[96:99]
	v_mfma_f32_16x16x32_bf16 v[88:91], v[168:171], v[200:203], v[88:91]
	v_mfma_f32_16x16x32_bf16 v[80:83], v[176:179], v[200:203], v[80:83]
	v_mfma_f32_16x16x32_bf16 v[72:75], v[168:171], v[212:215], v[72:75]
	v_mfma_f32_16x16x32_bf16 v[64:67], v[176:179], v[212:215], v[64:67]
	s_setprio 0
	s_barrier
; #define PG8_STAGE(bufoff, gbase, voff) do { _Pragma("unroll") for (int _i = 0; _i < 2; ++_i) \
;         __builtin_amdgcn_global_load_lds((const unsigned*)((const char*)(gbase) + (voff)[_i]), (LAS unsigned*)(lds + (bufoff) + ldsw + _i * 8192), 16, 0, 0); } while (0)
; #define PG8_LDA(dst, b, h) do { _Pragma("unroll") for (int m = 0; m < 4; ++m) _Pragma("unroll") for (int k = 0; k < 2; ++k) dst[m][k] = *(const LAS bf16x8*)(lds + PG8_SA(b, h) + aoff + m * 2048 + k * 1024); } while (0)
; #define PG8_WAIT_V(n) asm volatile("s_waitcnt vmcnt(" #n ")" ::: "memory")
; #define PG8_WAIT_L(n) asm volatile("s_waitcnt lgkmcnt(" #n ")" ::: "memory")
; #define PG8_BAR __builtin_amdgcn_s_barrier()
; #define PG8_SCHED __builtin_amdgcn_sched_barrier(0)
; template <class Epi, class Sched, bool SWAPD = false>
; __device__ __forceinline__ void gemm_phase(LAS unsigned char* lds, const Gemm g, const Sched& S, const Epi& E) {
;     ...
;             PG8_LDA(At, 1, 1); PG8_STAGE(PG8_SB(1, 0), b3, voffB); PG8_STAGE(PG8_SB(1, 1), b3 + hstepB, voffB); PG8_STAGE(PG8_SA(1, 0), a3, voffA);
;             PG8_WAIT_V(8); PG8_WAIT_L(0); PG8_BAR; PG8_MMA(1, 0, At, B0); PG8_MMA(1, 1, At, B1); PG8_BAR; PG8_SCHED;
;         }
	s_add_i32 s46, s64, s30
	v_lshl_add_u64 v[140:141], v[140:141], 0, s[8:9]
	s_mov_b32 m0, s46
	ds_read_b128 v[180:183], v147 offset:49152
	ds_read_b128 v[184:187], v147 offset:50176
	ds_read_b128 v[188:191], v147 offset:51200
	ds_read_b128 v[192:195], v147 offset:52224
	ds_read_b128 v[196:199], v147 offset:53248
	ds_read_b128 v[200:203], v147 offset:54272
	ds_read_b128 v[208:211], v147 offset:55296
	ds_read_b128 v[212:215], v147 offset:56320
	global_load_lds_dwordx4 v[140:141], off
	s_add_i32 m0, s46, 0x2000
	s_add_u32 s44, s44, 0x40080
	v_lshl_add_u64 v[140:141], v[204:205], 0, s[8:9]
	s_addc_u32 s45, s45, 0
	s_add_i32 s46, s65, s30
	global_load_lds_dwordx4 v[140:141], off
	v_lshl_add_u64 v[140:141], s[44:45], 0, v[130:131]
	s_mov_b32 m0, s46
	s_nop 0
	global_load_lds_dwordx4 v[140:141], off
	v_lshl_add_u64 v[140:141], s[44:45], 0, v[128:129]
	s_add_i32 m0, s46, 0x2000
	s_nop 0
	global_load_lds_dwordx4 v[140:141], off
	v_lshl_add_u64 v[140:141], v[216:217], 0, s[8:9]
	s_mov_b32 m0, s53
	s_nop 0
	global_load_lds_dwordx4 v[140:141], off
	v_lshl_add_u64 v[140:141], v[218:219], 0, s[8:9]
	s_mov_b32 m0, s54
	s_nop 0
	global_load_lds_dwordx4 v[140:141], off
	s_waitcnt vmcnt(8)
	s_waitcnt lgkmcnt(0)
	s_barrier
	s_setprio 1
	s_waitcnt lgkmcnt(0)
	v_mfma_f32_16x16x32_bf16 v[60:63], v[148:151], v[180:183], v[60:63]
	v_mfma_f32_16x16x32_bf16 v[52:55], v[156:159], v[180:183], v[52:55]
	v_mfma_f32_16x16x32_bf16 v[44:47], v[148:151], v[188:191], v[44:47]
	v_mfma_f32_16x16x32_bf16 v[36:39], v[156:159], v[188:191], v[36:39]
	v_mfma_f32_16x16x32_bf16 v[28:31], v[148:151], v[196:199], v[28:31]
	v_mfma_f32_16x16x32_bf16 v[20:23], v[156:159], v[196:199], v[20:23]
	v_mfma_f32_16x16x32_bf16 v[12:15], v[148:151], v[208:211], v[12:15]
	v_mfma_f32_16x16x32_bf16 v[4:7], v[156:159], v[208:211], v[4:7]
	v_mfma_f32_16x16x32_bf16 v[60:63], v[152:155], v[184:187], v[60:63]
	v_mfma_f32_16x16x32_bf16 v[52:55], v[160:163], v[184:187], v[52:55]
	v_mfma_f32_16x16x32_bf16 v[44:47], v[152:155], v[192:195], v[44:47]
	v_mfma_f32_16x16x32_bf16 v[36:39], v[160:163], v[192:195], v[36:39]
	v_mfma_f32_16x16x32_bf16 v[28:31], v[152:155], v[200:203], v[28:31]
	v_mfma_f32_16x16x32_bf16 v[20:23], v[160:163], v[200:203], v[20:23]
	v_mfma_f32_16x16x32_bf16 v[12:15], v[152:155], v[212:215], v[12:15]
	v_mfma_f32_16x16x32_bf16 v[4:7], v[160:163], v[212:215], v[4:7]
	v_mfma_f32_16x16x32_bf16 v[56:59], v[164:167], v[180:183], v[56:59]
	v_mfma_f32_16x16x32_bf16 v[48:51], v[172:175], v[180:183], v[48:51]
	v_mfma_f32_16x16x32_bf16 v[40:43], v[164:167], v[188:191], v[40:43]
	v_mfma_f32_16x16x32_bf16 v[32:35], v[172:175], v[188:191], v[32:35]
	v_mfma_f32_16x16x32_bf16 v[24:27], v[164:167], v[196:199], v[24:27]
	v_mfma_f32_16x16x32_bf16 v[16:19], v[172:175], v[196:199], v[16:19]
	v_mfma_f32_16x16x32_bf16 v[8:11], v[164:167], v[208:211], v[8:11]
	v_mfma_f32_16x16x32_bf16 v[0:3], v[172:175], v[208:211], v[0:3]
	v_mfma_f32_16x16x32_bf16 v[56:59], v[168:171], v[184:187], v[56:59]
	v_mfma_f32_16x16x32_bf16 v[48:51], v[176:179], v[184:187], v[48:51]
	v_mfma_f32_16x16x32_bf16 v[40:43], v[168:171], v[192:195], v[40:43]
	v_mfma_f32_16x16x32_bf16 v[32:35], v[176:179], v[192:195], v[32:35]
	v_mfma_f32_16x16x32_bf16 v[24:27], v[168:171], v[200:203], v[24:27]
	v_mfma_f32_16x16x32_bf16 v[16:19], v[176:179], v[200:203], v[16:19]
	v_mfma_f32_16x16x32_bf16 v[8:11], v[168:171], v[212:215], v[8:11]
	v_mfma_f32_16x16x32_bf16 v[0:3], v[176:179], v[212:215], v[0:3]
	s_setprio 0
	s_barrier
	s_add_i32 s63, s63, 2
	s_add_u32 s42, s42, 0x100
	s_addc_u32 s43, s43, 0
	s_add_u32 s61, s61, 0x100
	s_addc_u32 s62, s62, 0
	s_cmp_gt_u32 s63, 13
	s_cbranch_scc0 .LBB0_1044
	s_and_b64 vcc, exec, s[12:13]
	s_cbranch_vccz .LBB0_1047
	s_barrier

; #define PG8_STAGE(bufoff, gbase, voff) do { _Pragma("unroll") for (int _i = 0; _i < 2; ++_i) \
;         __builtin_amdgcn_global_load_lds((const unsigned*)((const char*)(gbase) + (voff)[_i]), (LAS unsigned*)(lds + (bufoff) + ldsw + _i * 8192), 16, 0, 0); } while (0)
; #define PG8_LDA(dst, b, h) do { _Pragma("unroll") for (int m = 0; m < 4; ++m) _Pragma("unroll") for (int k = 0; k < 2; ++k) dst[m][k] = *(const LAS bf16x8*)(lds + PG8_SA(b, h) + aoff + m * 2048 + k * 1024); } while (0)
; #define PG8_LDB(dst, b, h) do { _Pragma("unroll") for (int n = 0; n < 2; ++n) _Pragma("unroll") for (int k = 0; k < 2; ++k) dst[n][k] = *(const LAS bf16x8*)(lds + PG8_SB(b, h) + boff + n * 2048 + k * 1024); } while (0)
; #define PG8_WAIT_V(n) asm volatile("s_waitcnt vmcnt(" #n ")" ::: "memory")
; #define PG8_WAIT_L(n) asm volatile("s_waitcnt lgkmcnt(" #n ")" ::: "memory")
; #define PG8_BAR __builtin_amdgcn_s_barrier()
; #define PG8_SCHED __builtin_amdgcn_sched_barrier(0)
; template <class Epi, class Sched, bool SWAPD = false>
; __device__ __forceinline__ void gemm_phase(LAS unsigned char* lds, const Gemm g, const Sched& S, const Epi& E) {
;     ...
;             const bool last = (t == nt - 2);
;             const char* a1 = cA + (size_t)(t + 1) * kstepA;
;             const char* a2 = last ? nA : cA + (size_t)(t + 2) * kstepA; const char* b2 = last ? nB : cB + (size_t)(t + 2) * kstep;
;             const char* a3 = a2 + kstepA; const char* b3 = b2 + kstep;
;             PG8_LDB(B0, 0, 0); PG8_LDB(B1, 0, 1); PG8_SCHED; PG8_LDA(At, 0, 0); PG8_STAGE(PG8_SA(1, 1), a1 + hstepA, voffA);
;             PG8_WAIT_V(8); PG8_WAIT_L(0); PG8_BAR; PG8_MMA(0, 0, At, B0); PG8_MMA(0, 1, At, B1); PG8_BAR; PG8_SCHED;
;             PG8_LDA(At, 0, 1); PG8_STAGE(PG8_SB(0, 0), b2, voffB); PG8_STAGE(PG8_SB(0, 1), b2 + hstepB, voffB); PG8_STAGE(PG8_SA(0, 0), a2, voffA);
.LBB0_1121:
	ds_read_b128 v[128:131], v210
	ds_read_b128 v[132:135], v210 offset:1024
	ds_read_b128 v[136:139], v210 offset:2048
	ds_read_b128 v[140:143], v210 offset:3072
	ds_read_b128 v[144:147], v211
	ds_read_b128 v[148:151], v211 offset:1024
	ds_read_b128 v[152:155], v211 offset:2048
	ds_read_b128 v[156:159], v211 offset:3072
	s_add_u32 s36, s34, 0x100
	s_addc_u32 s37, s35, 0
	s_cmp_eq_u32 s64, 40
	s_cselect_b32 s41, s58, s37
	s_cselect_b32 s40, s59, s36
	s_cselect_b32 s39, s60, s63
	s_cselect_b32 s38, s61, s62
	v_lshl_add_u64 v[204:205], s[34:35], 0, v[180:181]
	s_add_i32 m0, s33, 0xc000
	ds_read_b128 v[188:191], v212
	ds_read_b128 v[192:195], v212 offset:1024
	ds_read_b128 v[196:199], v212 offset:2048
	ds_read_b128 v[200:203], v212 offset:3072
	ds_read_b128 v[214:217], v212 offset:4096
	ds_read_b128 v[218:221], v212 offset:5120
	ds_read_b128 v[222:225], v212 offset:6144
	ds_read_b128 v[226:229], v212 offset:7168
	global_load_lds_dwordx4 v[204:205], off
	v_lshl_add_u64 v[204:205], s[34:35], 0, v[182:183]
	s_add_i32 m0, s33, 0xe000
	s_nop 0
	global_load_lds_dwordx4 v[204:205], off
	s_waitcnt vmcnt(8)
	s_waitcnt lgkmcnt(0)
	s_barrier
	s_setprio 1
	s_waitcnt lgkmcnt(0)
	v_mfma_f32_16x16x32_bf16 v[124:127], v[128:131], v[188:191], v[124:127]
	v_mfma_f32_16x16x32_bf16 v[120:123], v[136:139], v[188:191], v[120:123]
	v_mfma_f32_16x16x32_bf16 v[116:119], v[128:131], v[196:199], v[116:119]
	v_mfma_f32_16x16x32_bf16 v[112:115], v[136:139], v[196:199], v[112:115]
	v_mfma_f32_16x16x32_bf16 v[92:95], v[128:131], v[214:217], v[92:95]
	v_mfma_f32_16x16x32_bf16 v[88:91], v[136:139], v[214:217], v[88:91]
	v_mfma_f32_16x16x32_bf16 v[76:79], v[128:131], v[222:225], v[76:79]
	v_mfma_f32_16x16x32_bf16 v[72:75], v[136:139], v[222:225], v[72:75]
	v_mfma_f32_16x16x32_bf16 v[124:127], v[132:135], v[192:195], v[124:127]
	v_mfma_f32_16x16x32_bf16 v[120:123], v[140:143], v[192:195], v[120:123]
	v_mfma_f32_16x16x32_bf16 v[116:119], v[132:135], v[200:203], v[116:119]
	v_mfma_f32_16x16x32_bf16 v[112:115], v[140:143], v[200:203], v[112:115]
	v_mfma_f32_16x16x32_bf16 v[92:95], v[132:135], v[218:221], v[92:95]
	v_mfma_f32_16x16x32_bf16 v[88:91], v[140:143], v[218:221], v[88:91]
	v_mfma_f32_16x16x32_bf16 v[76:79], v[132:135], v[226:229], v[76:79]
	v_mfma_f32_16x16x32_bf16 v[72:75], v[140:143], v[226:229], v[72:75]
	v_mfma_f32_16x16x32_bf16 v[108:111], v[144:147], v[188:191], v[108:111]
	v_mfma_f32_16x16x32_bf16 v[104:107], v[152:155], v[188:191], v[104:107]
	v_mfma_f32_16x16x32_bf16 v[100:103], v[144:147], v[196:199], v[100:103]
	v_mfma_f32_16x16x32_bf16 v[96:99], v[152:155], v[196:199], v[96:99]
	v_mfma_f32_16x16x32_bf16 v[84:87], v[144:147], v[214:217], v[84:87]
	v_mfma_f32_16x16x32_bf16 v[80:83], v[152:155], v[214:217], v[80:83]
	v_mfma_f32_16x16x32_bf16 v[68:71], v[144:147], v[222:225], v[68:71]
	v_mfma_f32_16x16x32_bf16 v[64:67], v[152:155], v[222:225], v[64:67]
	v_mfma_f32_16x16x32_bf16 v[108:111], v[148:151], v[192:195], v[108:111]
	v_mfma_f32_16x16x32_bf16 v[104:107], v[156:159], v[192:195], v[104:107]
	v_mfma_f32_16x16x32_bf16 v[100:103], v[148:151], v[200:203], v[100:103]
	v_mfma_f32_16x16x32_bf16 v[96:99], v[156:159], v[200:203], v[96:99]
	v_mfma_f32_16x16x32_bf16 v[84:87], v[148:151], v[218:221], v[84:87]
	v_mfma_f32_16x16x32_bf16 v[80:83], v[156:159], v[218:221], v[80:83]
	v_mfma_f32_16x16x32_bf16 v[68:71], v[148:151], v[226:229], v[68:71]
	v_mfma_f32_16x16x32_bf16 v[64:67], v[156:159], v[226:229], v[64:67]
	s_setprio 0
	s_barrier
	s_add_i32 s34, s52, s31
	v_lshl_add_u64 v[204:205], s[38:39], 0, v[160:161]
	s_mov_b32 m0, s34
	ds_read_b128 v[188:191], v212 offset:16384
	ds_read_b128 v[192:195], v212 offset:17408
	ds_read_b128 v[196:199], v212 offset:18432
	ds_read_b128 v[200:203], v212 offset:19456
	ds_read_b128 v[214:217], v212 offset:20480
	ds_read_b128 v[218:221], v212 offset:21504
	ds_read_b128 v[222:225], v212 offset:22528
	ds_read_b128 v[226:229], v212 offset:23552
	global_load_lds_dwordx4 v[204:205], off
	s_add_i32 m0, s34, 0x2000
	s_add_u32 s34, s38, 0xb0000
	v_lshl_add_u64 v[230:231], s[38:39], 0, v[162:163]
	s_addc_u32 s35, s39, 0
	s_add_i32 s65, s53, s31
	global_load_lds_dwordx4 v[230:231], off
	v_lshl_add_u64 v[232:233], s[34:35], 0, v[160:161]
	s_mov_b32 m0, s65
	v_lshl_add_u64 v[234:235], s[40:41], 0, v[162:163]
	global_load_lds_dwordx4 v[232:233], off
	v_lshl_add_u64 v[232:233], s[34:35], 0, v[162:163]
	s_add_i32 m0, s65, 0x2000
	s_nop 0
	global_load_lds_dwordx4 v[232:233], off
	v_lshl_add_u64 v[232:233], s[40:41], 0, v[160:161]
	s_mov_b32 m0, s33
	s_nop 0
	global_load_lds_dwordx4 v[232:233], off
	s_mov_b32 m0, s42
	s_nop 0
	global_load_lds_dwordx4 v[234:235], off
	s_waitcnt vmcnt(8)
	s_waitcnt lgkmcnt(0)
	s_barrier
; #define PG8_STAGE(bufoff, gbase, voff) do { _Pragma("unroll") for (int _i = 0; _i < 2; ++_i) \
;         __builtin_amdgcn_global_load_lds((const unsigned*)((const char*)(gbase) + (voff)[_i]), (LAS unsigned*)(lds + (bufoff) + ldsw + _i * 8192), 16, 0, 0); } while (0)
; #define PG8_LDA(dst, b, h) do { _Pragma("unroll") for (int m = 0; m < 4; ++m) _Pragma("unroll") for (int k = 0; k < 2; ++k) dst[m][k] = *(const LAS bf16x8*)(lds + PG8_SA(b, h) + aoff + m * 2048 + k * 1024); } while (0)
; #define PG8_LDB(dst, b, h) do { _Pragma("unroll") for (int n = 0; n < 2; ++n) _Pragma("unroll") for (int k = 0; k < 2; ++k) dst[n][k] = *(const LAS bf16x8*)(lds + PG8_SB(b, h) + boff + n * 2048 + k * 1024); } while (0)
; #define PG8_WAIT_V(n) asm volatile("s_waitcnt vmcnt(" #n ")" ::: "memory")
; #define PG8_WAIT_L(n) asm volatile("s_waitcnt lgkmcnt(" #n ")" ::: "memory")
; #define PG8_BAR __builtin_amdgcn_s_barrier()
; #define PG8_SCHED __builtin_amdgcn_sched_barrier(0)
; template <class Epi, class Sched, bool SWAPD = false>
; __device__ __forceinline__ void gemm_phase(LAS unsigned char* lds, const Gemm g, const Sched& S, const Epi& E) {
;     ...
;             PG8_WAIT_V(8); PG8_WAIT_L(0); PG8_BAR; PG8_MMA(1, 0, At, B0); PG8_MMA(1, 1, At, B1); PG8_BAR; PG8_SCHED;
;             PG8_LDB(B0, 1, 0); PG8_LDB(B1, 1, 1); PG8_SCHED; PG8_LDA(At, 1, 0); PG8_STAGE(PG8_SA(0, 1), a2 + hstepA, voffA);
;             PG8_WAIT_V(8); PG8_WAIT_L(0); PG8_BAR; PG8_MMA(0, 0, At, B0); PG8_MMA(0, 1, At, B1); PG8_BAR; PG8_SCHED;
	s_setprio 1
	s_waitcnt lgkmcnt(0)
	v_mfma_f32_16x16x32_bf16 v[60:63], v[128:131], v[188:191], v[60:63]
	v_mfma_f32_16x16x32_bf16 v[56:59], v[136:139], v[188:191], v[56:59]
	v_mfma_f32_16x16x32_bf16 v[44:47], v[128:131], v[196:199], v[44:47]
	v_mfma_f32_16x16x32_bf16 v[40:43], v[136:139], v[196:199], v[40:43]
	v_mfma_f32_16x16x32_bf16 v[36:39], v[128:131], v[214:217], v[36:39]
	v_mfma_f32_16x16x32_bf16 v[32:35], v[136:139], v[214:217], v[32:35]
	v_mfma_f32_16x16x32_bf16 v[20:23], v[128:131], v[222:225], v[20:23]
	v_mfma_f32_16x16x32_bf16 v[16:19], v[136:139], v[222:225], v[16:19]
	v_mfma_f32_16x16x32_bf16 v[60:63], v[132:135], v[192:195], v[60:63]
	v_mfma_f32_16x16x32_bf16 v[56:59], v[140:143], v[192:195], v[56:59]
	v_mfma_f32_16x16x32_bf16 v[44:47], v[132:135], v[200:203], v[44:47]
	v_mfma_f32_16x16x32_bf16 v[40:43], v[140:143], v[200:203], v[40:43]
	v_mfma_f32_16x16x32_bf16 v[36:39], v[132:135], v[218:221], v[36:39]
	v_mfma_f32_16x16x32_bf16 v[32:35], v[140:143], v[218:221], v[32:35]
	v_mfma_f32_16x16x32_bf16 v[20:23], v[132:135], v[226:229], v[20:23]
	v_mfma_f32_16x16x32_bf16 v[16:19], v[140:143], v[226:229], v[16:19]
	v_mfma_f32_16x16x32_bf16 v[52:55], v[144:147], v[188:191], v[52:55]
	v_mfma_f32_16x16x32_bf16 v[48:51], v[152:155], v[188:191], v[48:51]
	v_mfma_f32_16x16x32_bf16 v[28:31], v[144:147], v[196:199], v[28:31]
	v_mfma_f32_16x16x32_bf16 v[24:27], v[152:155], v[196:199], v[24:27]
	v_mfma_f32_16x16x32_bf16 v[12:15], v[144:147], v[214:217], v[12:15]
	v_mfma_f32_16x16x32_bf16 v[8:11], v[152:155], v[214:217], v[8:11]
	v_mfma_f32_16x16x32_bf16 v[4:7], v[144:147], v[222:225], v[4:7]
	v_mfma_f32_16x16x32_bf16 v[0:3], v[152:155], v[222:225], v[0:3]
	v_mfma_f32_16x16x32_bf16 v[52:55], v[148:151], v[192:195], v[52:55]
	v_mfma_f32_16x16x32_bf16 v[48:51], v[156:159], v[192:195], v[48:51]
	v_mfma_f32_16x16x32_bf16 v[28:31], v[148:151], v[200:203], v[28:31]
	v_mfma_f32_16x16x32_bf16 v[24:27], v[156:159], v[200:203], v[24:27]
	v_mfma_f32_16x16x32_bf16 v[12:15], v[148:151], v[218:221], v[12:15]
	v_mfma_f32_16x16x32_bf16 v[8:11], v[156:159], v[218:221], v[8:11]
	v_mfma_f32_16x16x32_bf16 v[4:7], v[148:151], v[226:229], v[4:7]
	v_mfma_f32_16x16x32_bf16 v[0:3], v[156:159], v[226:229], v[0:3]
	s_setprio 0
	s_barrier
	s_add_i32 s65, 0, 0x18000
	s_add_i32 s66, 0, 0x1c000
	v_add_u32_e32 v140, s65, v208
	v_add_u32_e32 v156, s66, v208
	ds_read_b128 v[128:131], v140
	ds_read_b128 v[132:135], v140 offset:1024
	ds_read_b128 v[136:139], v140 offset:2048
	ds_read_b128 v[140:143], v140 offset:3072
	ds_read_b128 v[144:147], v156
	ds_read_b128 v[148:151], v156 offset:1024
	ds_read_b128 v[152:155], v156 offset:2048
	ds_read_b128 v[156:159], v156 offset:3072
	s_add_u32 s34, s40, 0xb0000
	s_addc_u32 s35, s41, 0
	s_mov_b32 m0, s43
	v_lshl_add_u64 v[236:237], s[34:35], 0, v[160:161]
	ds_read_b128 v[188:191], v212 offset:32768
	ds_read_b128 v[192:195], v212 offset:33792
	ds_read_b128 v[196:199], v212 offset:34816
	ds_read_b128 v[200:203], v212 offset:35840
	ds_read_b128 v[214:217], v212 offset:36864
	ds_read_b128 v[218:221], v212 offset:37888
	ds_read_b128 v[222:225], v212 offset:38912
	ds_read_b128 v[226:229], v212 offset:39936
	global_load_lds_dwordx4 v[236:237], off
	v_lshl_add_u64 v[236:237], s[34:35], 0, v[162:163]
	s_mov_b32 m0, s44
	s_nop 0
	global_load_lds_dwordx4 v[236:237], off
	s_waitcnt vmcnt(8)
	s_waitcnt lgkmcnt(0)
	s_barrier
	s_setprio 1
	s_waitcnt lgkmcnt(0)
	v_mfma_f32_16x16x32_bf16 v[124:127], v[128:131], v[188:191], v[124:127]
	v_mfma_f32_16x16x32_bf16 v[120:123], v[136:139], v[188:191], v[120:123]
	v_mfma_f32_16x16x32_bf16 v[116:119], v[128:131], v[196:199], v[116:119]
	v_mfma_f32_16x16x32_bf16 v[112:115], v[136:139], v[196:199], v[112:115]
	v_mfma_f32_16x16x32_bf16 v[92:95], v[128:131], v[214:217], v[92:95]
	v_mfma_f32_16x16x32_bf16 v[88:91], v[136:139], v[214:217], v[88:91]
	v_mfma_f32_16x16x32_bf16 v[76:79], v[128:131], v[222:225], v[76:79]
	v_mfma_f32_16x16x32_bf16 v[72:75], v[136:139], v[222:225], v[72:75]
	v_mfma_f32_16x16x32_bf16 v[124:127], v[132:135], v[192:195], v[124:127]
	v_mfma_f32_16x16x32_bf16 v[120:123], v[140:143], v[192:195], v[120:123]
	v_mfma_f32_16x16x32_bf16 v[116:119], v[132:135], v[200:203], v[116:119]
	v_mfma_f32_16x16x32_bf16 v[112:115], v[140:143], v[200:203], v[112:115]
	v_mfma_f32_16x16x32_bf16 v[92:95], v[132:135], v[218:221], v[92:95]
	v_mfma_f32_16x16x32_bf16 v[88:91], v[140:143], v[218:221], v[88:91]
	v_mfma_f32_16x16x32_bf16 v[76:79], v[132:135], v[226:229], v[76:79]
	v_mfma_f32_16x16x32_bf16 v[72:75], v[140:143], v[226:229], v[72:75]
	v_mfma_f32_16x16x32_bf16 v[108:111], v[144:147], v[188:191], v[108:111]
	v_mfma_f32_16x16x32_bf16 v[104:107], v[152:155], v[188:191], v[104:107]
	v_mfma_f32_16x16x32_bf16 v[100:103], v[144:147], v[196:199], v[100:103]
	v_mfma_f32_16x16x32_bf16 v[96:99], v[152:155], v[196:199], v[96:99]
	v_mfma_f32_16x16x32_bf16 v[84:87], v[144:147], v[214:217], v[84:87]
	v_mfma_f32_16x16x32_bf16 v[80:83], v[152:155], v[214:217], v[80:83]
	v_mfma_f32_16x16x32_bf16 v[68:71], v[144:147], v[222:225], v[68:71]
	v_mfma_f32_16x16x32_bf16 v[64:67], v[152:155], v[222:225], v[64:67]
	v_mfma_f32_16x16x32_bf16 v[108:111], v[148:151], v[192:195], v[108:111]
	v_mfma_f32_16x16x32_bf16 v[104:107], v[156:159], v[192:195], v[104:107]
	v_mfma_f32_16x16x32_bf16 v[100:103], v[148:151], v[200:203], v[100:103]
	v_mfma_f32_16x16x32_bf16 v[96:99], v[156:159], v[200:203], v[96:99]
	v_mfma_f32_16x16x32_bf16 v[84:87], v[148:151], v[218:221], v[84:87]
	v_mfma_f32_16x16x32_bf16 v[80:83], v[156:159], v[218:221], v[80:83]
	v_mfma_f32_16x16x32_bf16 v[68:71], v[148:151], v[226:229], v[68:71]
	v_mfma_f32_16x16x32_bf16 v[64:67], v[156:159], v[226:229], v[64:67]
	s_setprio 0
	s_barrier
; #define PG8_STAGE(bufoff, gbase, voff) do { _Pragma("unroll") for (int _i = 0; _i < 2; ++_i) \
;         __builtin_amdgcn_global_load_lds((const unsigned*)((const char*)(gbase) + (voff)[_i]), (LAS unsigned*)(lds + (bufoff) + ldsw + _i * 8192), 16, 0, 0); } while (0)
; #define PG8_LDA(dst, b, h) do { _Pragma("unroll") for (int m = 0; m < 4; ++m) _Pragma("unroll") for (int k = 0; k < 2; ++k) dst[m][k] = *(const LAS bf16x8*)(lds + PG8_SA(b, h) + aoff + m * 2048 + k * 1024); } while (0)
; #define PG8_WAIT_V(n) asm volatile("s_waitcnt vmcnt(" #n ")" ::: "memory")
; #define PG8_WAIT_L(n) asm volatile("s_waitcnt lgkmcnt(" #n ")" ::: "memory")
; #define PG8_BAR __builtin_amdgcn_s_barrier()
; #define PG8_SCHED __builtin_amdgcn_sched_barrier(0)
; template <class Epi, class Sched, bool SWAPD = false>
; __device__ __forceinline__ void gemm_phase(LAS unsigned char* lds, const Gemm g, const Sched& S, const Epi& E) {
;     ...
;             PG8_LDA(At, 1, 1); PG8_STAGE(PG8_SB(1, 0), b3, voffB); PG8_STAGE(PG8_SB(1, 1), b3 + hstepB, voffB); PG8_STAGE(PG8_SA(1, 0), a3, voffA);
;             PG8_WAIT_V(8); PG8_WAIT_L(0); PG8_BAR; PG8_MMA(1, 0, At, B0); PG8_MMA(1, 1, At, B1); PG8_BAR; PG8_SCHED;
;         }
	s_add_i32 s34, s65, s31
	v_lshl_add_u64 v[204:205], v[204:205], 0, s[8:9]
	s_mov_b32 m0, s34
	ds_read_b128 v[188:191], v212 offset:49152
	ds_read_b128 v[192:195], v212 offset:50176
	ds_read_b128 v[196:199], v212 offset:51200
	ds_read_b128 v[200:203], v212 offset:52224
	ds_read_b128 v[214:217], v212 offset:53248
	ds_read_b128 v[218:221], v212 offset:54272
	ds_read_b128 v[222:225], v212 offset:55296
	ds_read_b128 v[226:229], v212 offset:56320
	global_load_lds_dwordx4 v[204:205], off
	s_add_i32 m0, s34, 0x2000
	s_add_u32 s34, s38, 0xb0080
	v_lshl_add_u64 v[204:205], v[230:231], 0, s[8:9]
	s_addc_u32 s35, s39, 0
	s_add_i32 s38, s66, s31
	global_load_lds_dwordx4 v[204:205], off
	v_lshl_add_u64 v[204:205], s[34:35], 0, v[160:161]
	s_mov_b32 m0, s38
	s_nop 0
	global_load_lds_dwordx4 v[204:205], off
	v_lshl_add_u64 v[204:205], s[34:35], 0, v[162:163]
	s_add_i32 m0, s38, 0x2000
	s_nop 0
	global_load_lds_dwordx4 v[204:205], off
	v_lshl_add_u64 v[204:205], v[232:233], 0, s[8:9]
	s_mov_b32 m0, s50
	s_nop 0
	global_load_lds_dwordx4 v[204:205], off
	v_lshl_add_u64 v[204:205], v[234:235], 0, s[8:9]
	s_mov_b32 m0, s51
	s_nop 0
	global_load_lds_dwordx4 v[204:205], off
	s_waitcnt vmcnt(8)
	s_waitcnt lgkmcnt(0)
	s_barrier
	s_setprio 1
	s_waitcnt lgkmcnt(0)
	v_mfma_f32_16x16x32_bf16 v[60:63], v[128:131], v[188:191], v[60:63]
	v_mfma_f32_16x16x32_bf16 v[56:59], v[136:139], v[188:191], v[56:59]
	v_mfma_f32_16x16x32_bf16 v[44:47], v[128:131], v[196:199], v[44:47]
	v_mfma_f32_16x16x32_bf16 v[40:43], v[136:139], v[196:199], v[40:43]
	v_mfma_f32_16x16x32_bf16 v[36:39], v[128:131], v[214:217], v[36:39]
	v_mfma_f32_16x16x32_bf16 v[32:35], v[136:139], v[214:217], v[32:35]
	v_mfma_f32_16x16x32_bf16 v[20:23], v[128:131], v[222:225], v[20:23]
	v_mfma_f32_16x16x32_bf16 v[16:19], v[136:139], v[222:225], v[16:19]
	v_mfma_f32_16x16x32_bf16 v[60:63], v[132:135], v[192:195], v[60:63]
	v_mfma_f32_16x16x32_bf16 v[56:59], v[140:143], v[192:195], v[56:59]
	v_mfma_f32_16x16x32_bf16 v[44:47], v[132:135], v[200:203], v[44:47]
	v_mfma_f32_16x16x32_bf16 v[40:43], v[140:143], v[200:203], v[40:43]
	v_mfma_f32_16x16x32_bf16 v[36:39], v[132:135], v[218:221], v[36:39]
	v_mfma_f32_16x16x32_bf16 v[32:35], v[140:143], v[218:221], v[32:35]
	v_mfma_f32_16x16x32_bf16 v[20:23], v[132:135], v[226:229], v[20:23]
	v_mfma_f32_16x16x32_bf16 v[16:19], v[140:143], v[226:229], v[16:19]
	v_mfma_f32_16x16x32_bf16 v[52:55], v[144:147], v[188:191], v[52:55]
	v_mfma_f32_16x16x32_bf16 v[48:51], v[152:155], v[188:191], v[48:51]
	v_mfma_f32_16x16x32_bf16 v[28:31], v[144:147], v[196:199], v[28:31]
	v_mfma_f32_16x16x32_bf16 v[24:27], v[152:155], v[196:199], v[24:27]
	v_mfma_f32_16x16x32_bf16 v[12:15], v[144:147], v[214:217], v[12:15]
	v_mfma_f32_16x16x32_bf16 v[8:11], v[152:155], v[214:217], v[8:11]
	v_mfma_f32_16x16x32_bf16 v[4:7], v[144:147], v[222:225], v[4:7]
	v_mfma_f32_16x16x32_bf16 v[0:3], v[152:155], v[222:225], v[0:3]
	v_mfma_f32_16x16x32_bf16 v[52:55], v[148:151], v[192:195], v[52:55]
	v_mfma_f32_16x16x32_bf16 v[48:51], v[156:159], v[192:195], v[48:51]
	v_mfma_f32_16x16x32_bf16 v[28:31], v[148:151], v[200:203], v[28:31]
	v_mfma_f32_16x16x32_bf16 v[24:27], v[156:159], v[200:203], v[24:27]
	v_mfma_f32_16x16x32_bf16 v[12:15], v[148:151], v[218:221], v[12:15]
	v_mfma_f32_16x16x32_bf16 v[8:11], v[156:159], v[218:221], v[8:11]
	v_mfma_f32_16x16x32_bf16 v[4:7], v[148:151], v[226:229], v[4:7]
	v_mfma_f32_16x16x32_bf16 v[0:3], v[156:159], v[226:229], v[0:3]
	s_setprio 0
	s_barrier
	s_add_i32 s64, s64, 2
	s_add_u32 s62, s62, 0x100
	s_addc_u32 s63, s63, 0
	s_cmp_gt_u32 s64, 41
	s_mov_b64 s[34:35], s[36:37]
	s_cbranch_scc0 .LBB0_1121
	s_and_b64 vcc, exec, s[12:13]
	s_cbranch_vccz .LBB0_1124
	s_barrier

; #define PG8_STAGE(bufoff, gbase, voff) do { _Pragma("unroll") for (int _i = 0; _i < 2; ++_i) \
;         __builtin_amdgcn_global_load_lds((const unsigned*)((const char*)(gbase) + (voff)[_i]), (LAS unsigned*)(lds + (bufoff) + ldsw + _i * 8192), 16, 0, 0); } while (0)
; #define PG8_LDA(dst, b, h) do { _Pragma("unroll") for (int m = 0; m < 4; ++m) _Pragma("unroll") for (int k = 0; k < 2; ++k) dst[m][k] = *(const LAS bf16x8*)(lds + PG8_SA(b, h) + aoff + m * 2048 + k * 1024); } while (0)
; #define PG8_LDB(dst, b, h) do { _Pragma("unroll") for (int n = 0; n < 2; ++n) _Pragma("unroll") for (int k = 0; k < 2; ++k) dst[n][k] = *(const LAS bf16x8*)(lds + PG8_SB(b, h) + boff + n * 2048 + k * 1024); } while (0)
; #define PG8_WAIT_V(n) asm volatile("s_waitcnt vmcnt(" #n ")" ::: "memory")
; #define PG8_WAIT_L(n) asm volatile("s_waitcnt lgkmcnt(" #n ")" ::: "memory")
; #define PG8_BAR __builtin_amdgcn_s_barrier()
; #define PG8_SCHED __builtin_amdgcn_sched_barrier(0)
; template <class Epi, class Sched, bool SWAPD = false>
; __device__ __forceinline__ void gemm_phase(LAS unsigned char* lds, const Gemm g, const Sched& S, const Epi& E) {
;     ...
;             const bool last = (t == nt - 2);
;             const char* a1 = cA + (size_t)(t + 1) * kstepA;
;             const char* a2 = last ? nA : cA + (size_t)(t + 2) * kstepA; const char* b2 = last ? nB : cB + (size_t)(t + 2) * kstep;
;             const char* a3 = a2 + kstepA; const char* b3 = b2 + kstep;
;             PG8_LDB(B0, 0, 0); PG8_LDB(B1, 0, 1); PG8_SCHED; PG8_LDA(At, 0, 0); PG8_STAGE(PG8_SA(1, 1), a1 + hstepA, voffA);
;             PG8_WAIT_V(8); PG8_WAIT_L(0); PG8_BAR; PG8_MMA(0, 0, At, B0); PG8_MMA(0, 1, At, B1); PG8_BAR; PG8_SCHED;
;             PG8_LDA(At, 0, 1); PG8_STAGE(PG8_SB(0, 0), b2, voffB); PG8_STAGE(PG8_SB(0, 1), b2 + hstepB, voffB); PG8_STAGE(PG8_SA(0, 0), a2, voffA);
.LBB0_1531:
	ds_read_b128 v[142:145], v151
	ds_read_b128 v[154:157], v151 offset:1024
	ds_read_b128 v[158:161], v151 offset:2048
	ds_read_b128 v[162:165], v151 offset:3072
	ds_read_b128 v[166:169], v152
	ds_read_b128 v[170:173], v152 offset:1024
	ds_read_b128 v[174:177], v152 offset:2048
	ds_read_b128 v[178:181], v152 offset:3072
	s_add_u32 s42, s40, 0xfffe0080
	s_addc_u32 s43, s41, -1
	s_cmp_eq_u32 s61, 4
	s_cselect_b32 s45, s9, s43
	s_cselect_b32 s44, s25, s42
	s_cselect_b32 s43, s27, s60
	s_cselect_b32 s42, s58, s59
	v_lshl_add_u64 v[216:217], s[40:41], 0, v[134:135]
	s_add_i32 m0, s33, 0xc000
	ds_read_b128 v[182:185], v153
	ds_read_b128 v[186:189], v153 offset:1024
	ds_read_b128 v[190:193], v153 offset:2048
	ds_read_b128 v[194:197], v153 offset:3072
	ds_read_b128 v[198:201], v153 offset:4096
	ds_read_b128 v[202:205], v153 offset:5120
	ds_read_b128 v[208:211], v153 offset:6144
	ds_read_b128 v[212:215], v153 offset:7168
	global_load_lds_dwordx4 v[216:217], off
	v_lshl_add_u64 v[216:217], s[40:41], 0, v[136:137]
	s_add_i32 m0, s33, 0xe000
	s_nop 0
	global_load_lds_dwordx4 v[216:217], off
	s_waitcnt vmcnt(8)
	s_waitcnt lgkmcnt(0)
	s_barrier
	s_setprio 1
	s_waitcnt lgkmcnt(0)
	v_mfma_f32_16x16x32_bf16 v[124:127], v[182:185], v[142:145], v[124:127]
	v_mfma_f32_16x16x32_bf16 v[120:123], v[182:185], v[158:161], v[120:123]
	v_mfma_f32_16x16x32_bf16 v[108:111], v[190:193], v[142:145], v[108:111]
	v_mfma_f32_16x16x32_bf16 v[104:107], v[190:193], v[158:161], v[104:107]
	v_mfma_f32_16x16x32_bf16 v[96:99], v[198:201], v[142:145], v[96:99]
	v_mfma_f32_16x16x32_bf16 v[88:91], v[198:201], v[158:161], v[88:91]
	v_mfma_f32_16x16x32_bf16 v[80:83], v[208:211], v[142:145], v[80:83]
	v_mfma_f32_16x16x32_bf16 v[72:75], v[208:211], v[158:161], v[72:75]
	v_mfma_f32_16x16x32_bf16 v[124:127], v[186:189], v[154:157], v[124:127]
	v_mfma_f32_16x16x32_bf16 v[120:123], v[186:189], v[162:165], v[120:123]
	v_mfma_f32_16x16x32_bf16 v[108:111], v[194:197], v[154:157], v[108:111]
	v_mfma_f32_16x16x32_bf16 v[104:107], v[194:197], v[162:165], v[104:107]
	v_mfma_f32_16x16x32_bf16 v[96:99], v[202:205], v[154:157], v[96:99]
	v_mfma_f32_16x16x32_bf16 v[88:91], v[202:205], v[162:165], v[88:91]
	v_mfma_f32_16x16x32_bf16 v[80:83], v[212:215], v[154:157], v[80:83]
	v_mfma_f32_16x16x32_bf16 v[72:75], v[212:215], v[162:165], v[72:75]
	v_mfma_f32_16x16x32_bf16 v[116:119], v[182:185], v[166:169], v[116:119]
	v_mfma_f32_16x16x32_bf16 v[112:115], v[182:185], v[174:177], v[112:115]
	v_mfma_f32_16x16x32_bf16 v[100:103], v[190:193], v[166:169], v[100:103]
	v_mfma_f32_16x16x32_bf16 v[92:95], v[190:193], v[174:177], v[92:95]
	v_mfma_f32_16x16x32_bf16 v[84:87], v[198:201], v[166:169], v[84:87]
	v_mfma_f32_16x16x32_bf16 v[76:79], v[198:201], v[174:177], v[76:79]
	v_mfma_f32_16x16x32_bf16 v[68:71], v[208:211], v[166:169], v[68:71]
	v_mfma_f32_16x16x32_bf16 v[64:67], v[208:211], v[174:177], v[64:67]
	v_mfma_f32_16x16x32_bf16 v[116:119], v[186:189], v[170:173], v[116:119]
	v_mfma_f32_16x16x32_bf16 v[112:115], v[186:189], v[178:181], v[112:115]
	v_mfma_f32_16x16x32_bf16 v[100:103], v[194:197], v[170:173], v[100:103]
	v_mfma_f32_16x16x32_bf16 v[92:95], v[194:197], v[178:181], v[92:95]
	v_mfma_f32_16x16x32_bf16 v[84:87], v[202:205], v[170:173], v[84:87]
	v_mfma_f32_16x16x32_bf16 v[76:79], v[202:205], v[178:181], v[76:79]
	v_mfma_f32_16x16x32_bf16 v[68:71], v[212:215], v[170:173], v[68:71]
	v_mfma_f32_16x16x32_bf16 v[64:67], v[212:215], v[178:181], v[64:67]
	s_setprio 0
	s_barrier
	s_add_i32 s62, s55, s21
	v_lshl_add_u64 v[216:217], s[42:43], 0, v[128:129]
	s_mov_b32 m0, s62
	ds_read_b128 v[182:185], v153 offset:16384
	ds_read_b128 v[186:189], v153 offset:17408
	ds_read_b128 v[190:193], v153 offset:18432
	ds_read_b128 v[194:197], v153 offset:19456
	ds_read_b128 v[198:201], v153 offset:20480
	ds_read_b128 v[202:205], v153 offset:21504
	ds_read_b128 v[208:211], v153 offset:22528
	ds_read_b128 v[212:215], v153 offset:23552
	global_load_lds_dwordx4 v[216:217], off
	s_add_i32 m0, s62, 0x2000
	s_add_u32 s62, s42, 0x20000
	v_lshl_add_u64 v[218:219], s[42:43], 0, v[130:131]
	s_addc_u32 s63, s43, 0
	s_add_i32 s64, s56, s21
	global_load_lds_dwordx4 v[218:219], off
	v_lshl_add_u64 v[220:221], s[62:63], 0, v[128:129]
	s_mov_b32 m0, s64
	v_lshl_add_u64 v[222:223], s[44:45], 0, v[130:131]
	global_load_lds_dwordx4 v[220:221], off
	v_lshl_add_u64 v[220:221], s[62:63], 0, v[130:131]
	s_add_i32 m0, s64, 0x2000
	s_nop 0
	global_load_lds_dwordx4 v[220:221], off
	v_lshl_add_u64 v[220:221], s[44:45], 0, v[128:129]
	s_mov_b32 m0, s33
	s_nop 0
	global_load_lds_dwordx4 v[220:221], off
	s_mov_b32 m0, s46
	s_nop 0
	global_load_lds_dwordx4 v[222:223], off
	s_waitcnt vmcnt(8)
	s_waitcnt lgkmcnt(0)
	s_barrier
; #define PG8_STAGE(bufoff, gbase, voff) do { _Pragma("unroll") for (int _i = 0; _i < 2; ++_i) \
;         __builtin_amdgcn_global_load_lds((const unsigned*)((const char*)(gbase) + (voff)[_i]), (LAS unsigned*)(lds + (bufoff) + ldsw + _i * 8192), 16, 0, 0); } while (0)
; #define PG8_LDA(dst, b, h) do { _Pragma("unroll") for (int m = 0; m < 4; ++m) _Pragma("unroll") for (int k = 0; k < 2; ++k) dst[m][k] = *(const LAS bf16x8*)(lds + PG8_SA(b, h) + aoff + m * 2048 + k * 1024); } while (0)
; #define PG8_LDB(dst, b, h) do { _Pragma("unroll") for (int n = 0; n < 2; ++n) _Pragma("unroll") for (int k = 0; k < 2; ++k) dst[n][k] = *(const LAS bf16x8*)(lds + PG8_SB(b, h) + boff + n * 2048 + k * 1024); } while (0)
; #define PG8_WAIT_V(n) asm volatile("s_waitcnt vmcnt(" #n ")" ::: "memory")
; #define PG8_WAIT_L(n) asm volatile("s_waitcnt lgkmcnt(" #n ")" ::: "memory")
; #define PG8_BAR __builtin_amdgcn_s_barrier()
; #define PG8_SCHED __builtin_amdgcn_sched_barrier(0)
; template <class Epi, class Sched, bool SWAPD = false>
; __device__ __forceinline__ void gemm_phase(LAS unsigned char* lds, const Gemm g, const Sched& S, const Epi& E) {
;     ...
;             PG8_WAIT_V(8); PG8_WAIT_L(0); PG8_BAR; PG8_MMA(1, 0, At, B0); PG8_MMA(1, 1, At, B1); PG8_BAR; PG8_SCHED;
;             PG8_LDB(B0, 1, 0); PG8_LDB(B1, 1, 1); PG8_SCHED; PG8_LDA(At, 1, 0); PG8_STAGE(PG8_SA(0, 1), a2 + hstepA, voffA);
;             PG8_WAIT_V(8); PG8_WAIT_L(0); PG8_BAR; PG8_MMA(0, 0, At, B0); PG8_MMA(0, 1, At, B1); PG8_BAR; PG8_SCHED;
	s_setprio 1
	s_waitcnt lgkmcnt(0)
	v_mfma_f32_16x16x32_bf16 v[60:63], v[182:185], v[142:145], v[60:63]
	v_mfma_f32_16x16x32_bf16 v[56:59], v[182:185], v[158:161], v[56:59]
	v_mfma_f32_16x16x32_bf16 v[48:51], v[190:193], v[142:145], v[48:51]
	v_mfma_f32_16x16x32_bf16 v[40:43], v[190:193], v[158:161], v[40:43]
	v_mfma_f32_16x16x32_bf16 v[32:35], v[198:201], v[142:145], v[32:35]
	v_mfma_f32_16x16x32_bf16 v[24:27], v[198:201], v[158:161], v[24:27]
	v_mfma_f32_16x16x32_bf16 v[16:19], v[208:211], v[142:145], v[16:19]
	v_mfma_f32_16x16x32_bf16 v[8:11], v[208:211], v[158:161], v[8:11]
	v_mfma_f32_16x16x32_bf16 v[60:63], v[186:189], v[154:157], v[60:63]
	v_mfma_f32_16x16x32_bf16 v[56:59], v[186:189], v[162:165], v[56:59]
	v_mfma_f32_16x16x32_bf16 v[48:51], v[194:197], v[154:157], v[48:51]
	v_mfma_f32_16x16x32_bf16 v[40:43], v[194:197], v[162:165], v[40:43]
	v_mfma_f32_16x16x32_bf16 v[32:35], v[202:205], v[154:157], v[32:35]
	v_mfma_f32_16x16x32_bf16 v[24:27], v[202:205], v[162:165], v[24:27]
	v_mfma_f32_16x16x32_bf16 v[16:19], v[212:215], v[154:157], v[16:19]
	v_mfma_f32_16x16x32_bf16 v[8:11], v[212:215], v[162:165], v[8:11]
	v_mfma_f32_16x16x32_bf16 v[52:55], v[182:185], v[166:169], v[52:55]
	v_mfma_f32_16x16x32_bf16 v[44:47], v[182:185], v[174:177], v[44:47]
	v_mfma_f32_16x16x32_bf16 v[36:39], v[190:193], v[166:169], v[36:39]
	v_mfma_f32_16x16x32_bf16 v[28:31], v[190:193], v[174:177], v[28:31]
	v_mfma_f32_16x16x32_bf16 v[20:23], v[198:201], v[166:169], v[20:23]
	v_mfma_f32_16x16x32_bf16 v[12:15], v[198:201], v[174:177], v[12:15]
	v_mfma_f32_16x16x32_bf16 v[4:7], v[208:211], v[166:169], v[4:7]
	v_mfma_f32_16x16x32_bf16 v[0:3], v[208:211], v[174:177], v[0:3]
	v_mfma_f32_16x16x32_bf16 v[52:55], v[186:189], v[170:173], v[52:55]
	v_mfma_f32_16x16x32_bf16 v[44:47], v[186:189], v[178:181], v[44:47]
	v_mfma_f32_16x16x32_bf16 v[36:39], v[194:197], v[170:173], v[36:39]
	v_mfma_f32_16x16x32_bf16 v[28:31], v[194:197], v[178:181], v[28:31]
	v_mfma_f32_16x16x32_bf16 v[20:23], v[202:205], v[170:173], v[20:23]
	v_mfma_f32_16x16x32_bf16 v[12:15], v[202:205], v[178:181], v[12:15]
	v_mfma_f32_16x16x32_bf16 v[4:7], v[212:215], v[170:173], v[4:7]
	v_mfma_f32_16x16x32_bf16 v[0:3], v[212:215], v[178:181], v[0:3]
	s_setprio 0
	s_barrier
	s_add_i32 s62, 0, 0x18000
	s_add_i32 s63, 0, 0x1c000
	v_add_u32_e32 v162, s62, v146
	v_add_u32_e32 v178, s63, v146
	ds_read_b128 v[142:145], v162
	ds_read_b128 v[154:157], v162 offset:1024
	ds_read_b128 v[158:161], v162 offset:2048
	ds_read_b128 v[162:165], v162 offset:3072
	ds_read_b128 v[166:169], v178
	ds_read_b128 v[170:173], v178 offset:1024
	ds_read_b128 v[174:177], v178 offset:2048
	ds_read_b128 v[178:181], v178 offset:3072
	s_add_u32 s44, s44, 0x20000
	s_addc_u32 s45, s45, 0
	s_mov_b32 m0, s47
	v_lshl_add_u64 v[224:225], s[44:45], 0, v[128:129]
	ds_read_b128 v[182:185], v153 offset:32768
	ds_read_b128 v[186:189], v153 offset:33792
	ds_read_b128 v[190:193], v153 offset:34816
	ds_read_b128 v[194:197], v153 offset:35840
	ds_read_b128 v[198:201], v153 offset:36864
	ds_read_b128 v[202:205], v153 offset:37888
	ds_read_b128 v[208:211], v153 offset:38912
	ds_read_b128 v[212:215], v153 offset:39936
	global_load_lds_dwordx4 v[224:225], off
	v_lshl_add_u64 v[224:225], s[44:45], 0, v[130:131]
	s_mov_b32 m0, s50
	s_nop 0
	global_load_lds_dwordx4 v[224:225], off
	s_waitcnt vmcnt(8)
	s_waitcnt lgkmcnt(0)
	s_barrier
	s_setprio 1
	s_waitcnt lgkmcnt(0)
	v_mfma_f32_16x16x32_bf16 v[124:127], v[182:185], v[142:145], v[124:127]
	v_mfma_f32_16x16x32_bf16 v[120:123], v[182:185], v[158:161], v[120:123]
	v_mfma_f32_16x16x32_bf16 v[108:111], v[190:193], v[142:145], v[108:111]
	v_mfma_f32_16x16x32_bf16 v[104:107], v[190:193], v[158:161], v[104:107]
	v_mfma_f32_16x16x32_bf16 v[96:99], v[198:201], v[142:145], v[96:99]
	v_mfma_f32_16x16x32_bf16 v[88:91], v[198:201], v[158:161], v[88:91]
	v_mfma_f32_16x16x32_bf16 v[80:83], v[208:211], v[142:145], v[80:83]
	v_mfma_f32_16x16x32_bf16 v[72:75], v[208:211], v[158:161], v[72:75]
	v_mfma_f32_16x16x32_bf16 v[124:127], v[186:189], v[154:157], v[124:127]
	v_mfma_f32_16x16x32_bf16 v[120:123], v[186:189], v[162:165], v[120:123]
	v_mfma_f32_16x16x32_bf16 v[108:111], v[194:197], v[154:157], v[108:111]
	v_mfma_f32_16x16x32_bf16 v[104:107], v[194:197], v[162:165], v[104:107]
	v_mfma_f32_16x16x32_bf16 v[96:99], v[202:205], v[154:157], v[96:99]
	v_mfma_f32_16x16x32_bf16 v[88:91], v[202:205], v[162:165], v[88:91]
	v_mfma_f32_16x16x32_bf16 v[80:83], v[212:215], v[154:157], v[80:83]
	v_mfma_f32_16x16x32_bf16 v[72:75], v[212:215], v[162:165], v[72:75]
	v_mfma_f32_16x16x32_bf16 v[116:119], v[182:185], v[166:169], v[116:119]
	v_mfma_f32_16x16x32_bf16 v[112:115], v[182:185], v[174:177], v[112:115]
	v_mfma_f32_16x16x32_bf16 v[100:103], v[190:193], v[166:169], v[100:103]
	v_mfma_f32_16x16x32_bf16 v[92:95], v[190:193], v[174:177], v[92:95]
	v_mfma_f32_16x16x32_bf16 v[84:87], v[198:201], v[166:169], v[84:87]
	v_mfma_f32_16x16x32_bf16 v[76:79], v[198:201], v[174:177], v[76:79]
	v_mfma_f32_16x16x32_bf16 v[68:71], v[208:211], v[166:169], v[68:71]
	v_mfma_f32_16x16x32_bf16 v[64:67], v[208:211], v[174:177], v[64:67]
	v_mfma_f32_16x16x32_bf16 v[116:119], v[186:189], v[170:173], v[116:119]
	v_mfma_f32_16x16x32_bf16 v[112:115], v[186:189], v[178:181], v[112:115]
	v_mfma_f32_16x16x32_bf16 v[100:103], v[194:197], v[170:173], v[100:103]
	v_mfma_f32_16x16x32_bf16 v[92:95], v[194:197], v[178:181], v[92:95]
	v_mfma_f32_16x16x32_bf16 v[84:87], v[202:205], v[170:173], v[84:87]
	v_mfma_f32_16x16x32_bf16 v[76:79], v[202:205], v[178:181], v[76:79]
	v_mfma_f32_16x16x32_bf16 v[68:71], v[212:215], v[170:173], v[68:71]
	v_mfma_f32_16x16x32_bf16 v[64:67], v[212:215], v[178:181], v[64:67]
	s_setprio 0
	s_barrier
; #define PG8_STAGE(bufoff, gbase, voff) do { _Pragma("unroll") for (int _i = 0; _i < 2; ++_i) \
;         __builtin_amdgcn_global_load_lds((const unsigned*)((const char*)(gbase) + (voff)[_i]), (LAS unsigned*)(lds + (bufoff) + ldsw + _i * 8192), 16, 0, 0); } while (0)
; #define PG8_LDA(dst, b, h) do { _Pragma("unroll") for (int m = 0; m < 4; ++m) _Pragma("unroll") for (int k = 0; k < 2; ++k) dst[m][k] = *(const LAS bf16x8*)(lds + PG8_SA(b, h) + aoff + m * 2048 + k * 1024); } while (0)
; #define PG8_WAIT_V(n) asm volatile("s_waitcnt vmcnt(" #n ")" ::: "memory")
; #define PG8_WAIT_L(n) asm volatile("s_waitcnt lgkmcnt(" #n ")" ::: "memory")
; #define PG8_BAR __builtin_amdgcn_s_barrier()
; #define PG8_SCHED __builtin_amdgcn_sched_barrier(0)
; template <class Epi, class Sched, bool SWAPD = false>
; __device__ __forceinline__ void gemm_phase(LAS unsigned char* lds, const Gemm g, const Sched& S, const Epi& E) {
;     ...
;             PG8_LDA(At, 1, 1); PG8_STAGE(PG8_SB(1, 0), b3, voffB); PG8_STAGE(PG8_SB(1, 1), b3 + hstepB, voffB); PG8_STAGE(PG8_SA(1, 0), a3, voffA);
;             PG8_WAIT_V(8); PG8_WAIT_L(0); PG8_BAR; PG8_MMA(1, 0, At, B0); PG8_MMA(1, 1, At, B1); PG8_BAR; PG8_SCHED;
;         }
	s_add_i32 s44, s62, s21
	v_lshl_add_u64 v[216:217], v[216:217], 0, s[12:13]
	s_mov_b32 m0, s44
	ds_read_b128 v[182:185], v153 offset:49152
	ds_read_b128 v[186:189], v153 offset:50176
	ds_read_b128 v[190:193], v153 offset:51200
	ds_read_b128 v[194:197], v153 offset:52224
	ds_read_b128 v[198:201], v153 offset:53248
	ds_read_b128 v[202:205], v153 offset:54272
	ds_read_b128 v[208:211], v153 offset:55296
	ds_read_b128 v[212:215], v153 offset:56320
	global_load_lds_dwordx4 v[216:217], off
	s_add_i32 m0, s44, 0x2000
	s_add_u32 s42, s42, 0x20080
	v_lshl_add_u64 v[216:217], v[218:219], 0, s[12:13]
	s_addc_u32 s43, s43, 0
	s_add_i32 s44, s63, s21
	global_load_lds_dwordx4 v[216:217], off
	v_lshl_add_u64 v[216:217], s[42:43], 0, v[128:129]
	s_mov_b32 m0, s44
	s_nop 0
	global_load_lds_dwordx4 v[216:217], off
	v_lshl_add_u64 v[216:217], s[42:43], 0, v[130:131]
	s_add_i32 m0, s44, 0x2000
	s_nop 0
	global_load_lds_dwordx4 v[216:217], off
	v_lshl_add_u64 v[216:217], v[220:221], 0, s[12:13]
	s_mov_b32 m0, s52
	s_nop 0
	global_load_lds_dwordx4 v[216:217], off
	v_lshl_add_u64 v[216:217], v[222:223], 0, s[12:13]
	s_mov_b32 m0, s53
	s_nop 0
	global_load_lds_dwordx4 v[216:217], off
	s_waitcnt vmcnt(8)
	s_waitcnt lgkmcnt(0)
	s_barrier
	s_setprio 1
	s_waitcnt lgkmcnt(0)
	v_mfma_f32_16x16x32_bf16 v[60:63], v[182:185], v[142:145], v[60:63]
	v_mfma_f32_16x16x32_bf16 v[56:59], v[182:185], v[158:161], v[56:59]
	v_mfma_f32_16x16x32_bf16 v[48:51], v[190:193], v[142:145], v[48:51]
	v_mfma_f32_16x16x32_bf16 v[40:43], v[190:193], v[158:161], v[40:43]
	v_mfma_f32_16x16x32_bf16 v[32:35], v[198:201], v[142:145], v[32:35]
	v_mfma_f32_16x16x32_bf16 v[24:27], v[198:201], v[158:161], v[24:27]
	v_mfma_f32_16x16x32_bf16 v[16:19], v[208:211], v[142:145], v[16:19]
	v_mfma_f32_16x16x32_bf16 v[8:11], v[208:211], v[158:161], v[8:11]
	v_mfma_f32_16x16x32_bf16 v[60:63], v[186:189], v[154:157], v[60:63]
	v_mfma_f32_16x16x32_bf16 v[56:59], v[186:189], v[162:165], v[56:59]
	v_mfma_f32_16x16x32_bf16 v[48:51], v[194:197], v[154:157], v[48:51]
	v_mfma_f32_16x16x32_bf16 v[40:43], v[194:197], v[162:165], v[40:43]
	v_mfma_f32_16x16x32_bf16 v[32:35], v[202:205], v[154:157], v[32:35]
	v_mfma_f32_16x16x32_bf16 v[24:27], v[202:205], v[162:165], v[24:27]
	v_mfma_f32_16x16x32_bf16 v[16:19], v[212:215], v[154:157], v[16:19]
	v_mfma_f32_16x16x32_bf16 v[8:11], v[212:215], v[162:165], v[8:11]
	v_mfma_f32_16x16x32_bf16 v[52:55], v[182:185], v[166:169], v[52:55]
	v_mfma_f32_16x16x32_bf16 v[44:47], v[182:185], v[174:177], v[44:47]
	v_mfma_f32_16x16x32_bf16 v[36:39], v[190:193], v[166:169], v[36:39]
	v_mfma_f32_16x16x32_bf16 v[28:31], v[190:193], v[174:177], v[28:31]
	v_mfma_f32_16x16x32_bf16 v[20:23], v[198:201], v[166:169], v[20:23]
	v_mfma_f32_16x16x32_bf16 v[12:15], v[198:201], v[174:177], v[12:15]
	v_mfma_f32_16x16x32_bf16 v[4:7], v[208:211], v[166:169], v[4:7]
	v_mfma_f32_16x16x32_bf16 v[0:3], v[208:211], v[174:177], v[0:3]
	v_mfma_f32_16x16x32_bf16 v[52:55], v[186:189], v[170:173], v[52:55]
	v_mfma_f32_16x16x32_bf16 v[44:47], v[186:189], v[178:181], v[44:47]
	v_mfma_f32_16x16x32_bf16 v[36:39], v[194:197], v[170:173], v[36:39]
	v_mfma_f32_16x16x32_bf16 v[28:31], v[194:197], v[178:181], v[28:31]
	v_mfma_f32_16x16x32_bf16 v[20:23], v[202:205], v[170:173], v[20:23]
	v_mfma_f32_16x16x32_bf16 v[12:15], v[202:205], v[178:181], v[12:15]
	v_mfma_f32_16x16x32_bf16 v[4:7], v[212:215], v[170:173], v[4:7]
	v_mfma_f32_16x16x32_bf16 v[0:3], v[212:215], v[178:181], v[0:3]
	s_setprio 0
	s_barrier
	s_add_i32 s61, s61, 2
	s_add_u32 s40, s40, 0x100
	s_addc_u32 s41, s41, 0
	s_add_u32 s59, s59, 0x100
	s_addc_u32 s60, s60, 0
	s_cmp_gt_u32 s61, 5
	s_cbranch_scc0 .LBB0_1531
	s_and_b64 vcc, exec, s[22:23]
	s_cbranch_vccz .LBB0_1534
	s_barrier

; #define PG8_STAGE(bufoff, gbase, voff) do { _Pragma("unroll") for (int _i = 0; _i < 2; ++_i) \
;         __builtin_amdgcn_global_load_lds((const unsigned*)((const char*)(gbase) + (voff)[_i]), (LAS unsigned*)(lds + (bufoff) + ldsw + _i * 8192), 16, 0, 0); } while (0)
; #define PG8_LDA(dst, b, h) do { _Pragma("unroll") for (int m = 0; m < 4; ++m) _Pragma("unroll") for (int k = 0; k < 2; ++k) dst[m][k] = *(const LAS bf16x8*)(lds + PG8_SA(b, h) + aoff + m * 2048 + k * 1024); } while (0)
; #define PG8_LDB(dst, b, h) do { _Pragma("unroll") for (int n = 0; n < 2; ++n) _Pragma("unroll") for (int k = 0; k < 2; ++k) dst[n][k] = *(const LAS bf16x8*)(lds + PG8_SB(b, h) + boff + n * 2048 + k * 1024); } while (0)
; #define PG8_WAIT_V(n) asm volatile("s_waitcnt vmcnt(" #n ")" ::: "memory")
; #define PG8_WAIT_L(n) asm volatile("s_waitcnt lgkmcnt(" #n ")" ::: "memory")
; #define PG8_BAR __builtin_amdgcn_s_barrier()
; #define PG8_SCHED __builtin_amdgcn_sched_barrier(0)
; template <class Epi, class Sched, bool SWAPD = false>
; __device__ __forceinline__ void gemm_phase(LAS unsigned char* lds, const Gemm g, const Sched& S, const Epi& E) {
;     ...
;             const bool last = (t == nt - 2);
;             const char* a1 = cA + (size_t)(t + 1) * kstepA;
;             const char* a2 = last ? nA : cA + (size_t)(t + 2) * kstepA; const char* b2 = last ? nB : cB + (size_t)(t + 2) * kstep;
;             const char* a3 = a2 + kstepA; const char* b3 = b2 + kstep;
;             PG8_LDB(B0, 0, 0); PG8_LDB(B1, 0, 1); PG8_SCHED; PG8_LDA(At, 0, 0); PG8_STAGE(PG8_SA(1, 1), a1 + hstepA, voffA);
;             PG8_WAIT_V(8); PG8_WAIT_L(0); PG8_BAR; PG8_MMA(0, 0, At, B0); PG8_MMA(0, 1, At, B1); PG8_BAR; PG8_SCHED;
;             PG8_LDA(At, 0, 1); PG8_STAGE(PG8_SB(0, 0), b2, voffB); PG8_STAGE(PG8_SB(0, 1), b2 + hstepB, voffB); PG8_STAGE(PG8_SA(0, 0), a2, voffA);
.LBB0_1661:
	ds_read_b128 v[154:157], v150
	ds_read_b128 v[158:161], v150 offset:1024
	ds_read_b128 v[162:165], v150 offset:2048
	ds_read_b128 v[166:169], v150 offset:3072
	ds_read_b128 v[170:173], v151
	ds_read_b128 v[174:177], v151 offset:1024
	ds_read_b128 v[178:181], v151 offset:2048
	ds_read_b128 v[182:185], v151 offset:3072
	s_add_u32 s46, s44, 0x100
	s_addc_u32 s47, s45, 0
	s_add_u32 s50, s75, s44
	s_addc_u32 s51, s76, s45
	s_cmp_eq_u32 s77, 4
	s_cselect_b32 s52, s74, s50
	s_cselect_b32 s50, 0, s46
	s_cselect_b32 s53, s9, s51
	s_cselect_b32 s51, 0, s47
	s_add_u32 s50, s0, s50
	s_addc_u32 s51, s1, s51
	s_mov_b32 m0, s62
	v_lshl_add_u64 v[220:221], v[144:145], 0, s[44:45]
	ds_read_b128 v[186:189], v152
	ds_read_b128 v[190:193], v152 offset:1024
	ds_read_b128 v[194:197], v152 offset:2048
	ds_read_b128 v[198:201], v152 offset:3072
	ds_read_b128 v[202:205], v152 offset:4096
	ds_read_b128 v[208:211], v152 offset:5120
	ds_read_b128 v[212:215], v152 offset:6144
	ds_read_b128 v[216:219], v152 offset:7168
	global_load_lds_dwordx4 v[220:221], off
	v_lshl_add_u64 v[220:221], v[146:147], 0, s[44:45]
	s_mov_b32 m0, s63
	s_nop 0
	global_load_lds_dwordx4 v[220:221], off
	s_waitcnt vmcnt(8)
	s_waitcnt lgkmcnt(0)
	s_barrier
	s_setprio 1
	s_waitcnt lgkmcnt(0)
	v_mfma_f32_16x16x32_bf16 v[124:127], v[154:157], v[186:189], v[124:127]
	v_mfma_f32_16x16x32_bf16 v[120:123], v[162:165], v[186:189], v[120:123]
	v_mfma_f32_16x16x32_bf16 v[112:115], v[154:157], v[194:197], v[112:115]
	v_mfma_f32_16x16x32_bf16 v[104:107], v[162:165], v[194:197], v[104:107]
	v_mfma_f32_16x16x32_bf16 v[96:99], v[154:157], v[202:205], v[96:99]
	v_mfma_f32_16x16x32_bf16 v[88:91], v[162:165], v[202:205], v[88:91]
	v_mfma_f32_16x16x32_bf16 v[80:83], v[154:157], v[212:215], v[80:83]
	v_mfma_f32_16x16x32_bf16 v[72:75], v[162:165], v[212:215], v[72:75]
	v_mfma_f32_16x16x32_bf16 v[124:127], v[158:161], v[190:193], v[124:127]
	v_mfma_f32_16x16x32_bf16 v[120:123], v[166:169], v[190:193], v[120:123]
	v_mfma_f32_16x16x32_bf16 v[112:115], v[158:161], v[198:201], v[112:115]
	v_mfma_f32_16x16x32_bf16 v[104:107], v[166:169], v[198:201], v[104:107]
	v_mfma_f32_16x16x32_bf16 v[96:99], v[158:161], v[208:211], v[96:99]
	v_mfma_f32_16x16x32_bf16 v[88:91], v[166:169], v[208:211], v[88:91]
	v_mfma_f32_16x16x32_bf16 v[80:83], v[158:161], v[216:219], v[80:83]
	v_mfma_f32_16x16x32_bf16 v[72:75], v[166:169], v[216:219], v[72:75]
	v_mfma_f32_16x16x32_bf16 v[116:119], v[170:173], v[186:189], v[116:119]
	v_mfma_f32_16x16x32_bf16 v[108:111], v[178:181], v[186:189], v[108:111]
	v_mfma_f32_16x16x32_bf16 v[100:103], v[170:173], v[194:197], v[100:103]
	v_mfma_f32_16x16x32_bf16 v[92:95], v[178:181], v[194:197], v[92:95]
	v_mfma_f32_16x16x32_bf16 v[84:87], v[170:173], v[202:205], v[84:87]
	v_mfma_f32_16x16x32_bf16 v[76:79], v[178:181], v[202:205], v[76:79]
	v_mfma_f32_16x16x32_bf16 v[68:71], v[170:173], v[212:215], v[68:71]
	v_mfma_f32_16x16x32_bf16 v[64:67], v[178:181], v[212:215], v[64:67]
	v_mfma_f32_16x16x32_bf16 v[116:119], v[174:177], v[190:193], v[116:119]
	v_mfma_f32_16x16x32_bf16 v[108:111], v[182:185], v[190:193], v[108:111]
	v_mfma_f32_16x16x32_bf16 v[100:103], v[174:177], v[198:201], v[100:103]
	v_mfma_f32_16x16x32_bf16 v[92:95], v[182:185], v[198:201], v[92:95]
	v_mfma_f32_16x16x32_bf16 v[84:87], v[174:177], v[208:211], v[84:87]
	v_mfma_f32_16x16x32_bf16 v[76:79], v[182:185], v[208:211], v[76:79]
	v_mfma_f32_16x16x32_bf16 v[68:71], v[174:177], v[216:219], v[68:71]
	v_mfma_f32_16x16x32_bf16 v[64:67], v[182:185], v[216:219], v[64:67]
	s_setprio 0
	s_barrier
	s_mov_b32 m0, s64
	v_lshl_add_u64 v[220:221], s[50:51], 0, v[132:133]
	s_add_u32 s44, s50, 0x20000
	ds_read_b128 v[186:189], v152 offset:16384
	ds_read_b128 v[190:193], v152 offset:17408
	ds_read_b128 v[194:197], v152 offset:18432
	ds_read_b128 v[198:201], v152 offset:19456
	ds_read_b128 v[202:205], v152 offset:20480
	ds_read_b128 v[208:211], v152 offset:21504
	ds_read_b128 v[212:215], v152 offset:22528
	ds_read_b128 v[216:219], v152 offset:23552
	global_load_lds_dwordx4 v[220:221], off
	v_lshl_add_u64 v[222:223], s[50:51], 0, v[128:129]
	s_mov_b32 m0, s65
	s_addc_u32 s45, s51, 0
	global_load_lds_dwordx4 v[222:223], off
	v_lshl_add_u64 v[224:225], s[44:45], 0, v[132:133]
	s_mov_b32 m0, s66
	v_lshl_add_u64 v[226:227], s[52:53], 0, v[130:131]
	global_load_lds_dwordx4 v[224:225], off
	v_lshl_add_u64 v[224:225], s[44:45], 0, v[128:129]
	s_mov_b32 m0, s67
	s_nop 0
	global_load_lds_dwordx4 v[224:225], off
	v_lshl_add_u64 v[224:225], s[52:53], 0, v[134:135]
	s_mov_b32 m0, s30
	s_nop 0
	global_load_lds_dwordx4 v[224:225], off
	s_mov_b32 m0, s31
	s_nop 0
	global_load_lds_dwordx4 v[226:227], off
	s_waitcnt vmcnt(8)
	s_waitcnt lgkmcnt(0)
	s_barrier
; #define PG8_STAGE(bufoff, gbase, voff) do { _Pragma("unroll") for (int _i = 0; _i < 2; ++_i) \
;         __builtin_amdgcn_global_load_lds((const unsigned*)((const char*)(gbase) + (voff)[_i]), (LAS unsigned*)(lds + (bufoff) + ldsw + _i * 8192), 16, 0, 0); } while (0)
; #define PG8_LDA(dst, b, h) do { _Pragma("unroll") for (int m = 0; m < 4; ++m) _Pragma("unroll") for (int k = 0; k < 2; ++k) dst[m][k] = *(const LAS bf16x8*)(lds + PG8_SA(b, h) + aoff + m * 2048 + k * 1024); } while (0)
; #define PG8_LDB(dst, b, h) do { _Pragma("unroll") for (int n = 0; n < 2; ++n) _Pragma("unroll") for (int k = 0; k < 2; ++k) dst[n][k] = *(const LAS bf16x8*)(lds + PG8_SB(b, h) + boff + n * 2048 + k * 1024); } while (0)
; #define PG8_WAIT_V(n) asm volatile("s_waitcnt vmcnt(" #n ")" ::: "memory")
; #define PG8_WAIT_L(n) asm volatile("s_waitcnt lgkmcnt(" #n ")" ::: "memory")
; #define PG8_BAR __builtin_amdgcn_s_barrier()
; #define PG8_SCHED __builtin_amdgcn_sched_barrier(0)
; template <class Epi, class Sched, bool SWAPD = false>
; __device__ __forceinline__ void gemm_phase(LAS unsigned char* lds, const Gemm g, const Sched& S, const Epi& E) {
;     ...
;             PG8_WAIT_V(8); PG8_WAIT_L(0); PG8_BAR; PG8_MMA(1, 0, At, B0); PG8_MMA(1, 1, At, B1); PG8_BAR; PG8_SCHED;
;             PG8_LDB(B0, 1, 0); PG8_LDB(B1, 1, 1); PG8_SCHED; PG8_LDA(At, 1, 0); PG8_STAGE(PG8_SA(0, 1), a2 + hstepA, voffA);
;             PG8_WAIT_V(8); PG8_WAIT_L(0); PG8_BAR; PG8_MMA(0, 0, At, B0); PG8_MMA(0, 1, At, B1); PG8_BAR; PG8_SCHED;
	s_setprio 1
	s_waitcnt lgkmcnt(0)
	v_mfma_f32_16x16x32_bf16 v[60:63], v[154:157], v[186:189], v[60:63]
	v_mfma_f32_16x16x32_bf16 v[56:59], v[162:165], v[186:189], v[56:59]
	v_mfma_f32_16x16x32_bf16 v[48:51], v[154:157], v[194:197], v[48:51]
	v_mfma_f32_16x16x32_bf16 v[40:43], v[162:165], v[194:197], v[40:43]
	v_mfma_f32_16x16x32_bf16 v[32:35], v[154:157], v[202:205], v[32:35]
	v_mfma_f32_16x16x32_bf16 v[24:27], v[162:165], v[202:205], v[24:27]
	v_mfma_f32_16x16x32_bf16 v[16:19], v[154:157], v[212:215], v[16:19]
	v_mfma_f32_16x16x32_bf16 v[8:11], v[162:165], v[212:215], v[8:11]
	v_mfma_f32_16x16x32_bf16 v[60:63], v[158:161], v[190:193], v[60:63]
	v_mfma_f32_16x16x32_bf16 v[56:59], v[166:169], v[190:193], v[56:59]
	v_mfma_f32_16x16x32_bf16 v[48:51], v[158:161], v[198:201], v[48:51]
	v_mfma_f32_16x16x32_bf16 v[40:43], v[166:169], v[198:201], v[40:43]
	v_mfma_f32_16x16x32_bf16 v[32:35], v[158:161], v[208:211], v[32:35]
	v_mfma_f32_16x16x32_bf16 v[24:27], v[166:169], v[208:211], v[24:27]
	v_mfma_f32_16x16x32_bf16 v[16:19], v[158:161], v[216:219], v[16:19]
	v_mfma_f32_16x16x32_bf16 v[8:11], v[166:169], v[216:219], v[8:11]
	v_mfma_f32_16x16x32_bf16 v[52:55], v[170:173], v[186:189], v[52:55]
	v_mfma_f32_16x16x32_bf16 v[44:47], v[178:181], v[186:189], v[44:47]
	v_mfma_f32_16x16x32_bf16 v[36:39], v[170:173], v[194:197], v[36:39]
	v_mfma_f32_16x16x32_bf16 v[28:31], v[178:181], v[194:197], v[28:31]
	v_mfma_f32_16x16x32_bf16 v[20:23], v[170:173], v[202:205], v[20:23]
	v_mfma_f32_16x16x32_bf16 v[12:15], v[178:181], v[202:205], v[12:15]
	v_mfma_f32_16x16x32_bf16 v[4:7], v[170:173], v[212:215], v[4:7]
	v_mfma_f32_16x16x32_bf16 v[0:3], v[178:181], v[212:215], v[0:3]
	v_mfma_f32_16x16x32_bf16 v[52:55], v[174:177], v[190:193], v[52:55]
	v_mfma_f32_16x16x32_bf16 v[44:47], v[182:185], v[190:193], v[44:47]
	v_mfma_f32_16x16x32_bf16 v[36:39], v[174:177], v[198:201], v[36:39]
	v_mfma_f32_16x16x32_bf16 v[28:31], v[182:185], v[198:201], v[28:31]
	v_mfma_f32_16x16x32_bf16 v[20:23], v[174:177], v[208:211], v[20:23]
	v_mfma_f32_16x16x32_bf16 v[12:15], v[182:185], v[208:211], v[12:15]
	v_mfma_f32_16x16x32_bf16 v[4:7], v[174:177], v[216:219], v[4:7]
	v_mfma_f32_16x16x32_bf16 v[0:3], v[182:185], v[216:219], v[0:3]
	s_setprio 0
	s_barrier
	s_add_i32 s78, 0, 0x18000
	v_add_u32_e32 v136, s78, v149
	s_add_i32 s79, 0, 0x1c000
	ds_read_b128 v[154:157], v136
	ds_read_b128 v[158:161], v136 offset:1024
	ds_read_b128 v[162:165], v136 offset:2048
	ds_read_b128 v[166:169], v136 offset:3072
	v_add_u32_e32 v136, s79, v149
	ds_read_b128 v[170:173], v136
	ds_read_b128 v[174:177], v136 offset:1024
	ds_read_b128 v[178:181], v136 offset:2048
	ds_read_b128 v[182:185], v136 offset:3072
	s_add_u32 s44, s52, 0x80000
	s_addc_u32 s45, s53, 0
	s_mov_b32 m0, s33
	v_lshl_add_u64 v[228:229], s[44:45], 0, v[134:135]
	ds_read_b128 v[186:189], v152 offset:32768
	ds_read_b128 v[190:193], v152 offset:33792
	ds_read_b128 v[194:197], v152 offset:34816
	ds_read_b128 v[198:201], v152 offset:35840
	ds_read_b128 v[202:205], v152 offset:36864
	ds_read_b128 v[208:211], v152 offset:37888
	ds_read_b128 v[212:215], v152 offset:38912
	ds_read_b128 v[216:219], v152 offset:39936
	global_load_lds_dwordx4 v[228:229], off
	v_lshl_add_u64 v[228:229], s[44:45], 0, v[130:131]
	s_mov_b32 m0, s54
	s_nop 0
	global_load_lds_dwordx4 v[228:229], off
	s_waitcnt vmcnt(8)
	s_waitcnt lgkmcnt(0)
	s_barrier
	s_setprio 1
	s_waitcnt lgkmcnt(0)
	v_mfma_f32_16x16x32_bf16 v[124:127], v[154:157], v[186:189], v[124:127]
	v_mfma_f32_16x16x32_bf16 v[120:123], v[162:165], v[186:189], v[120:123]
	v_mfma_f32_16x16x32_bf16 v[112:115], v[154:157], v[194:197], v[112:115]
	v_mfma_f32_16x16x32_bf16 v[104:107], v[162:165], v[194:197], v[104:107]
	v_mfma_f32_16x16x32_bf16 v[96:99], v[154:157], v[202:205], v[96:99]
	v_mfma_f32_16x16x32_bf16 v[88:91], v[162:165], v[202:205], v[88:91]
	v_mfma_f32_16x16x32_bf16 v[80:83], v[154:157], v[212:215], v[80:83]
	v_mfma_f32_16x16x32_bf16 v[72:75], v[162:165], v[212:215], v[72:75]
	v_mfma_f32_16x16x32_bf16 v[124:127], v[158:161], v[190:193], v[124:127]
	v_mfma_f32_16x16x32_bf16 v[120:123], v[166:169], v[190:193], v[120:123]
	v_mfma_f32_16x16x32_bf16 v[112:115], v[158:161], v[198:201], v[112:115]
	v_mfma_f32_16x16x32_bf16 v[104:107], v[166:169], v[198:201], v[104:107]
	v_mfma_f32_16x16x32_bf16 v[96:99], v[158:161], v[208:211], v[96:99]
	v_mfma_f32_16x16x32_bf16 v[88:91], v[166:169], v[208:211], v[88:91]
	v_mfma_f32_16x16x32_bf16 v[80:83], v[158:161], v[216:219], v[80:83]
	v_mfma_f32_16x16x32_bf16 v[72:75], v[166:169], v[216:219], v[72:75]
	v_mfma_f32_16x16x32_bf16 v[116:119], v[170:173], v[186:189], v[116:119]
	v_mfma_f32_16x16x32_bf16 v[108:111], v[178:181], v[186:189], v[108:111]
	v_mfma_f32_16x16x32_bf16 v[100:103], v[170:173], v[194:197], v[100:103]
	v_mfma_f32_16x16x32_bf16 v[92:95], v[178:181], v[194:197], v[92:95]
	v_mfma_f32_16x16x32_bf16 v[84:87], v[170:173], v[202:205], v[84:87]
	v_mfma_f32_16x16x32_bf16 v[76:79], v[178:181], v[202:205], v[76:79]
	v_mfma_f32_16x16x32_bf16 v[68:71], v[170:173], v[212:215], v[68:71]
	v_mfma_f32_16x16x32_bf16 v[64:67], v[178:181], v[212:215], v[64:67]
	v_mfma_f32_16x16x32_bf16 v[116:119], v[174:177], v[190:193], v[116:119]
	v_mfma_f32_16x16x32_bf16 v[108:111], v[182:185], v[190:193], v[108:111]
	v_mfma_f32_16x16x32_bf16 v[100:103], v[174:177], v[198:201], v[100:103]
	v_mfma_f32_16x16x32_bf16 v[92:95], v[182:185], v[198:201], v[92:95]
	v_mfma_f32_16x16x32_bf16 v[84:87], v[174:177], v[208:211], v[84:87]
	v_mfma_f32_16x16x32_bf16 v[76:79], v[182:185], v[208:211], v[76:79]
	v_mfma_f32_16x16x32_bf16 v[68:71], v[174:177], v[216:219], v[68:71]
	v_mfma_f32_16x16x32_bf16 v[64:67], v[182:185], v[216:219], v[64:67]
	s_setprio 0
	s_barrier
; #define PG8_STAGE(bufoff, gbase, voff) do { _Pragma("unroll") for (int _i = 0; _i < 2; ++_i) \
;         __builtin_amdgcn_global_load_lds((const unsigned*)((const char*)(gbase) + (voff)[_i]), (LAS unsigned*)(lds + (bufoff) + ldsw + _i * 8192), 16, 0, 0); } while (0)
; #define PG8_LDA(dst, b, h) do { _Pragma("unroll") for (int m = 0; m < 4; ++m) _Pragma("unroll") for (int k = 0; k < 2; ++k) dst[m][k] = *(const LAS bf16x8*)(lds + PG8_SA(b, h) + aoff + m * 2048 + k * 1024); } while (0)
; #define PG8_WAIT_V(n) asm volatile("s_waitcnt vmcnt(" #n ")" ::: "memory")
; #define PG8_WAIT_L(n) asm volatile("s_waitcnt lgkmcnt(" #n ")" ::: "memory")
; #define PG8_BAR __builtin_amdgcn_s_barrier()
; #define PG8_SCHED __builtin_amdgcn_sched_barrier(0)
; template <class Epi, class Sched, bool SWAPD = false>
; __device__ __forceinline__ void gemm_phase(LAS unsigned char* lds, const Gemm g, const Sched& S, const Epi& E) {
;     ...
;             PG8_LDA(At, 1, 1); PG8_STAGE(PG8_SB(1, 0), b3, voffB); PG8_STAGE(PG8_SB(1, 1), b3 + hstepB, voffB); PG8_STAGE(PG8_SA(1, 0), a3, voffA);
;             PG8_WAIT_V(8); PG8_WAIT_L(0); PG8_BAR; PG8_MMA(1, 0, At, B0); PG8_MMA(1, 1, At, B1); PG8_BAR; PG8_SCHED;
;         }
	s_add_i32 s44, s78, s21
	v_lshl_add_u64 v[220:221], v[220:221], 0, s[24:25]
	s_mov_b32 m0, s44
	ds_read_b128 v[186:189], v152 offset:49152
	ds_read_b128 v[190:193], v152 offset:50176
	ds_read_b128 v[194:197], v152 offset:51200
	ds_read_b128 v[198:201], v152 offset:52224
	ds_read_b128 v[202:205], v152 offset:53248
	ds_read_b128 v[208:211], v152 offset:54272
	ds_read_b128 v[212:215], v152 offset:55296
	ds_read_b128 v[216:219], v152 offset:56320
	global_load_lds_dwordx4 v[220:221], off
	s_add_i32 m0, s44, 0x2000
	s_add_u32 s44, s50, 0x20080
	v_lshl_add_u64 v[220:221], v[222:223], 0, s[24:25]
	s_addc_u32 s45, s51, 0
	s_add_i32 s50, s79, s21
	global_load_lds_dwordx4 v[220:221], off
	v_lshl_add_u64 v[220:221], s[44:45], 0, v[132:133]
	s_mov_b32 m0, s50
	s_nop 0
	global_load_lds_dwordx4 v[220:221], off
	v_lshl_add_u64 v[220:221], s[44:45], 0, v[128:129]
	s_add_i32 m0, s50, 0x2000
	s_nop 0
	global_load_lds_dwordx4 v[220:221], off
	v_lshl_add_u64 v[220:221], v[224:225], 0, s[24:25]
	s_mov_b32 m0, s56
	s_nop 0
	global_load_lds_dwordx4 v[220:221], off
	v_lshl_add_u64 v[220:221], v[226:227], 0, s[24:25]
	s_mov_b32 m0, s57
	s_nop 0
	global_load_lds_dwordx4 v[220:221], off
	s_waitcnt vmcnt(8)
	s_waitcnt lgkmcnt(0)
	s_barrier
	s_setprio 1
	s_waitcnt lgkmcnt(0)
	v_mfma_f32_16x16x32_bf16 v[60:63], v[154:157], v[186:189], v[60:63]
	v_mfma_f32_16x16x32_bf16 v[56:59], v[162:165], v[186:189], v[56:59]
	v_mfma_f32_16x16x32_bf16 v[48:51], v[154:157], v[194:197], v[48:51]
	v_mfma_f32_16x16x32_bf16 v[40:43], v[162:165], v[194:197], v[40:43]
	v_mfma_f32_16x16x32_bf16 v[32:35], v[154:157], v[202:205], v[32:35]
	v_mfma_f32_16x16x32_bf16 v[24:27], v[162:165], v[202:205], v[24:27]
	v_mfma_f32_16x16x32_bf16 v[16:19], v[154:157], v[212:215], v[16:19]
	v_mfma_f32_16x16x32_bf16 v[8:11], v[162:165], v[212:215], v[8:11]
	v_mfma_f32_16x16x32_bf16 v[60:63], v[158:161], v[190:193], v[60:63]
	v_mfma_f32_16x16x32_bf16 v[56:59], v[166:169], v[190:193], v[56:59]
	v_mfma_f32_16x16x32_bf16 v[48:51], v[158:161], v[198:201], v[48:51]
	v_mfma_f32_16x16x32_bf16 v[40:43], v[166:169], v[198:201], v[40:43]
	v_mfma_f32_16x16x32_bf16 v[32:35], v[158:161], v[208:211], v[32:35]
	v_mfma_f32_16x16x32_bf16 v[24:27], v[166:169], v[208:211], v[24:27]
	v_mfma_f32_16x16x32_bf16 v[16:19], v[158:161], v[216:219], v[16:19]
	v_mfma_f32_16x16x32_bf16 v[8:11], v[166:169], v[216:219], v[8:11]
	v_mfma_f32_16x16x32_bf16 v[52:55], v[170:173], v[186:189], v[52:55]
	v_mfma_f32_16x16x32_bf16 v[44:47], v[178:181], v[186:189], v[44:47]
	v_mfma_f32_16x16x32_bf16 v[36:39], v[170:173], v[194:197], v[36:39]
	v_mfma_f32_16x16x32_bf16 v[28:31], v[178:181], v[194:197], v[28:31]
	v_mfma_f32_16x16x32_bf16 v[20:23], v[170:173], v[202:205], v[20:23]
	v_mfma_f32_16x16x32_bf16 v[12:15], v[178:181], v[202:205], v[12:15]
	v_mfma_f32_16x16x32_bf16 v[4:7], v[170:173], v[212:215], v[4:7]
	v_mfma_f32_16x16x32_bf16 v[0:3], v[178:181], v[212:215], v[0:3]
	v_mfma_f32_16x16x32_bf16 v[52:55], v[174:177], v[190:193], v[52:55]
	v_mfma_f32_16x16x32_bf16 v[44:47], v[182:185], v[190:193], v[44:47]
	v_mfma_f32_16x16x32_bf16 v[36:39], v[174:177], v[198:201], v[36:39]
	v_mfma_f32_16x16x32_bf16 v[28:31], v[182:185], v[198:201], v[28:31]
	v_mfma_f32_16x16x32_bf16 v[20:23], v[174:177], v[208:211], v[20:23]
	v_mfma_f32_16x16x32_bf16 v[12:15], v[182:185], v[208:211], v[12:15]
	v_mfma_f32_16x16x32_bf16 v[4:7], v[174:177], v[216:219], v[4:7]
	v_mfma_f32_16x16x32_bf16 v[0:3], v[182:185], v[216:219], v[0:3]
	s_setprio 0
	s_barrier
	s_add_i32 s77, s77, 2
	s_cmp_gt_u32 s77, 5
	s_mov_b64 s[44:45], s[46:47]
	s_cbranch_scc0 .LBB0_1661
	s_and_b64 vcc, exec, s[26:27]
	s_cbranch_vccz .LBB0_1664
	s_barrier

; #define PG8_STAGE(bufoff, gbase, voff) do { _Pragma("unroll") for (int _i = 0; _i < 2; ++_i) \
;         __builtin_amdgcn_global_load_lds((const unsigned*)((const char*)(gbase) + (voff)[_i]), (LAS unsigned*)(lds + (bufoff) + ldsw + _i * 8192), 16, 0, 0); } while (0)
; #define PG8_LDA(dst, b, h) do { _Pragma("unroll") for (int m = 0; m < 4; ++m) _Pragma("unroll") for (int k = 0; k < 2; ++k) dst[m][k] = *(const LAS bf16x8*)(lds + PG8_SA(b, h) + aoff + m * 2048 + k * 1024); } while (0)
; #define PG8_LDB(dst, b, h) do { _Pragma("unroll") for (int n = 0; n < 2; ++n) _Pragma("unroll") for (int k = 0; k < 2; ++k) dst[n][k] = *(const LAS bf16x8*)(lds + PG8_SB(b, h) + boff + n * 2048 + k * 1024); } while (0)
; #define PG8_WAIT_V(n) asm volatile("s_waitcnt vmcnt(" #n ")" ::: "memory")
; #define PG8_WAIT_L(n) asm volatile("s_waitcnt lgkmcnt(" #n ")" ::: "memory")
; #define PG8_BAR __builtin_amdgcn_s_barrier()
; #define PG8_SCHED __builtin_amdgcn_sched_barrier(0)
; template <class Epi, class Sched, bool SWAPD = false>
; __device__ __forceinline__ void gemm_phase(LAS unsigned char* lds, const Gemm g, const Sched& S, const Epi& E) {
;     ...
;             const bool last = (t == nt - 2);
;             const char* a1 = cA + (size_t)(t + 1) * kstepA;
;             const char* a2 = last ? nA : cA + (size_t)(t + 2) * kstepA; const char* b2 = last ? nB : cB + (size_t)(t + 2) * kstep;
;             const char* a3 = a2 + kstepA; const char* b3 = b2 + kstep;
;             PG8_LDB(B0, 0, 0); PG8_LDB(B1, 0, 1); PG8_SCHED; PG8_LDA(At, 0, 0); PG8_STAGE(PG8_SA(1, 1), a1 + hstepA, voffA);
;             PG8_WAIT_V(8); PG8_WAIT_L(0); PG8_BAR; PG8_MMA(0, 0, At, B0); PG8_MMA(0, 1, At, B1); PG8_BAR; PG8_SCHED;
;             PG8_LDA(At, 0, 1); PG8_STAGE(PG8_SB(0, 0), b2, voffB); PG8_STAGE(PG8_SB(0, 1), b2 + hstepB, voffB); PG8_STAGE(PG8_SA(0, 0), a2, voffA);
.LBB0_1737:
	ds_read_b128 v[104:107], v176
	ds_read_b128 v[108:111], v176 offset:1024
	ds_read_b128 v[124:127], v176 offset:2048
	ds_read_b128 v[128:131], v176 offset:3072
	ds_read_b128 v[180:183], v177
	ds_read_b128 v[184:187], v177 offset:1024
	ds_read_b128 v[188:191], v177 offset:2048
	ds_read_b128 v[192:195], v177 offset:3072
	s_add_u32 s42, s40, 0xfffc0080
	s_addc_u32 s43, s41, -1
	s_cmp_eq_u32 s60, 12
	s_cselect_b32 s45, s23, s43
	s_cselect_b32 s44, s25, s42
	s_cselect_b32 s43, s56, s59
	s_cselect_b32 s42, s57, s58
	v_lshl_add_u64 v[172:173], s[40:41], 0, v[164:165]
	s_add_i32 m0, s30, 0xc000
	ds_read_b128 v[196:199], v178
	ds_read_b128 v[200:203], v178 offset:1024
	ds_read_b128 v[208:211], v178 offset:2048
	ds_read_b128 v[212:215], v178 offset:3072
	ds_read_b128 v[216:219], v178 offset:4096
	ds_read_b128 v[220:223], v178 offset:5120
	ds_read_b128 v[224:227], v178 offset:6144
	ds_read_b128 v[228:231], v178 offset:7168
	global_load_lds_dwordx4 v[172:173], off
	v_lshl_add_u64 v[172:173], s[40:41], 0, v[166:167]
	s_add_i32 m0, s30, 0xe000
	s_nop 0
	global_load_lds_dwordx4 v[172:173], off
	s_waitcnt vmcnt(8)
	s_waitcnt lgkmcnt(0)
	s_barrier
	s_setprio 1
	s_waitcnt lgkmcnt(0)
	v_mfma_f32_16x16x32_bf16 v[140:143], v[104:107], v[196:199], v[140:143]
	v_mfma_f32_16x16x32_bf16 v[136:139], v[124:127], v[196:199], v[136:139]
	v_mfma_f32_16x16x32_bf16 v[116:119], v[104:107], v[208:211], v[116:119]
	v_mfma_f32_16x16x32_bf16 v[112:115], v[124:127], v[208:211], v[112:115]
	v_mfma_f32_16x16x32_bf16 v[92:95], v[104:107], v[216:219], v[92:95]
	v_mfma_f32_16x16x32_bf16 v[88:91], v[124:127], v[216:219], v[88:91]
	v_mfma_f32_16x16x32_bf16 v[76:79], v[104:107], v[224:227], v[76:79]
	v_mfma_f32_16x16x32_bf16 v[72:75], v[124:127], v[224:227], v[72:75]
	v_mfma_f32_16x16x32_bf16 v[140:143], v[108:111], v[200:203], v[140:143]
	v_mfma_f32_16x16x32_bf16 v[136:139], v[128:131], v[200:203], v[136:139]
	v_mfma_f32_16x16x32_bf16 v[116:119], v[108:111], v[212:215], v[116:119]
	v_mfma_f32_16x16x32_bf16 v[112:115], v[128:131], v[212:215], v[112:115]
	v_mfma_f32_16x16x32_bf16 v[92:95], v[108:111], v[220:223], v[92:95]
	v_mfma_f32_16x16x32_bf16 v[88:91], v[128:131], v[220:223], v[88:91]
	v_mfma_f32_16x16x32_bf16 v[76:79], v[108:111], v[228:231], v[76:79]
	v_mfma_f32_16x16x32_bf16 v[72:75], v[128:131], v[228:231], v[72:75]
	v_mfma_f32_16x16x32_bf16 v[132:135], v[180:183], v[196:199], v[132:135]
	v_mfma_f32_16x16x32_bf16 v[120:123], v[188:191], v[196:199], v[120:123]
	v_mfma_f32_16x16x32_bf16 v[100:103], v[180:183], v[208:211], v[100:103]
	v_mfma_f32_16x16x32_bf16 v[96:99], v[188:191], v[208:211], v[96:99]
	v_mfma_f32_16x16x32_bf16 v[84:87], v[180:183], v[216:219], v[84:87]
	v_mfma_f32_16x16x32_bf16 v[80:83], v[188:191], v[216:219], v[80:83]
	v_mfma_f32_16x16x32_bf16 v[68:71], v[180:183], v[224:227], v[68:71]
	v_mfma_f32_16x16x32_bf16 v[64:67], v[188:191], v[224:227], v[64:67]
	v_mfma_f32_16x16x32_bf16 v[132:135], v[184:187], v[200:203], v[132:135]
	v_mfma_f32_16x16x32_bf16 v[120:123], v[192:195], v[200:203], v[120:123]
	v_mfma_f32_16x16x32_bf16 v[100:103], v[184:187], v[212:215], v[100:103]
	v_mfma_f32_16x16x32_bf16 v[96:99], v[192:195], v[212:215], v[96:99]
	v_mfma_f32_16x16x32_bf16 v[84:87], v[184:187], v[220:223], v[84:87]
	v_mfma_f32_16x16x32_bf16 v[80:83], v[192:195], v[220:223], v[80:83]
	v_mfma_f32_16x16x32_bf16 v[68:71], v[184:187], v[228:231], v[68:71]
	v_mfma_f32_16x16x32_bf16 v[64:67], v[192:195], v[228:231], v[64:67]
	s_setprio 0
	s_barrier
	s_add_i32 s61, s54, s21
	v_lshl_add_u64 v[172:173], s[42:43], 0, v[144:145]
	s_mov_b32 m0, s61
	ds_read_b128 v[196:199], v178 offset:16384
	ds_read_b128 v[200:203], v178 offset:17408
	ds_read_b128 v[208:211], v178 offset:18432
	ds_read_b128 v[212:215], v178 offset:19456
	ds_read_b128 v[216:219], v178 offset:20480
	ds_read_b128 v[220:223], v178 offset:21504
	ds_read_b128 v[224:227], v178 offset:22528
	ds_read_b128 v[228:231], v178 offset:23552
	global_load_lds_dwordx4 v[172:173], off
	s_add_i32 m0, s61, 0x2000
	s_add_u32 s62, s42, 0x40000
	v_lshl_add_u64 v[204:205], s[42:43], 0, v[146:147]
	s_addc_u32 s63, s43, 0
	s_add_i32 s61, s55, s21
	global_load_lds_dwordx4 v[204:205], off
	v_lshl_add_u64 v[232:233], s[62:63], 0, v[144:145]
	s_mov_b32 m0, s61
	v_lshl_add_u64 v[234:235], s[44:45], 0, v[146:147]
	global_load_lds_dwordx4 v[232:233], off
	v_lshl_add_u64 v[232:233], s[62:63], 0, v[146:147]
	s_add_i32 m0, s61, 0x2000
	s_nop 0
	global_load_lds_dwordx4 v[232:233], off
	v_lshl_add_u64 v[232:233], s[44:45], 0, v[144:145]
	s_mov_b32 m0, s30
	s_nop 0
	global_load_lds_dwordx4 v[232:233], off
	s_mov_b32 m0, s31
	s_nop 0
	global_load_lds_dwordx4 v[234:235], off
	s_waitcnt vmcnt(8)
	s_waitcnt lgkmcnt(0)
	s_barrier
; #define PG8_STAGE(bufoff, gbase, voff) do { _Pragma("unroll") for (int _i = 0; _i < 2; ++_i) \
;         __builtin_amdgcn_global_load_lds((const unsigned*)((const char*)(gbase) + (voff)[_i]), (LAS unsigned*)(lds + (bufoff) + ldsw + _i * 8192), 16, 0, 0); } while (0)
; #define PG8_LDA(dst, b, h) do { _Pragma("unroll") for (int m = 0; m < 4; ++m) _Pragma("unroll") for (int k = 0; k < 2; ++k) dst[m][k] = *(const LAS bf16x8*)(lds + PG8_SA(b, h) + aoff + m * 2048 + k * 1024); } while (0)
; #define PG8_LDB(dst, b, h) do { _Pragma("unroll") for (int n = 0; n < 2; ++n) _Pragma("unroll") for (int k = 0; k < 2; ++k) dst[n][k] = *(const LAS bf16x8*)(lds + PG8_SB(b, h) + boff + n * 2048 + k * 1024); } while (0)
; #define PG8_WAIT_V(n) asm volatile("s_waitcnt vmcnt(" #n ")" ::: "memory")
; #define PG8_WAIT_L(n) asm volatile("s_waitcnt lgkmcnt(" #n ")" ::: "memory")
; #define PG8_BAR __builtin_amdgcn_s_barrier()
; #define PG8_SCHED __builtin_amdgcn_sched_barrier(0)
; template <class Epi, class Sched, bool SWAPD = false>
; __device__ __forceinline__ void gemm_phase(LAS unsigned char* lds, const Gemm g, const Sched& S, const Epi& E) {
;     ...
;             PG8_WAIT_V(8); PG8_WAIT_L(0); PG8_BAR; PG8_MMA(1, 0, At, B0); PG8_MMA(1, 1, At, B1); PG8_BAR; PG8_SCHED;
;             PG8_LDB(B0, 1, 0); PG8_LDB(B1, 1, 1); PG8_SCHED; PG8_LDA(At, 1, 0); PG8_STAGE(PG8_SA(0, 1), a2 + hstepA, voffA);
;             PG8_WAIT_V(8); PG8_WAIT_L(0); PG8_BAR; PG8_MMA(0, 0, At, B0); PG8_MMA(0, 1, At, B1); PG8_BAR; PG8_SCHED;
	s_setprio 1
	s_waitcnt lgkmcnt(0)
	v_mfma_f32_16x16x32_bf16 v[60:63], v[104:107], v[196:199], v[60:63]
	v_mfma_f32_16x16x32_bf16 v[56:59], v[124:127], v[196:199], v[56:59]
	v_mfma_f32_16x16x32_bf16 v[44:47], v[104:107], v[208:211], v[44:47]
	v_mfma_f32_16x16x32_bf16 v[40:43], v[124:127], v[208:211], v[40:43]
	v_mfma_f32_16x16x32_bf16 v[28:31], v[104:107], v[216:219], v[28:31]
	v_mfma_f32_16x16x32_bf16 v[24:27], v[124:127], v[216:219], v[24:27]
	v_mfma_f32_16x16x32_bf16 v[12:15], v[104:107], v[224:227], v[12:15]
	v_mfma_f32_16x16x32_bf16 v[8:11], v[124:127], v[224:227], v[8:11]
	v_mfma_f32_16x16x32_bf16 v[60:63], v[108:111], v[200:203], v[60:63]
	v_mfma_f32_16x16x32_bf16 v[56:59], v[128:131], v[200:203], v[56:59]
	v_mfma_f32_16x16x32_bf16 v[44:47], v[108:111], v[212:215], v[44:47]
	v_mfma_f32_16x16x32_bf16 v[40:43], v[128:131], v[212:215], v[40:43]
	v_mfma_f32_16x16x32_bf16 v[28:31], v[108:111], v[220:223], v[28:31]
	v_mfma_f32_16x16x32_bf16 v[24:27], v[128:131], v[220:223], v[24:27]
	v_mfma_f32_16x16x32_bf16 v[12:15], v[108:111], v[228:231], v[12:15]
	v_mfma_f32_16x16x32_bf16 v[8:11], v[128:131], v[228:231], v[8:11]
	v_mfma_f32_16x16x32_bf16 v[52:55], v[180:183], v[196:199], v[52:55]
	v_mfma_f32_16x16x32_bf16 v[48:51], v[188:191], v[196:199], v[48:51]
	v_mfma_f32_16x16x32_bf16 v[36:39], v[180:183], v[208:211], v[36:39]
	v_mfma_f32_16x16x32_bf16 v[32:35], v[188:191], v[208:211], v[32:35]
	v_mfma_f32_16x16x32_bf16 v[20:23], v[180:183], v[216:219], v[20:23]
	v_mfma_f32_16x16x32_bf16 v[16:19], v[188:191], v[216:219], v[16:19]
	v_mfma_f32_16x16x32_bf16 v[4:7], v[180:183], v[224:227], v[4:7]
	v_mfma_f32_16x16x32_bf16 v[0:3], v[188:191], v[224:227], v[0:3]
	v_mfma_f32_16x16x32_bf16 v[52:55], v[184:187], v[200:203], v[52:55]
	v_mfma_f32_16x16x32_bf16 v[48:51], v[192:195], v[200:203], v[48:51]
	v_mfma_f32_16x16x32_bf16 v[36:39], v[184:187], v[212:215], v[36:39]
	v_mfma_f32_16x16x32_bf16 v[32:35], v[192:195], v[212:215], v[32:35]
	v_mfma_f32_16x16x32_bf16 v[20:23], v[184:187], v[220:223], v[20:23]
	v_mfma_f32_16x16x32_bf16 v[16:19], v[192:195], v[220:223], v[16:19]
	v_mfma_f32_16x16x32_bf16 v[4:7], v[184:187], v[228:231], v[4:7]
	v_mfma_f32_16x16x32_bf16 v[0:3], v[192:195], v[228:231], v[0:3]
	s_setprio 0
	s_barrier
	s_add_i32 s61, 0, 0x18000
	s_add_i32 s62, 0, 0x1c000
	v_add_u32_e32 v128, s61, v174
	v_add_u32_e32 v179, s62, v174
	ds_read_b128 v[104:107], v128
	ds_read_b128 v[108:111], v128 offset:1024
	ds_read_b128 v[124:127], v128 offset:2048
	ds_read_b128 v[128:131], v128 offset:3072
	ds_read_b128 v[180:183], v179
	ds_read_b128 v[184:187], v179 offset:1024
	ds_read_b128 v[188:191], v179 offset:2048
	ds_read_b128 v[192:195], v179 offset:3072
	s_add_u32 s44, s44, 0x40000
	s_addc_u32 s45, s45, 0
	s_mov_b32 m0, s33
	v_lshl_add_u64 v[236:237], s[44:45], 0, v[144:145]
	ds_read_b128 v[196:199], v178 offset:32768
	ds_read_b128 v[200:203], v178 offset:33792
	ds_read_b128 v[208:211], v178 offset:34816
	ds_read_b128 v[212:215], v178 offset:35840
	ds_read_b128 v[216:219], v178 offset:36864
	ds_read_b128 v[220:223], v178 offset:37888
	ds_read_b128 v[224:227], v178 offset:38912
	ds_read_b128 v[228:231], v178 offset:39936
	global_load_lds_dwordx4 v[236:237], off
	v_lshl_add_u64 v[236:237], s[44:45], 0, v[146:147]
	s_mov_b32 m0, s46
	s_nop 0
	global_load_lds_dwordx4 v[236:237], off
	s_waitcnt vmcnt(8)
	s_waitcnt lgkmcnt(0)
	s_barrier
	s_setprio 1
	s_waitcnt lgkmcnt(0)
	v_mfma_f32_16x16x32_bf16 v[140:143], v[104:107], v[196:199], v[140:143]
	v_mfma_f32_16x16x32_bf16 v[136:139], v[124:127], v[196:199], v[136:139]
	v_mfma_f32_16x16x32_bf16 v[116:119], v[104:107], v[208:211], v[116:119]
	v_mfma_f32_16x16x32_bf16 v[112:115], v[124:127], v[208:211], v[112:115]
	v_mfma_f32_16x16x32_bf16 v[92:95], v[104:107], v[216:219], v[92:95]
	v_mfma_f32_16x16x32_bf16 v[88:91], v[124:127], v[216:219], v[88:91]
	v_mfma_f32_16x16x32_bf16 v[76:79], v[104:107], v[224:227], v[76:79]
	v_mfma_f32_16x16x32_bf16 v[72:75], v[124:127], v[224:227], v[72:75]
	v_mfma_f32_16x16x32_bf16 v[140:143], v[108:111], v[200:203], v[140:143]
	v_mfma_f32_16x16x32_bf16 v[136:139], v[128:131], v[200:203], v[136:139]
	v_mfma_f32_16x16x32_bf16 v[116:119], v[108:111], v[212:215], v[116:119]
	v_mfma_f32_16x16x32_bf16 v[112:115], v[128:131], v[212:215], v[112:115]
	v_mfma_f32_16x16x32_bf16 v[92:95], v[108:111], v[220:223], v[92:95]
	v_mfma_f32_16x16x32_bf16 v[88:91], v[128:131], v[220:223], v[88:91]
	v_mfma_f32_16x16x32_bf16 v[76:79], v[108:111], v[228:231], v[76:79]
	v_mfma_f32_16x16x32_bf16 v[72:75], v[128:131], v[228:231], v[72:75]
	v_mfma_f32_16x16x32_bf16 v[132:135], v[180:183], v[196:199], v[132:135]
	v_mfma_f32_16x16x32_bf16 v[120:123], v[188:191], v[196:199], v[120:123]
	v_mfma_f32_16x16x32_bf16 v[100:103], v[180:183], v[208:211], v[100:103]
	v_mfma_f32_16x16x32_bf16 v[96:99], v[188:191], v[208:211], v[96:99]
	v_mfma_f32_16x16x32_bf16 v[84:87], v[180:183], v[216:219], v[84:87]
	v_mfma_f32_16x16x32_bf16 v[80:83], v[188:191], v[216:219], v[80:83]
	v_mfma_f32_16x16x32_bf16 v[68:71], v[180:183], v[224:227], v[68:71]
	v_mfma_f32_16x16x32_bf16 v[64:67], v[188:191], v[224:227], v[64:67]
	v_mfma_f32_16x16x32_bf16 v[132:135], v[184:187], v[200:203], v[132:135]
	v_mfma_f32_16x16x32_bf16 v[120:123], v[192:195], v[200:203], v[120:123]
	v_mfma_f32_16x16x32_bf16 v[100:103], v[184:187], v[212:215], v[100:103]
	v_mfma_f32_16x16x32_bf16 v[96:99], v[192:195], v[212:215], v[96:99]
	v_mfma_f32_16x16x32_bf16 v[84:87], v[184:187], v[220:223], v[84:87]
	v_mfma_f32_16x16x32_bf16 v[80:83], v[192:195], v[220:223], v[80:83]
	v_mfma_f32_16x16x32_bf16 v[68:71], v[184:187], v[228:231], v[68:71]
	v_mfma_f32_16x16x32_bf16 v[64:67], v[192:195], v[228:231], v[64:67]
	s_setprio 0
	s_barrier
; #define PG8_STAGE(bufoff, gbase, voff) do { _Pragma("unroll") for (int _i = 0; _i < 2; ++_i) \
;         __builtin_amdgcn_global_load_lds((const unsigned*)((const char*)(gbase) + (voff)[_i]), (LAS unsigned*)(lds + (bufoff) + ldsw + _i * 8192), 16, 0, 0); } while (0)
; #define PG8_LDA(dst, b, h) do { _Pragma("unroll") for (int m = 0; m < 4; ++m) _Pragma("unroll") for (int k = 0; k < 2; ++k) dst[m][k] = *(const LAS bf16x8*)(lds + PG8_SA(b, h) + aoff + m * 2048 + k * 1024); } while (0)
; #define PG8_WAIT_V(n) asm volatile("s_waitcnt vmcnt(" #n ")" ::: "memory")
; #define PG8_WAIT_L(n) asm volatile("s_waitcnt lgkmcnt(" #n ")" ::: "memory")
; #define PG8_BAR __builtin_amdgcn_s_barrier()
; #define PG8_SCHED __builtin_amdgcn_sched_barrier(0)
; template <class Epi, class Sched, bool SWAPD = false>
; __device__ __forceinline__ void gemm_phase(LAS unsigned char* lds, const Gemm g, const Sched& S, const Epi& E) {
;     ...
;             PG8_LDA(At, 1, 1); PG8_STAGE(PG8_SB(1, 0), b3, voffB); PG8_STAGE(PG8_SB(1, 1), b3 + hstepB, voffB); PG8_STAGE(PG8_SA(1, 0), a3, voffA);
;             PG8_WAIT_V(8); PG8_WAIT_L(0); PG8_BAR; PG8_MMA(1, 0, At, B0); PG8_MMA(1, 1, At, B1); PG8_BAR; PG8_SCHED;
;         }
	s_add_i32 s44, s61, s21
	v_lshl_add_u64 v[172:173], v[172:173], 0, s[8:9]
	s_mov_b32 m0, s44
	ds_read_b128 v[196:199], v178 offset:49152
	ds_read_b128 v[200:203], v178 offset:50176
	ds_read_b128 v[208:211], v178 offset:51200
	ds_read_b128 v[212:215], v178 offset:52224
	ds_read_b128 v[216:219], v178 offset:53248
	ds_read_b128 v[220:223], v178 offset:54272
	ds_read_b128 v[224:227], v178 offset:55296
	ds_read_b128 v[228:231], v178 offset:56320
	global_load_lds_dwordx4 v[172:173], off
	s_add_i32 m0, s44, 0x2000
	s_add_u32 s42, s42, 0x40080
	v_lshl_add_u64 v[172:173], v[204:205], 0, s[8:9]
	s_addc_u32 s43, s43, 0
	s_add_i32 s44, s62, s21
	global_load_lds_dwordx4 v[172:173], off
	v_lshl_add_u64 v[172:173], s[42:43], 0, v[144:145]
	s_mov_b32 m0, s44
	s_nop 0
	global_load_lds_dwordx4 v[172:173], off
	v_lshl_add_u64 v[172:173], s[42:43], 0, v[146:147]
	s_add_i32 m0, s44, 0x2000
	s_nop 0
	global_load_lds_dwordx4 v[172:173], off
	v_lshl_add_u64 v[172:173], v[232:233], 0, s[8:9]
	s_mov_b32 m0, s52
	s_nop 0
	global_load_lds_dwordx4 v[172:173], off
	v_lshl_add_u64 v[172:173], v[234:235], 0, s[8:9]
	s_mov_b32 m0, s53
	s_nop 0
	global_load_lds_dwordx4 v[172:173], off
	s_waitcnt vmcnt(8)
	s_waitcnt lgkmcnt(0)
	s_barrier
	s_setprio 1
	s_waitcnt lgkmcnt(0)
	v_mfma_f32_16x16x32_bf16 v[60:63], v[104:107], v[196:199], v[60:63]
	v_mfma_f32_16x16x32_bf16 v[56:59], v[124:127], v[196:199], v[56:59]
	v_mfma_f32_16x16x32_bf16 v[44:47], v[104:107], v[208:211], v[44:47]
	v_mfma_f32_16x16x32_bf16 v[40:43], v[124:127], v[208:211], v[40:43]
	v_mfma_f32_16x16x32_bf16 v[28:31], v[104:107], v[216:219], v[28:31]
	v_mfma_f32_16x16x32_bf16 v[24:27], v[124:127], v[216:219], v[24:27]
	v_mfma_f32_16x16x32_bf16 v[12:15], v[104:107], v[224:227], v[12:15]
	v_mfma_f32_16x16x32_bf16 v[8:11], v[124:127], v[224:227], v[8:11]
	v_mfma_f32_16x16x32_bf16 v[60:63], v[108:111], v[200:203], v[60:63]
	v_mfma_f32_16x16x32_bf16 v[56:59], v[128:131], v[200:203], v[56:59]
	v_mfma_f32_16x16x32_bf16 v[44:47], v[108:111], v[212:215], v[44:47]
	v_mfma_f32_16x16x32_bf16 v[40:43], v[128:131], v[212:215], v[40:43]
	v_mfma_f32_16x16x32_bf16 v[28:31], v[108:111], v[220:223], v[28:31]
	v_mfma_f32_16x16x32_bf16 v[24:27], v[128:131], v[220:223], v[24:27]
	v_mfma_f32_16x16x32_bf16 v[12:15], v[108:111], v[228:231], v[12:15]
	v_mfma_f32_16x16x32_bf16 v[8:11], v[128:131], v[228:231], v[8:11]
	v_mfma_f32_16x16x32_bf16 v[52:55], v[180:183], v[196:199], v[52:55]
	v_mfma_f32_16x16x32_bf16 v[48:51], v[188:191], v[196:199], v[48:51]
	v_mfma_f32_16x16x32_bf16 v[36:39], v[180:183], v[208:211], v[36:39]
	v_mfma_f32_16x16x32_bf16 v[32:35], v[188:191], v[208:211], v[32:35]
	v_mfma_f32_16x16x32_bf16 v[20:23], v[180:183], v[216:219], v[20:23]
	v_mfma_f32_16x16x32_bf16 v[16:19], v[188:191], v[216:219], v[16:19]
	v_mfma_f32_16x16x32_bf16 v[4:7], v[180:183], v[224:227], v[4:7]
	v_mfma_f32_16x16x32_bf16 v[0:3], v[188:191], v[224:227], v[0:3]
	v_mfma_f32_16x16x32_bf16 v[52:55], v[184:187], v[200:203], v[52:55]
	v_mfma_f32_16x16x32_bf16 v[48:51], v[192:195], v[200:203], v[48:51]
	v_mfma_f32_16x16x32_bf16 v[36:39], v[184:187], v[212:215], v[36:39]
	v_mfma_f32_16x16x32_bf16 v[32:35], v[192:195], v[212:215], v[32:35]
	v_mfma_f32_16x16x32_bf16 v[20:23], v[184:187], v[220:223], v[20:23]
	v_mfma_f32_16x16x32_bf16 v[16:19], v[192:195], v[220:223], v[16:19]
	v_mfma_f32_16x16x32_bf16 v[4:7], v[184:187], v[228:231], v[4:7]
	v_mfma_f32_16x16x32_bf16 v[0:3], v[192:195], v[228:231], v[0:3]
	s_setprio 0
	s_barrier
	s_add_i32 s60, s60, 2
	s_add_u32 s40, s40, 0x100
	s_addc_u32 s41, s41, 0
	s_add_u32 s58, s58, 0x100
	s_addc_u32 s59, s59, 0
	s_cmp_gt_u32 s60, 13
	s_cbranch_scc0 .LBB0_1737
	s_and_b64 vcc, exec, s[12:13]
	s_cbranch_vccz .LBB0_1740
	s_barrier

; #define PG8_STAGE(bufoff, gbase, voff) do { _Pragma("unroll") for (int _i = 0; _i < 2; ++_i) \
;         __builtin_amdgcn_global_load_lds((const unsigned*)((const char*)(gbase) + (voff)[_i]), (LAS unsigned*)(lds + (bufoff) + ldsw + _i * 8192), 16, 0, 0); } while (0)
; #define PG8_LDA(dst, b, h) do { _Pragma("unroll") for (int m = 0; m < 4; ++m) _Pragma("unroll") for (int k = 0; k < 2; ++k) dst[m][k] = *(const LAS bf16x8*)(lds + PG8_SA(b, h) + aoff + m * 2048 + k * 1024); } while (0)
; #define PG8_LDB(dst, b, h) do { _Pragma("unroll") for (int n = 0; n < 2; ++n) _Pragma("unroll") for (int k = 0; k < 2; ++k) dst[n][k] = *(const LAS bf16x8*)(lds + PG8_SB(b, h) + boff + n * 2048 + k * 1024); } while (0)
; #define PG8_WAIT_V(n) asm volatile("s_waitcnt vmcnt(" #n ")" ::: "memory")
; #define PG8_WAIT_L(n) asm volatile("s_waitcnt lgkmcnt(" #n ")" ::: "memory")
; #define PG8_BAR __builtin_amdgcn_s_barrier()
; #define PG8_SCHED __builtin_amdgcn_sched_barrier(0)
; template <class Epi, class Sched, bool SWAPD = false>
; __device__ __forceinline__ void gemm_phase(LAS unsigned char* lds, const Gemm g, const Sched& S, const Epi& E) {
;     ...
;             const bool last = (t == nt - 2);
;             const char* a1 = cA + (size_t)(t + 1) * kstepA;
;             const char* a2 = last ? nA : cA + (size_t)(t + 2) * kstepA; const char* b2 = last ? nB : cB + (size_t)(t + 2) * kstep;
;             const char* a3 = a2 + kstepA; const char* b3 = b2 + kstep;
;             PG8_LDB(B0, 0, 0); PG8_LDB(B1, 0, 1); PG8_SCHED; PG8_LDA(At, 0, 0); PG8_STAGE(PG8_SA(1, 1), a1 + hstepA, voffA);
;             PG8_WAIT_V(8); PG8_WAIT_L(0); PG8_BAR; PG8_MMA(0, 0, At, B0); PG8_MMA(0, 1, At, B1); PG8_BAR; PG8_SCHED;
;             PG8_LDA(At, 0, 1); PG8_STAGE(PG8_SB(0, 0), b2, voffB); PG8_STAGE(PG8_SB(0, 1), b2 + hstepB, voffB); PG8_STAGE(PG8_SA(0, 0), a2, voffA);
.LBB0_1863:
	ds_read_b128 v[148:151], v145
	ds_read_b128 v[152:155], v145 offset:1024
	ds_read_b128 v[156:159], v145 offset:2048
	ds_read_b128 v[160:163], v145 offset:3072
	ds_read_b128 v[164:167], v146
	ds_read_b128 v[168:171], v146 offset:1024
	ds_read_b128 v[172:175], v146 offset:2048
	ds_read_b128 v[176:179], v146 offset:3072
	s_add_u32 s38, s36, 0xfffc0080
	s_addc_u32 s39, s37, -1
	s_cmp_eq_u32 s58, 12
	s_cselect_b32 s41, s21, s39
	s_cselect_b32 s40, s23, s38
	s_cselect_b32 s39, s54, s57
	s_cselect_b32 s38, s55, s56
	v_lshl_add_u64 v[140:141], s[36:37], 0, v[132:133]
	s_add_i32 m0, s35, 0xc000
	ds_read_b128 v[180:183], v147
	ds_read_b128 v[184:187], v147 offset:1024
	ds_read_b128 v[188:191], v147 offset:2048
	ds_read_b128 v[192:195], v147 offset:3072
	ds_read_b128 v[196:199], v147 offset:4096
	ds_read_b128 v[200:203], v147 offset:5120
	ds_read_b128 v[208:211], v147 offset:6144
	ds_read_b128 v[212:215], v147 offset:7168
	global_load_lds_dwordx4 v[140:141], off
	v_lshl_add_u64 v[140:141], s[36:37], 0, v[134:135]
	s_add_i32 m0, s35, 0xe000
	s_nop 0
	global_load_lds_dwordx4 v[140:141], off
	s_waitcnt vmcnt(8)
	s_waitcnt lgkmcnt(0)
	s_barrier
	s_setprio 1
	s_waitcnt lgkmcnt(0)
	v_mfma_f32_16x16x32_bf16 v[124:127], v[148:151], v[180:183], v[124:127]
	v_mfma_f32_16x16x32_bf16 v[116:119], v[156:159], v[180:183], v[116:119]
	v_mfma_f32_16x16x32_bf16 v[108:111], v[148:151], v[188:191], v[108:111]
	v_mfma_f32_16x16x32_bf16 v[100:103], v[156:159], v[188:191], v[100:103]
	v_mfma_f32_16x16x32_bf16 v[92:95], v[148:151], v[196:199], v[92:95]
	v_mfma_f32_16x16x32_bf16 v[84:87], v[156:159], v[196:199], v[84:87]
	v_mfma_f32_16x16x32_bf16 v[76:79], v[148:151], v[208:211], v[76:79]
	v_mfma_f32_16x16x32_bf16 v[68:71], v[156:159], v[208:211], v[68:71]
	v_mfma_f32_16x16x32_bf16 v[124:127], v[152:155], v[184:187], v[124:127]
	v_mfma_f32_16x16x32_bf16 v[116:119], v[160:163], v[184:187], v[116:119]
	v_mfma_f32_16x16x32_bf16 v[108:111], v[152:155], v[192:195], v[108:111]
	v_mfma_f32_16x16x32_bf16 v[100:103], v[160:163], v[192:195], v[100:103]
	v_mfma_f32_16x16x32_bf16 v[92:95], v[152:155], v[200:203], v[92:95]
	v_mfma_f32_16x16x32_bf16 v[84:87], v[160:163], v[200:203], v[84:87]
	v_mfma_f32_16x16x32_bf16 v[76:79], v[152:155], v[212:215], v[76:79]
	v_mfma_f32_16x16x32_bf16 v[68:71], v[160:163], v[212:215], v[68:71]
	v_mfma_f32_16x16x32_bf16 v[120:123], v[164:167], v[180:183], v[120:123]
	v_mfma_f32_16x16x32_bf16 v[112:115], v[172:175], v[180:183], v[112:115]
	v_mfma_f32_16x16x32_bf16 v[104:107], v[164:167], v[188:191], v[104:107]
	v_mfma_f32_16x16x32_bf16 v[96:99], v[172:175], v[188:191], v[96:99]
	v_mfma_f32_16x16x32_bf16 v[88:91], v[164:167], v[196:199], v[88:91]
	v_mfma_f32_16x16x32_bf16 v[80:83], v[172:175], v[196:199], v[80:83]
	v_mfma_f32_16x16x32_bf16 v[72:75], v[164:167], v[208:211], v[72:75]
	v_mfma_f32_16x16x32_bf16 v[64:67], v[172:175], v[208:211], v[64:67]
	v_mfma_f32_16x16x32_bf16 v[120:123], v[168:171], v[184:187], v[120:123]
	v_mfma_f32_16x16x32_bf16 v[112:115], v[176:179], v[184:187], v[112:115]
	v_mfma_f32_16x16x32_bf16 v[104:107], v[168:171], v[192:195], v[104:107]
	v_mfma_f32_16x16x32_bf16 v[96:99], v[176:179], v[192:195], v[96:99]
	v_mfma_f32_16x16x32_bf16 v[88:91], v[168:171], v[200:203], v[88:91]
	v_mfma_f32_16x16x32_bf16 v[80:83], v[176:179], v[200:203], v[80:83]
	v_mfma_f32_16x16x32_bf16 v[72:75], v[168:171], v[212:215], v[72:75]
	v_mfma_f32_16x16x32_bf16 v[64:67], v[176:179], v[212:215], v[64:67]
	s_setprio 0
	s_barrier
	s_add_i32 s59, s50, s42
	v_lshl_add_u64 v[140:141], s[38:39], 0, v[130:131]
	s_mov_b32 m0, s59
	ds_read_b128 v[180:183], v147 offset:16384
	ds_read_b128 v[184:187], v147 offset:17408
	ds_read_b128 v[188:191], v147 offset:18432
	ds_read_b128 v[192:195], v147 offset:19456
	ds_read_b128 v[196:199], v147 offset:20480
	ds_read_b128 v[200:203], v147 offset:21504
	ds_read_b128 v[208:211], v147 offset:22528
	ds_read_b128 v[212:215], v147 offset:23552
	global_load_lds_dwordx4 v[140:141], off
	s_add_i32 m0, s59, 0x2000
	s_add_u32 s60, s38, 0x40000
	v_lshl_add_u64 v[204:205], s[38:39], 0, v[128:129]
	s_addc_u32 s61, s39, 0
	s_add_i32 s59, s51, s42
	global_load_lds_dwordx4 v[204:205], off
	v_lshl_add_u64 v[216:217], s[60:61], 0, v[130:131]
	s_mov_b32 m0, s59
	v_lshl_add_u64 v[218:219], s[40:41], 0, v[128:129]
	global_load_lds_dwordx4 v[216:217], off
	v_lshl_add_u64 v[216:217], s[60:61], 0, v[128:129]
	s_add_i32 m0, s59, 0x2000
	s_nop 0
	global_load_lds_dwordx4 v[216:217], off
	v_lshl_add_u64 v[216:217], s[40:41], 0, v[130:131]
	s_mov_b32 m0, s35
	s_nop 0
	global_load_lds_dwordx4 v[216:217], off
	s_mov_b32 m0, s44
	s_nop 0
	global_load_lds_dwordx4 v[218:219], off
	s_waitcnt vmcnt(8)
	s_waitcnt lgkmcnt(0)
	s_barrier
; #define PG8_STAGE(bufoff, gbase, voff) do { _Pragma("unroll") for (int _i = 0; _i < 2; ++_i) \
;         __builtin_amdgcn_global_load_lds((const unsigned*)((const char*)(gbase) + (voff)[_i]), (LAS unsigned*)(lds + (bufoff) + ldsw + _i * 8192), 16, 0, 0); } while (0)
; #define PG8_LDA(dst, b, h) do { _Pragma("unroll") for (int m = 0; m < 4; ++m) _Pragma("unroll") for (int k = 0; k < 2; ++k) dst[m][k] = *(const LAS bf16x8*)(lds + PG8_SA(b, h) + aoff + m * 2048 + k * 1024); } while (0)
; #define PG8_LDB(dst, b, h) do { _Pragma("unroll") for (int n = 0; n < 2; ++n) _Pragma("unroll") for (int k = 0; k < 2; ++k) dst[n][k] = *(const LAS bf16x8*)(lds + PG8_SB(b, h) + boff + n * 2048 + k * 1024); } while (0)
; #define PG8_WAIT_V(n) asm volatile("s_waitcnt vmcnt(" #n ")" ::: "memory")
; #define PG8_WAIT_L(n) asm volatile("s_waitcnt lgkmcnt(" #n ")" ::: "memory")
; #define PG8_BAR __builtin_amdgcn_s_barrier()
; #define PG8_SCHED __builtin_amdgcn_sched_barrier(0)
; template <class Epi, class Sched, bool SWAPD = false>
; __device__ __forceinline__ void gemm_phase(LAS unsigned char* lds, const Gemm g, const Sched& S, const Epi& E) {
;     ...
;             PG8_WAIT_V(8); PG8_WAIT_L(0); PG8_BAR; PG8_MMA(1, 0, At, B0); PG8_MMA(1, 1, At, B1); PG8_BAR; PG8_SCHED;
;             PG8_LDB(B0, 1, 0); PG8_LDB(B1, 1, 1); PG8_SCHED; PG8_LDA(At, 1, 0); PG8_STAGE(PG8_SA(0, 1), a2 + hstepA, voffA);
;             PG8_WAIT_V(8); PG8_WAIT_L(0); PG8_BAR; PG8_MMA(0, 0, At, B0); PG8_MMA(0, 1, At, B1); PG8_BAR; PG8_SCHED;
	s_setprio 1
	s_waitcnt lgkmcnt(0)
	v_mfma_f32_16x16x32_bf16 v[60:63], v[148:151], v[180:183], v[60:63]
	v_mfma_f32_16x16x32_bf16 v[52:55], v[156:159], v[180:183], v[52:55]
	v_mfma_f32_16x16x32_bf16 v[44:47], v[148:151], v[188:191], v[44:47]
	v_mfma_f32_16x16x32_bf16 v[36:39], v[156:159], v[188:191], v[36:39]
	v_mfma_f32_16x16x32_bf16 v[28:31], v[148:151], v[196:199], v[28:31]
	v_mfma_f32_16x16x32_bf16 v[20:23], v[156:159], v[196:199], v[20:23]
	v_mfma_f32_16x16x32_bf16 v[12:15], v[148:151], v[208:211], v[12:15]
	v_mfma_f32_16x16x32_bf16 v[4:7], v[156:159], v[208:211], v[4:7]
	v_mfma_f32_16x16x32_bf16 v[60:63], v[152:155], v[184:187], v[60:63]
	v_mfma_f32_16x16x32_bf16 v[52:55], v[160:163], v[184:187], v[52:55]
	v_mfma_f32_16x16x32_bf16 v[44:47], v[152:155], v[192:195], v[44:47]
	v_mfma_f32_16x16x32_bf16 v[36:39], v[160:163], v[192:195], v[36:39]
	v_mfma_f32_16x16x32_bf16 v[28:31], v[152:155], v[200:203], v[28:31]
	v_mfma_f32_16x16x32_bf16 v[20:23], v[160:163], v[200:203], v[20:23]
	v_mfma_f32_16x16x32_bf16 v[12:15], v[152:155], v[212:215], v[12:15]
	v_mfma_f32_16x16x32_bf16 v[4:7], v[160:163], v[212:215], v[4:7]
	v_mfma_f32_16x16x32_bf16 v[56:59], v[164:167], v[180:183], v[56:59]
	v_mfma_f32_16x16x32_bf16 v[48:51], v[172:175], v[180:183], v[48:51]
	v_mfma_f32_16x16x32_bf16 v[40:43], v[164:167], v[188:191], v[40:43]
	v_mfma_f32_16x16x32_bf16 v[32:35], v[172:175], v[188:191], v[32:35]
	v_mfma_f32_16x16x32_bf16 v[24:27], v[164:167], v[196:199], v[24:27]
	v_mfma_f32_16x16x32_bf16 v[16:19], v[172:175], v[196:199], v[16:19]
	v_mfma_f32_16x16x32_bf16 v[8:11], v[164:167], v[208:211], v[8:11]
	v_mfma_f32_16x16x32_bf16 v[0:3], v[172:175], v[208:211], v[0:3]
	v_mfma_f32_16x16x32_bf16 v[56:59], v[168:171], v[184:187], v[56:59]
	v_mfma_f32_16x16x32_bf16 v[48:51], v[176:179], v[184:187], v[48:51]
	v_mfma_f32_16x16x32_bf16 v[40:43], v[168:171], v[192:195], v[40:43]
	v_mfma_f32_16x16x32_bf16 v[32:35], v[176:179], v[192:195], v[32:35]
	v_mfma_f32_16x16x32_bf16 v[24:27], v[168:171], v[200:203], v[24:27]
	v_mfma_f32_16x16x32_bf16 v[16:19], v[176:179], v[200:203], v[16:19]
	v_mfma_f32_16x16x32_bf16 v[8:11], v[168:171], v[212:215], v[8:11]
	v_mfma_f32_16x16x32_bf16 v[0:3], v[176:179], v[212:215], v[0:3]
	s_setprio 0
	s_barrier
	s_add_i32 s59, 0, 0x18000
	s_add_i32 s60, 0, 0x1c000
	v_add_u32_e32 v160, s59, v143
	v_add_u32_e32 v176, s60, v143
	ds_read_b128 v[148:151], v160
	ds_read_b128 v[152:155], v160 offset:1024
	ds_read_b128 v[156:159], v160 offset:2048
	ds_read_b128 v[160:163], v160 offset:3072
	ds_read_b128 v[164:167], v176
	ds_read_b128 v[168:171], v176 offset:1024
	ds_read_b128 v[172:175], v176 offset:2048
	ds_read_b128 v[176:179], v176 offset:3072
	s_add_u32 s40, s40, 0x40000
	s_addc_u32 s41, s41, 0
	s_mov_b32 m0, s45
	v_lshl_add_u64 v[220:221], s[40:41], 0, v[130:131]
	ds_read_b128 v[180:183], v147 offset:32768
	ds_read_b128 v[184:187], v147 offset:33792
	ds_read_b128 v[188:191], v147 offset:34816
	ds_read_b128 v[192:195], v147 offset:35840
	ds_read_b128 v[196:199], v147 offset:36864
	ds_read_b128 v[200:203], v147 offset:37888
	ds_read_b128 v[208:211], v147 offset:38912
	ds_read_b128 v[212:215], v147 offset:39936
	global_load_lds_dwordx4 v[220:221], off
	v_lshl_add_u64 v[220:221], s[40:41], 0, v[128:129]
	s_mov_b32 m0, s46
	s_nop 0
	global_load_lds_dwordx4 v[220:221], off
	s_waitcnt vmcnt(8)
	s_waitcnt lgkmcnt(0)
	s_barrier
	s_setprio 1
	s_waitcnt lgkmcnt(0)
	v_mfma_f32_16x16x32_bf16 v[124:127], v[148:151], v[180:183], v[124:127]
	v_mfma_f32_16x16x32_bf16 v[116:119], v[156:159], v[180:183], v[116:119]
	v_mfma_f32_16x16x32_bf16 v[108:111], v[148:151], v[188:191], v[108:111]
	v_mfma_f32_16x16x32_bf16 v[100:103], v[156:159], v[188:191], v[100:103]
	v_mfma_f32_16x16x32_bf16 v[92:95], v[148:151], v[196:199], v[92:95]
	v_mfma_f32_16x16x32_bf16 v[84:87], v[156:159], v[196:199], v[84:87]
	v_mfma_f32_16x16x32_bf16 v[76:79], v[148:151], v[208:211], v[76:79]
	v_mfma_f32_16x16x32_bf16 v[68:71], v[156:159], v[208:211], v[68:71]
	v_mfma_f32_16x16x32_bf16 v[124:127], v[152:155], v[184:187], v[124:127]
	v_mfma_f32_16x16x32_bf16 v[116:119], v[160:163], v[184:187], v[116:119]
	v_mfma_f32_16x16x32_bf16 v[108:111], v[152:155], v[192:195], v[108:111]
	v_mfma_f32_16x16x32_bf16 v[100:103], v[160:163], v[192:195], v[100:103]
	v_mfma_f32_16x16x32_bf16 v[92:95], v[152:155], v[200:203], v[92:95]
	v_mfma_f32_16x16x32_bf16 v[84:87], v[160:163], v[200:203], v[84:87]
	v_mfma_f32_16x16x32_bf16 v[76:79], v[152:155], v[212:215], v[76:79]
	v_mfma_f32_16x16x32_bf16 v[68:71], v[160:163], v[212:215], v[68:71]
	v_mfma_f32_16x16x32_bf16 v[120:123], v[164:167], v[180:183], v[120:123]
	v_mfma_f32_16x16x32_bf16 v[112:115], v[172:175], v[180:183], v[112:115]
	v_mfma_f32_16x16x32_bf16 v[104:107], v[164:167], v[188:191], v[104:107]
	v_mfma_f32_16x16x32_bf16 v[96:99], v[172:175], v[188:191], v[96:99]
	v_mfma_f32_16x16x32_bf16 v[88:91], v[164:167], v[196:199], v[88:91]
	v_mfma_f32_16x16x32_bf16 v[80:83], v[172:175], v[196:199], v[80:83]
	v_mfma_f32_16x16x32_bf16 v[72:75], v[164:167], v[208:211], v[72:75]
	v_mfma_f32_16x16x32_bf16 v[64:67], v[172:175], v[208:211], v[64:67]
	v_mfma_f32_16x16x32_bf16 v[120:123], v[168:171], v[184:187], v[120:123]
	v_mfma_f32_16x16x32_bf16 v[112:115], v[176:179], v[184:187], v[112:115]
	v_mfma_f32_16x16x32_bf16 v[104:107], v[168:171], v[192:195], v[104:107]
	v_mfma_f32_16x16x32_bf16 v[96:99], v[176:179], v[192:195], v[96:99]
	v_mfma_f32_16x16x32_bf16 v[88:91], v[168:171], v[200:203], v[88:91]
	v_mfma_f32_16x16x32_bf16 v[80:83], v[176:179], v[200:203], v[80:83]
	v_mfma_f32_16x16x32_bf16 v[72:75], v[168:171], v[212:215], v[72:75]
	v_mfma_f32_16x16x32_bf16 v[64:67], v[176:179], v[212:215], v[64:67]
	s_setprio 0
	s_barrier
; #define PG8_STAGE(bufoff, gbase, voff) do { _Pragma("unroll") for (int _i = 0; _i < 2; ++_i) \
;         __builtin_amdgcn_global_load_lds((const unsigned*)((const char*)(gbase) + (voff)[_i]), (LAS unsigned*)(lds + (bufoff) + ldsw + _i * 8192), 16, 0, 0); } while (0)
; #define PG8_LDA(dst, b, h) do { _Pragma("unroll") for (int m = 0; m < 4; ++m) _Pragma("unroll") for (int k = 0; k < 2; ++k) dst[m][k] = *(const LAS bf16x8*)(lds + PG8_SA(b, h) + aoff + m * 2048 + k * 1024); } while (0)
; #define PG8_WAIT_V(n) asm volatile("s_waitcnt vmcnt(" #n ")" ::: "memory")
; #define PG8_WAIT_L(n) asm volatile("s_waitcnt lgkmcnt(" #n ")" ::: "memory")
; #define PG8_BAR __builtin_amdgcn_s_barrier()
; #define PG8_SCHED __builtin_amdgcn_sched_barrier(0)
; template <class Epi, class Sched, bool SWAPD = false>
; __device__ __forceinline__ void gemm_phase(LAS unsigned char* lds, const Gemm g, const Sched& S, const Epi& E) {
;     ...
;             PG8_LDA(At, 1, 1); PG8_STAGE(PG8_SB(1, 0), b3, voffB); PG8_STAGE(PG8_SB(1, 1), b3 + hstepB, voffB); PG8_STAGE(PG8_SA(1, 0), a3, voffA);
;             PG8_WAIT_V(8); PG8_WAIT_L(0); PG8_BAR; PG8_MMA(1, 0, At, B0); PG8_MMA(1, 1, At, B1); PG8_BAR; PG8_SCHED;
;         }
	s_add_i32 s40, s59, s42
	v_lshl_add_u64 v[140:141], v[140:141], 0, s[8:9]
	s_mov_b32 m0, s40
	ds_read_b128 v[180:183], v147 offset:49152
	ds_read_b128 v[184:187], v147 offset:50176
	ds_read_b128 v[188:191], v147 offset:51200
	ds_read_b128 v[192:195], v147 offset:52224
	ds_read_b128 v[196:199], v147 offset:53248
	ds_read_b128 v[200:203], v147 offset:54272
	ds_read_b128 v[208:211], v147 offset:55296
	ds_read_b128 v[212:215], v147 offset:56320
	global_load_lds_dwordx4 v[140:141], off
	s_add_i32 m0, s40, 0x2000
	s_add_u32 s38, s38, 0x40080
	v_lshl_add_u64 v[140:141], v[204:205], 0, s[8:9]
	s_addc_u32 s39, s39, 0
	s_add_i32 s40, s60, s42
	global_load_lds_dwordx4 v[140:141], off
	v_lshl_add_u64 v[140:141], s[38:39], 0, v[130:131]
	s_mov_b32 m0, s40
	s_nop 0
	global_load_lds_dwordx4 v[140:141], off
	v_lshl_add_u64 v[140:141], s[38:39], 0, v[128:129]
	s_add_i32 m0, s40, 0x2000
	s_nop 0
	global_load_lds_dwordx4 v[140:141], off
	v_lshl_add_u64 v[140:141], v[216:217], 0, s[8:9]
	s_mov_b32 m0, s48
	s_nop 0
	global_load_lds_dwordx4 v[140:141], off
	v_lshl_add_u64 v[140:141], v[218:219], 0, s[8:9]
	s_mov_b32 m0, s49
	s_nop 0
	global_load_lds_dwordx4 v[140:141], off
	s_waitcnt vmcnt(8)
	s_waitcnt lgkmcnt(0)
	s_barrier
	s_setprio 1
	s_waitcnt lgkmcnt(0)
	v_mfma_f32_16x16x32_bf16 v[60:63], v[148:151], v[180:183], v[60:63]
	v_mfma_f32_16x16x32_bf16 v[52:55], v[156:159], v[180:183], v[52:55]
	v_mfma_f32_16x16x32_bf16 v[44:47], v[148:151], v[188:191], v[44:47]
	v_mfma_f32_16x16x32_bf16 v[36:39], v[156:159], v[188:191], v[36:39]
	v_mfma_f32_16x16x32_bf16 v[28:31], v[148:151], v[196:199], v[28:31]
	v_mfma_f32_16x16x32_bf16 v[20:23], v[156:159], v[196:199], v[20:23]
	v_mfma_f32_16x16x32_bf16 v[12:15], v[148:151], v[208:211], v[12:15]
	v_mfma_f32_16x16x32_bf16 v[4:7], v[156:159], v[208:211], v[4:7]
	v_mfma_f32_16x16x32_bf16 v[60:63], v[152:155], v[184:187], v[60:63]
	v_mfma_f32_16x16x32_bf16 v[52:55], v[160:163], v[184:187], v[52:55]
	v_mfma_f32_16x16x32_bf16 v[44:47], v[152:155], v[192:195], v[44:47]
	v_mfma_f32_16x16x32_bf16 v[36:39], v[160:163], v[192:195], v[36:39]
	v_mfma_f32_16x16x32_bf16 v[28:31], v[152:155], v[200:203], v[28:31]
	v_mfma_f32_16x16x32_bf16 v[20:23], v[160:163], v[200:203], v[20:23]
	v_mfma_f32_16x16x32_bf16 v[12:15], v[152:155], v[212:215], v[12:15]
	v_mfma_f32_16x16x32_bf16 v[4:7], v[160:163], v[212:215], v[4:7]
	v_mfma_f32_16x16x32_bf16 v[56:59], v[164:167], v[180:183], v[56:59]
	v_mfma_f32_16x16x32_bf16 v[48:51], v[172:175], v[180:183], v[48:51]
	v_mfma_f32_16x16x32_bf16 v[40:43], v[164:167], v[188:191], v[40:43]
	v_mfma_f32_16x16x32_bf16 v[32:35], v[172:175], v[188:191], v[32:35]
	v_mfma_f32_16x16x32_bf16 v[24:27], v[164:167], v[196:199], v[24:27]
	v_mfma_f32_16x16x32_bf16 v[16:19], v[172:175], v[196:199], v[16:19]
	v_mfma_f32_16x16x32_bf16 v[8:11], v[164:167], v[208:211], v[8:11]
	v_mfma_f32_16x16x32_bf16 v[0:3], v[172:175], v[208:211], v[0:3]
	v_mfma_f32_16x16x32_bf16 v[56:59], v[168:171], v[184:187], v[56:59]
	v_mfma_f32_16x16x32_bf16 v[48:51], v[176:179], v[184:187], v[48:51]
	v_mfma_f32_16x16x32_bf16 v[40:43], v[168:171], v[192:195], v[40:43]
	v_mfma_f32_16x16x32_bf16 v[32:35], v[176:179], v[192:195], v[32:35]
	v_mfma_f32_16x16x32_bf16 v[24:27], v[168:171], v[200:203], v[24:27]
	v_mfma_f32_16x16x32_bf16 v[16:19], v[176:179], v[200:203], v[16:19]
	v_mfma_f32_16x16x32_bf16 v[8:11], v[168:171], v[212:215], v[8:11]
	v_mfma_f32_16x16x32_bf16 v[0:3], v[176:179], v[212:215], v[0:3]
	s_setprio 0
	s_barrier
	s_add_i32 s58, s58, 2
	s_add_u32 s36, s36, 0x100
	s_addc_u32 s37, s37, 0
	s_add_u32 s56, s56, 0x100
	s_addc_u32 s57, s57, 0
	s_cmp_gt_u32 s58, 13
	s_cbranch_scc0 .LBB0_1863
	s_and_b64 vcc, exec, s[10:11]
	s_cbranch_vccz .LBB0_1866
	s_barrier

; #define PG8_STAGE(bufoff, gbase, voff) do { _Pragma("unroll") for (int _i = 0; _i < 2; ++_i) \
;         __builtin_amdgcn_global_load_lds((const unsigned*)((const char*)(gbase) + (voff)[_i]), (LAS unsigned*)(lds + (bufoff) + ldsw + _i * 8192), 16, 0, 0); } while (0)
; #define PG8_LDA(dst, b, h) do { _Pragma("unroll") for (int m = 0; m < 4; ++m) _Pragma("unroll") for (int k = 0; k < 2; ++k) dst[m][k] = *(const LAS bf16x8*)(lds + PG8_SA(b, h) + aoff + m * 2048 + k * 1024); } while (0)
; #define PG8_LDB(dst, b, h) do { _Pragma("unroll") for (int n = 0; n < 2; ++n) _Pragma("unroll") for (int k = 0; k < 2; ++k) dst[n][k] = *(const LAS bf16x8*)(lds + PG8_SB(b, h) + boff + n * 2048 + k * 1024); } while (0)
; #define PG8_WAIT_V(n) asm volatile("s_waitcnt vmcnt(" #n ")" ::: "memory")
; #define PG8_WAIT_L(n) asm volatile("s_waitcnt lgkmcnt(" #n ")" ::: "memory")
; #define PG8_BAR __builtin_amdgcn_s_barrier()
; #define PG8_SCHED __builtin_amdgcn_sched_barrier(0)
; template <class Epi, class Sched, bool SWAPD = false>
; __device__ __forceinline__ void gemm_phase(LAS unsigned char* lds, const Gemm g, const Sched& S, const Epi& E) {
;     ...
;         const bool has_next = S.next(ui + 1, nxt);
;         const char* nA = has_next ? (const char*)g.A + nxt.aoff : cA; const char* nB = has_next ? (const char*)g.Bt + nxt.boff : cB;
;         const int nt = cur.nt ? cur.nt : ntK;
;         for (int t = 0; t < nt; t += 2) {
;             const bool last = (t == nt - 2);
;             const char* a1 = cA + (size_t)(t + 1) * kstepA;
;             const char* a2 = last ? nA : cA + (size_t)(t + 2) * kstepA; const char* b2 = last ? nB : cB + (size_t)(t + 2) * kstep;
;             const char* a3 = a2 + kstepA; const char* b3 = b2 + kstep;
;             PG8_LDB(B0, 0, 0); PG8_LDB(B1, 0, 1); PG8_SCHED; PG8_LDA(At, 0, 0); PG8_STAGE(PG8_SA(1, 1), a1 + hstepA, voffA);
;             PG8_WAIT_V(8); PG8_WAIT_L(0); PG8_BAR; PG8_MMA(0, 0, At, B0); PG8_MMA(0, 1, At, B1); PG8_BAR; PG8_SCHED;
;             PG8_LDA(At, 0, 1); PG8_STAGE(PG8_SB(0, 0), b2, voffB); PG8_STAGE(PG8_SB(0, 1), b2 + hstepB, voffB); PG8_STAGE(PG8_SA(0, 0), a2, voffA);
;             PG8_WAIT_V(8); PG8_WAIT_L(0); PG8_BAR; PG8_MMA(1, 0, At, B0); PG8_MMA(1, 1, At, B1); PG8_BAR; PG8_SCHED;
.LBB0_1940:
	ds_read_b128 v[156:159], v168
	ds_read_b128 v[160:163], v168 offset:1024
	ds_read_b128 v[172:175], v168 offset:2048
	ds_read_b128 v[176:179], v168 offset:3072
	ds_read_b128 v[180:183], v169
	ds_read_b128 v[184:187], v169 offset:1024
	ds_read_b128 v[188:191], v169 offset:2048
	ds_read_b128 v[192:195], v169 offset:3072
	s_add_u32 s22, s20, 0x100
	s_addc_u32 s23, s21, 0
	s_cmp_eq_u32 s53, 40
	s_cselect_b32 s27, s47, s23
	s_cselect_b32 s26, s48, s22
	s_cselect_b32 s25, s49, s52
	s_cselect_b32 s24, s50, s51
	v_lshl_add_u64 v[164:165], s[20:21], 0, v[148:149]
	s_add_i32 m0, s31, 0xc000
	ds_read_b128 v[196:199], v170
	ds_read_b128 v[200:203], v170 offset:1024
	ds_read_b128 v[204:207], v170 offset:2048
	ds_read_b128 v[208:211], v170 offset:3072
	ds_read_b128 v[212:215], v170 offset:4096
	ds_read_b128 v[216:219], v170 offset:5120
	ds_read_b128 v[220:223], v170 offset:6144
	ds_read_b128 v[224:227], v170 offset:7168
	global_load_lds_dwordx4 v[164:165], off
	v_lshl_add_u64 v[164:165], s[20:21], 0, v[150:151]
	s_add_i32 m0, s31, 0xe000
	s_nop 0
	global_load_lds_dwordx4 v[164:165], off
	s_waitcnt vmcnt(8)
	s_waitcnt lgkmcnt(0)
	s_barrier
	s_setprio 1
	s_waitcnt lgkmcnt(0)
	v_mfma_f32_16x16x32_bf16 v[124:127], v[156:159], v[196:199], v[124:127]
	v_mfma_f32_16x16x32_bf16 v[120:123], v[172:175], v[196:199], v[120:123]
	v_mfma_f32_16x16x32_bf16 v[108:111], v[156:159], v[204:207], v[108:111]
	v_mfma_f32_16x16x32_bf16 v[104:107], v[172:175], v[204:207], v[104:107]
	v_mfma_f32_16x16x32_bf16 v[92:95], v[156:159], v[212:215], v[92:95]
	v_mfma_f32_16x16x32_bf16 v[88:91], v[172:175], v[212:215], v[88:91]
	v_mfma_f32_16x16x32_bf16 v[76:79], v[156:159], v[220:223], v[76:79]
	v_mfma_f32_16x16x32_bf16 v[72:75], v[172:175], v[220:223], v[72:75]
	v_mfma_f32_16x16x32_bf16 v[124:127], v[160:163], v[200:203], v[124:127]
	v_mfma_f32_16x16x32_bf16 v[120:123], v[176:179], v[200:203], v[120:123]
	v_mfma_f32_16x16x32_bf16 v[108:111], v[160:163], v[208:211], v[108:111]
	v_mfma_f32_16x16x32_bf16 v[104:107], v[176:179], v[208:211], v[104:107]
	v_mfma_f32_16x16x32_bf16 v[92:95], v[160:163], v[216:219], v[92:95]
	v_mfma_f32_16x16x32_bf16 v[88:91], v[176:179], v[216:219], v[88:91]
	v_mfma_f32_16x16x32_bf16 v[76:79], v[160:163], v[224:227], v[76:79]
	v_mfma_f32_16x16x32_bf16 v[72:75], v[176:179], v[224:227], v[72:75]
	v_mfma_f32_16x16x32_bf16 v[116:119], v[180:183], v[196:199], v[116:119]
	v_mfma_f32_16x16x32_bf16 v[112:115], v[188:191], v[196:199], v[112:115]
	v_mfma_f32_16x16x32_bf16 v[100:103], v[180:183], v[204:207], v[100:103]
	v_mfma_f32_16x16x32_bf16 v[96:99], v[188:191], v[204:207], v[96:99]
	v_mfma_f32_16x16x32_bf16 v[84:87], v[180:183], v[212:215], v[84:87]
	v_mfma_f32_16x16x32_bf16 v[80:83], v[188:191], v[212:215], v[80:83]
	v_mfma_f32_16x16x32_bf16 v[68:71], v[180:183], v[220:223], v[68:71]
	v_mfma_f32_16x16x32_bf16 v[64:67], v[188:191], v[220:223], v[64:67]
	v_mfma_f32_16x16x32_bf16 v[116:119], v[184:187], v[200:203], v[116:119]
	v_mfma_f32_16x16x32_bf16 v[112:115], v[192:195], v[200:203], v[112:115]
	v_mfma_f32_16x16x32_bf16 v[100:103], v[184:187], v[208:211], v[100:103]
	v_mfma_f32_16x16x32_bf16 v[96:99], v[192:195], v[208:211], v[96:99]
	v_mfma_f32_16x16x32_bf16 v[84:87], v[184:187], v[216:219], v[84:87]
	v_mfma_f32_16x16x32_bf16 v[80:83], v[192:195], v[216:219], v[80:83]
	v_mfma_f32_16x16x32_bf16 v[68:71], v[184:187], v[224:227], v[68:71]
	v_mfma_f32_16x16x32_bf16 v[64:67], v[192:195], v[224:227], v[64:67]
	s_setprio 0
	s_barrier
	s_add_i32 s20, s41, s30
	v_lshl_add_u64 v[164:165], s[24:25], 0, v[128:129]
	s_mov_b32 m0, s20
	ds_read_b128 v[196:199], v170 offset:16384
	ds_read_b128 v[200:203], v170 offset:17408
	ds_read_b128 v[204:207], v170 offset:18432
	ds_read_b128 v[208:211], v170 offset:19456
	ds_read_b128 v[212:215], v170 offset:20480
	ds_read_b128 v[216:219], v170 offset:21504
	ds_read_b128 v[220:223], v170 offset:22528
	ds_read_b128 v[224:227], v170 offset:23552
	global_load_lds_dwordx4 v[164:165], off
	s_add_i32 m0, s20, 0x2000
	s_add_u32 s20, s24, 0xb0000
	v_lshl_add_u64 v[228:229], s[24:25], 0, v[130:131]
	s_addc_u32 s21, s25, 0
	s_add_i32 s54, s42, s30
	global_load_lds_dwordx4 v[228:229], off
	v_lshl_add_u64 v[230:231], s[20:21], 0, v[128:129]
	s_mov_b32 m0, s54
	v_lshl_add_u64 v[232:233], s[26:27], 0, v[130:131]
	global_load_lds_dwordx4 v[230:231], off
	v_lshl_add_u64 v[230:231], s[20:21], 0, v[130:131]
	s_add_i32 m0, s54, 0x2000
	s_nop 0
	global_load_lds_dwordx4 v[230:231], off
	v_lshl_add_u64 v[230:231], s[26:27], 0, v[128:129]
	s_mov_b32 m0, s31
	s_nop 0
	global_load_lds_dwordx4 v[230:231], off
	s_mov_b32 m0, s33
	s_nop 0
	global_load_lds_dwordx4 v[232:233], off
	s_waitcnt vmcnt(8)
	s_waitcnt lgkmcnt(0)
	s_barrier
; #define PG8_STAGE(bufoff, gbase, voff) do { _Pragma("unroll") for (int _i = 0; _i < 2; ++_i) \
;         __builtin_amdgcn_global_load_lds((const unsigned*)((const char*)(gbase) + (voff)[_i]), (LAS unsigned*)(lds + (bufoff) + ldsw + _i * 8192), 16, 0, 0); } while (0)
; #define PG8_LDA(dst, b, h) do { _Pragma("unroll") for (int m = 0; m < 4; ++m) _Pragma("unroll") for (int k = 0; k < 2; ++k) dst[m][k] = *(const LAS bf16x8*)(lds + PG8_SA(b, h) + aoff + m * 2048 + k * 1024); } while (0)
; #define PG8_LDB(dst, b, h) do { _Pragma("unroll") for (int n = 0; n < 2; ++n) _Pragma("unroll") for (int k = 0; k < 2; ++k) dst[n][k] = *(const LAS bf16x8*)(lds + PG8_SB(b, h) + boff + n * 2048 + k * 1024); } while (0)
; #define PG8_WAIT_V(n) asm volatile("s_waitcnt vmcnt(" #n ")" ::: "memory")
; #define PG8_WAIT_L(n) asm volatile("s_waitcnt lgkmcnt(" #n ")" ::: "memory")
; #define PG8_BAR __builtin_amdgcn_s_barrier()
; #define PG8_SCHED __builtin_amdgcn_sched_barrier(0)
; template <class Epi, class Sched, bool SWAPD = false>
; __device__ __forceinline__ void gemm_phase(LAS unsigned char* lds, const Gemm g, const Sched& S, const Epi& E) {
;     ...
;             PG8_WAIT_V(8); PG8_WAIT_L(0); PG8_BAR; PG8_MMA(1, 0, At, B0); PG8_MMA(1, 1, At, B1); PG8_BAR; PG8_SCHED;
;             PG8_LDB(B0, 1, 0); PG8_LDB(B1, 1, 1); PG8_SCHED; PG8_LDA(At, 1, 0); PG8_STAGE(PG8_SA(0, 1), a2 + hstepA, voffA);
;             PG8_WAIT_V(8); PG8_WAIT_L(0); PG8_BAR; PG8_MMA(0, 0, At, B0); PG8_MMA(0, 1, At, B1); PG8_BAR; PG8_SCHED;
	s_setprio 1
	s_waitcnt lgkmcnt(0)
	v_mfma_f32_16x16x32_bf16 v[60:63], v[156:159], v[196:199], v[60:63]
	v_mfma_f32_16x16x32_bf16 v[56:59], v[172:175], v[196:199], v[56:59]
	v_mfma_f32_16x16x32_bf16 v[44:47], v[156:159], v[204:207], v[44:47]
	v_mfma_f32_16x16x32_bf16 v[40:43], v[172:175], v[204:207], v[40:43]
	v_mfma_f32_16x16x32_bf16 v[28:31], v[156:159], v[212:215], v[28:31]
	v_mfma_f32_16x16x32_bf16 v[24:27], v[172:175], v[212:215], v[24:27]
	v_mfma_f32_16x16x32_bf16 v[12:15], v[156:159], v[220:223], v[12:15]
	v_mfma_f32_16x16x32_bf16 v[8:11], v[172:175], v[220:223], v[8:11]
	v_mfma_f32_16x16x32_bf16 v[60:63], v[160:163], v[200:203], v[60:63]
	v_mfma_f32_16x16x32_bf16 v[56:59], v[176:179], v[200:203], v[56:59]
	v_mfma_f32_16x16x32_bf16 v[44:47], v[160:163], v[208:211], v[44:47]
	v_mfma_f32_16x16x32_bf16 v[40:43], v[176:179], v[208:211], v[40:43]
	v_mfma_f32_16x16x32_bf16 v[28:31], v[160:163], v[216:219], v[28:31]
	v_mfma_f32_16x16x32_bf16 v[24:27], v[176:179], v[216:219], v[24:27]
	v_mfma_f32_16x16x32_bf16 v[12:15], v[160:163], v[224:227], v[12:15]
	v_mfma_f32_16x16x32_bf16 v[8:11], v[176:179], v[224:227], v[8:11]
	v_mfma_f32_16x16x32_bf16 v[52:55], v[180:183], v[196:199], v[52:55]
	v_mfma_f32_16x16x32_bf16 v[48:51], v[188:191], v[196:199], v[48:51]
	v_mfma_f32_16x16x32_bf16 v[36:39], v[180:183], v[204:207], v[36:39]
	v_mfma_f32_16x16x32_bf16 v[32:35], v[188:191], v[204:207], v[32:35]
	v_mfma_f32_16x16x32_bf16 v[20:23], v[180:183], v[212:215], v[20:23]
	v_mfma_f32_16x16x32_bf16 v[16:19], v[188:191], v[212:215], v[16:19]
	v_mfma_f32_16x16x32_bf16 v[4:7], v[180:183], v[220:223], v[4:7]
	v_mfma_f32_16x16x32_bf16 v[0:3], v[188:191], v[220:223], v[0:3]
	v_mfma_f32_16x16x32_bf16 v[52:55], v[184:187], v[200:203], v[52:55]
	v_mfma_f32_16x16x32_bf16 v[48:51], v[192:195], v[200:203], v[48:51]
	v_mfma_f32_16x16x32_bf16 v[36:39], v[184:187], v[208:211], v[36:39]
	v_mfma_f32_16x16x32_bf16 v[32:35], v[192:195], v[208:211], v[32:35]
	v_mfma_f32_16x16x32_bf16 v[20:23], v[184:187], v[216:219], v[20:23]
	v_mfma_f32_16x16x32_bf16 v[16:19], v[192:195], v[216:219], v[16:19]
	v_mfma_f32_16x16x32_bf16 v[4:7], v[184:187], v[224:227], v[4:7]
	v_mfma_f32_16x16x32_bf16 v[0:3], v[192:195], v[224:227], v[0:3]
	s_setprio 0
	s_barrier
	s_add_i32 s54, 0, 0x18000
	v_add_u32_e32 v171, s54, v166
	s_add_i32 s55, 0, 0x1c000
	ds_read_b128 v[156:159], v171
	ds_read_b128 v[160:163], v171 offset:1024
	ds_read_b128 v[172:175], v171 offset:2048
	ds_read_b128 v[176:179], v171 offset:3072
	v_add_u32_e32 v171, s55, v166
	ds_read_b128 v[180:183], v171
	ds_read_b128 v[184:187], v171 offset:1024
	ds_read_b128 v[188:191], v171 offset:2048
	ds_read_b128 v[192:195], v171 offset:3072
	s_add_u32 s20, s26, 0xb0000
	s_addc_u32 s21, s27, 0
	s_mov_b32 m0, s34
	v_lshl_add_u64 v[234:235], s[20:21], 0, v[128:129]
	ds_read_b128 v[196:199], v170 offset:32768
	ds_read_b128 v[200:203], v170 offset:33792
	ds_read_b128 v[204:207], v170 offset:34816
	ds_read_b128 v[208:211], v170 offset:35840
	ds_read_b128 v[212:215], v170 offset:36864
	ds_read_b128 v[216:219], v170 offset:37888
	ds_read_b128 v[220:223], v170 offset:38912
	ds_read_b128 v[224:227], v170 offset:39936
	global_load_lds_dwordx4 v[234:235], off
	v_lshl_add_u64 v[234:235], s[20:21], 0, v[130:131]
	s_mov_b32 m0, s35
	s_nop 0
	global_load_lds_dwordx4 v[234:235], off
	s_waitcnt vmcnt(8)
	s_waitcnt lgkmcnt(0)
	s_barrier
	s_setprio 1
	s_waitcnt lgkmcnt(0)
	v_mfma_f32_16x16x32_bf16 v[124:127], v[156:159], v[196:199], v[124:127]
	v_mfma_f32_16x16x32_bf16 v[120:123], v[172:175], v[196:199], v[120:123]
	v_mfma_f32_16x16x32_bf16 v[108:111], v[156:159], v[204:207], v[108:111]
	v_mfma_f32_16x16x32_bf16 v[104:107], v[172:175], v[204:207], v[104:107]
	v_mfma_f32_16x16x32_bf16 v[92:95], v[156:159], v[212:215], v[92:95]
	v_mfma_f32_16x16x32_bf16 v[88:91], v[172:175], v[212:215], v[88:91]
	v_mfma_f32_16x16x32_bf16 v[76:79], v[156:159], v[220:223], v[76:79]
	v_mfma_f32_16x16x32_bf16 v[72:75], v[172:175], v[220:223], v[72:75]
	v_mfma_f32_16x16x32_bf16 v[124:127], v[160:163], v[200:203], v[124:127]
	v_mfma_f32_16x16x32_bf16 v[120:123], v[176:179], v[200:203], v[120:123]
	v_mfma_f32_16x16x32_bf16 v[108:111], v[160:163], v[208:211], v[108:111]
	v_mfma_f32_16x16x32_bf16 v[104:107], v[176:179], v[208:211], v[104:107]
	v_mfma_f32_16x16x32_bf16 v[92:95], v[160:163], v[216:219], v[92:95]
	v_mfma_f32_16x16x32_bf16 v[88:91], v[176:179], v[216:219], v[88:91]
	v_mfma_f32_16x16x32_bf16 v[76:79], v[160:163], v[224:227], v[76:79]
	v_mfma_f32_16x16x32_bf16 v[72:75], v[176:179], v[224:227], v[72:75]
	v_mfma_f32_16x16x32_bf16 v[116:119], v[180:183], v[196:199], v[116:119]
	v_mfma_f32_16x16x32_bf16 v[112:115], v[188:191], v[196:199], v[112:115]
	v_mfma_f32_16x16x32_bf16 v[100:103], v[180:183], v[204:207], v[100:103]
	v_mfma_f32_16x16x32_bf16 v[96:99], v[188:191], v[204:207], v[96:99]
	v_mfma_f32_16x16x32_bf16 v[84:87], v[180:183], v[212:215], v[84:87]
	v_mfma_f32_16x16x32_bf16 v[80:83], v[188:191], v[212:215], v[80:83]
	v_mfma_f32_16x16x32_bf16 v[68:71], v[180:183], v[220:223], v[68:71]
	v_mfma_f32_16x16x32_bf16 v[64:67], v[188:191], v[220:223], v[64:67]
	v_mfma_f32_16x16x32_bf16 v[116:119], v[184:187], v[200:203], v[116:119]
	v_mfma_f32_16x16x32_bf16 v[112:115], v[192:195], v[200:203], v[112:115]
	v_mfma_f32_16x16x32_bf16 v[100:103], v[184:187], v[208:211], v[100:103]
	v_mfma_f32_16x16x32_bf16 v[96:99], v[192:195], v[208:211], v[96:99]
	v_mfma_f32_16x16x32_bf16 v[84:87], v[184:187], v[216:219], v[84:87]
	v_mfma_f32_16x16x32_bf16 v[80:83], v[192:195], v[216:219], v[80:83]
	v_mfma_f32_16x16x32_bf16 v[68:71], v[184:187], v[224:227], v[68:71]
	v_mfma_f32_16x16x32_bf16 v[64:67], v[192:195], v[224:227], v[64:67]
	s_setprio 0
	s_barrier
; #define PG8_STAGE(bufoff, gbase, voff) do { _Pragma("unroll") for (int _i = 0; _i < 2; ++_i) \
;         __builtin_amdgcn_global_load_lds((const unsigned*)((const char*)(gbase) + (voff)[_i]), (LAS unsigned*)(lds + (bufoff) + ldsw + _i * 8192), 16, 0, 0); } while (0)
; #define PG8_LDA(dst, b, h) do { _Pragma("unroll") for (int m = 0; m < 4; ++m) _Pragma("unroll") for (int k = 0; k < 2; ++k) dst[m][k] = *(const LAS bf16x8*)(lds + PG8_SA(b, h) + aoff + m * 2048 + k * 1024); } while (0)
; #define PG8_WAIT_V(n) asm volatile("s_waitcnt vmcnt(" #n ")" ::: "memory")
; #define PG8_WAIT_L(n) asm volatile("s_waitcnt lgkmcnt(" #n ")" ::: "memory")
; #define PG8_BAR __builtin_amdgcn_s_barrier()
; #define PG8_SCHED __builtin_amdgcn_sched_barrier(0)
; template <class Epi, class Sched, bool SWAPD = false>
; __device__ __forceinline__ void gemm_phase(LAS unsigned char* lds, const Gemm g, const Sched& S, const Epi& E) {
;     ...
;             PG8_LDA(At, 1, 1); PG8_STAGE(PG8_SB(1, 0), b3, voffB); PG8_STAGE(PG8_SB(1, 1), b3 + hstepB, voffB); PG8_STAGE(PG8_SA(1, 0), a3, voffA);
;             PG8_WAIT_V(8); PG8_WAIT_L(0); PG8_BAR; PG8_MMA(1, 0, At, B0); PG8_MMA(1, 1, At, B1); PG8_BAR; PG8_SCHED;
;         }
;         if (wr == 0) PG8_BAR;
	s_add_i32 s20, s54, s30
	v_lshl_add_u64 v[164:165], v[164:165], 0, s[6:7]
	s_mov_b32 m0, s20
	ds_read_b128 v[196:199], v170 offset:49152
	ds_read_b128 v[200:203], v170 offset:50176
	ds_read_b128 v[204:207], v170 offset:51200
	ds_read_b128 v[208:211], v170 offset:52224
	ds_read_b128 v[212:215], v170 offset:53248
	ds_read_b128 v[216:219], v170 offset:54272
	ds_read_b128 v[220:223], v170 offset:55296
	ds_read_b128 v[224:227], v170 offset:56320
	global_load_lds_dwordx4 v[164:165], off
	s_add_i32 m0, s20, 0x2000
	s_add_u32 s20, s24, 0xb0080
	v_lshl_add_u64 v[164:165], v[228:229], 0, s[6:7]
	s_addc_u32 s21, s25, 0
	s_add_i32 s24, s55, s30
	global_load_lds_dwordx4 v[164:165], off
	v_lshl_add_u64 v[164:165], s[20:21], 0, v[128:129]
	s_mov_b32 m0, s24
	s_nop 0
	global_load_lds_dwordx4 v[164:165], off
	v_lshl_add_u64 v[164:165], s[20:21], 0, v[130:131]
	s_add_i32 m0, s24, 0x2000
	s_nop 0
	global_load_lds_dwordx4 v[164:165], off
	v_lshl_add_u64 v[164:165], v[230:231], 0, s[6:7]
	s_mov_b32 m0, s39
	s_nop 0
	global_load_lds_dwordx4 v[164:165], off
	v_lshl_add_u64 v[164:165], v[232:233], 0, s[6:7]
	s_mov_b32 m0, s40
	s_nop 0
	global_load_lds_dwordx4 v[164:165], off
	s_waitcnt vmcnt(8)
	s_waitcnt lgkmcnt(0)
	s_barrier
	s_setprio 1
	s_waitcnt lgkmcnt(0)
	v_mfma_f32_16x16x32_bf16 v[60:63], v[156:159], v[196:199], v[60:63]
	v_mfma_f32_16x16x32_bf16 v[56:59], v[172:175], v[196:199], v[56:59]
	v_mfma_f32_16x16x32_bf16 v[44:47], v[156:159], v[204:207], v[44:47]
	v_mfma_f32_16x16x32_bf16 v[40:43], v[172:175], v[204:207], v[40:43]
	v_mfma_f32_16x16x32_bf16 v[28:31], v[156:159], v[212:215], v[28:31]
	v_mfma_f32_16x16x32_bf16 v[24:27], v[172:175], v[212:215], v[24:27]
	v_mfma_f32_16x16x32_bf16 v[12:15], v[156:159], v[220:223], v[12:15]
	v_mfma_f32_16x16x32_bf16 v[8:11], v[172:175], v[220:223], v[8:11]
	v_mfma_f32_16x16x32_bf16 v[60:63], v[160:163], v[200:203], v[60:63]
	v_mfma_f32_16x16x32_bf16 v[56:59], v[176:179], v[200:203], v[56:59]
	v_mfma_f32_16x16x32_bf16 v[44:47], v[160:163], v[208:211], v[44:47]
	v_mfma_f32_16x16x32_bf16 v[40:43], v[176:179], v[208:211], v[40:43]
	v_mfma_f32_16x16x32_bf16 v[28:31], v[160:163], v[216:219], v[28:31]
	v_mfma_f32_16x16x32_bf16 v[24:27], v[176:179], v[216:219], v[24:27]
	v_mfma_f32_16x16x32_bf16 v[12:15], v[160:163], v[224:227], v[12:15]
	v_mfma_f32_16x16x32_bf16 v[8:11], v[176:179], v[224:227], v[8:11]
	v_mfma_f32_16x16x32_bf16 v[52:55], v[180:183], v[196:199], v[52:55]
	v_mfma_f32_16x16x32_bf16 v[48:51], v[188:191], v[196:199], v[48:51]
	v_mfma_f32_16x16x32_bf16 v[36:39], v[180:183], v[204:207], v[36:39]
	v_mfma_f32_16x16x32_bf16 v[32:35], v[188:191], v[204:207], v[32:35]
	v_mfma_f32_16x16x32_bf16 v[20:23], v[180:183], v[212:215], v[20:23]
	v_mfma_f32_16x16x32_bf16 v[16:19], v[188:191], v[212:215], v[16:19]
	v_mfma_f32_16x16x32_bf16 v[4:7], v[180:183], v[220:223], v[4:7]
	v_mfma_f32_16x16x32_bf16 v[0:3], v[188:191], v[220:223], v[0:3]
	v_mfma_f32_16x16x32_bf16 v[52:55], v[184:187], v[200:203], v[52:55]
	v_mfma_f32_16x16x32_bf16 v[48:51], v[192:195], v[200:203], v[48:51]
	v_mfma_f32_16x16x32_bf16 v[36:39], v[184:187], v[208:211], v[36:39]
	v_mfma_f32_16x16x32_bf16 v[32:35], v[192:195], v[208:211], v[32:35]
	v_mfma_f32_16x16x32_bf16 v[20:23], v[184:187], v[216:219], v[20:23]
	v_mfma_f32_16x16x32_bf16 v[16:19], v[192:195], v[216:219], v[16:19]
	v_mfma_f32_16x16x32_bf16 v[4:7], v[184:187], v[224:227], v[4:7]
	v_mfma_f32_16x16x32_bf16 v[0:3], v[192:195], v[224:227], v[0:3]
	s_setprio 0
	s_barrier
	s_add_i32 s53, s53, 2
	s_add_u32 s51, s51, 0x100
	s_addc_u32 s52, s52, 0
	s_cmp_gt_u32 s53, 41
	s_mov_b64 s[20:21], s[22:23]
	s_cbranch_scc0 .LBB0_1940
	s_and_b64 vcc, exec, s[8:9]
	s_cbranch_vccz .LBB0_1943
	s_barrier
